# merge4: DMA burst + three stages in flight; mlp1: next tile's pipeline fill issued before the epilogue
# speedup vs baseline: 1.0997x; 1.0010x over previous
; template <int NI> ...
;     ...
;   const int lane = tid & 63, wid = tid >> 6, wr = wid >> 1, wc = wid & 1;
;   const int lrow = tid >> 2, lch = (tid & 3) * 8;
;   const int l15 = lane & 15, lq = lane >> 4;
;   const bf16_t* pa = A + (size_t)lrow * lda + lch;
;   const bf16_t* pb = B + (size_t)lrow * ldb + lch;
;   const size_t a64 = (size_t)64 * lda, b64 = (size_t)64 * ldb;
;   u32x4 a0[2], a1[2], b0[NB], b1[NB];
;   const int nk = K >> 5;
;   const int klast = K - 32;
;   const int wofs = lrow * GROW + lch;
;   const int raofs = (wr * 64 + l15) * GROW + lq * 8;
;   const int rbofs = 128 * GROW + (wc * (16 * NI) + l15) * GROW + lq * 8;
;     ...
;   G_LOAD(a0, b0, 0);
;   G_LOAD(a1, b1, 32);
;   __syncthreads();
;   G_WRITE(a0, b0, 0);
;   __syncthreads();
; __device__ void phase_merge4(CParams& p, int l, int tm, int tn, char* smem) {
;     ...
; #pragma unroll 1
;   for (int kb0 = 0; kb0 < 4; kb0++) {
;     int kb = kb0;
;     asm volatile("" : "+s"(kb));
;     int tid2 = tid;
;     asm volatile("" : "+v"(tid2));
;     unsigned pk[4][4][2];
;     {
;       f32x4 acc[4][4];
;       zero_acc<4>(acc);
;       gemm_mainloop<4>(p.br + (size_t)row0 * 1024 + kb * 256, 1024,
;                        p.WbT + (((size_t)l * 4 + kb) * 1024 + col0) * 256, 256, 256, sA, sB, acc, tid2);
.LBB0_878:
	s_or_b64 exec, exec, s[20:21]
	s_mov_b64 s[42:43], s[34:35]
	s_waitcnt lgkmcnt(0)
	s_barrier
	s_lshl_b64 s[6:7], s[50:51], 12
	s_load_dwordx4 s[48:51], s[42:43], 0x1d0
	s_load_dwordx4 s[52:55], s[42:43], 0x108
	s_load_dwordx2 s[20:21], s[42:43], 0x150
	s_add_u32 s24, s6, s88
	s_addc_u32 s25, s7, s89
	s_lshl_b64 s[6:7], s[88:89], 1
	s_waitcnt lgkmcnt(0)
	s_add_u32 s44, s50, s6
	s_addc_u32 s45, s51, s7
	s_mov_b64 exec, -1
	ds_read_b128 v[252:255], v145 offset:40960
	v_cndmask_b32_e64 v0, 0, 1, s[84:85]
	v_cmp_ne_u32_e64 s[40:41], 1, v0
	s_load_dwordx2 s[0:1], s[34:35], 0x150
	s_load_dwordx2 s[6:7], s[34:35], 0x1d0
	s_load_dwordx2 s[8:9], s[34:35], 0x1d8
	s_load_dwordx2 s[12:13], s[34:35], 0x108
	s_load_dwordx2 s[18:19], s[34:35], 0x110
	s_lshr_b32 s2, s24, 12
	v_readlane_b32 s4, v225, 4
	v_readfirstlane_b32 s56, v147
	v_and_b32_e32 v245, 63, v147
	s_nop 3
	s_and_b32 s20, s4, 7
	s_lshl_b32 s20, s20, 3
	s_lshr_b32 s57, s4, 6
	s_add_u32 s20, s20, s57
	s_lshr_b32 s21, s4, 3
	s_and_b32 s21, s21, 7
	s_lshl_b32 s21, s21, 7
	s_lshr_b32 s57, s56, 6
	s_lshl_b32 s56, s57, 11
	v_lshlrev_b32_e32 v249, 4, v245
	v_add_u32_e32 v249, s56, v249
	v_lshrrev_b32_e32 v246, 2, v245
	v_and_b32_e32 v247, 3, v245
	v_lshrrev_b32_e32 v248, 4, v245
	v_sub_u32_e32 v248, 0, v248
	v_and_b32_e32 v248, 3, v248
	v_xor_b32_e32 v248, v247, v248
	v_lshlrev_b32_e32 v248, 4, v248
	s_lshl_b32 s62, s57, 5
	v_add_u32_e32 v246, s62, v246
	v_lshl_add_u32 v236, v246, 11, v248
	v_add_u32_e32 v237, 0x8000, v236
	s_lshl_b32 s63, s57, 1
	s_sub_u32 s63, 0, s63
	s_and_b32 s63, s63, 3
	v_xor_b32_e32 v248, s63, v247
	v_lshlrev_b32_e32 v248, 4, v248
	v_lshl_add_u32 v238, v246, 9, v248
	v_lshl_add_u32 v240, v246, 11, v248
	s_lshl_b32 s63, s57, 1
	s_add_u32 s63, s63, 1
	s_sub_u32 s63, 0, s63
	s_and_b32 s63, s63, 3
	v_xor_b32_e32 v248, s63, v247
	v_lshlrev_b32_e32 v248, 4, v248
	v_add_u32_e32 v246, 16, v246
	v_lshl_add_u32 v239, v246, 9, v248
	v_lshl_add_u32 v241, v246, 11, v248
	v_and_b32_e32 v246, 15, v245
	v_lshrrev_b32_e32 v247, 2, v246
	v_sub_u32_e32 v248, 0, v247
	v_and_b32_e32 v248, 3, v248
	v_lshrrev_b32_e32 v244, 4, v245
	v_xor_b32_e32 v248, v244, v248
	v_lshlrev_b32_e32 v248, 4, v248
	s_lshr_b32 s62, s57, 1
	s_and_b32 s63, s57, 1
	s_lshl_b32 s92, s62, 6
	v_add_u32_e32 v242, s92, v246
	v_lshl_add_u32 v242, v242, 6, v248
	v_and_b32_e32 v243, 3, v246
	v_lshl_add_u32 v243, v247, 4, v243
	s_lshl_b32 s93, s63, 6
	v_add_u32_e32 v243, s93, v243
	v_lshl_add_u32 v243, v243, 6, v248
	v_add_u32_e32 v243, 0x2000, v243
	v_add_u32_e32 v247, s92, v246
	v_lshlrev_b32_e32 v247, 10, v247
	v_lshl_add_u32 v247, v244, 4, v247
	v_add_u32_e32 v247, s93, v247
	v_lshlrev_b32_e32 v244, 1, v247
	s_waitcnt lgkmcnt(0)
	s_mov_b32 s22, 0
	s_lshr_b32 s62, s22, 2
	s_lshl_b32 s62, s62, 6
	s_add_u32 s62, s62, s20
	s_lshl_b32 s62, s62, 18
	s_and_b32 s63, s22, 3
	s_lshl_b32 s92, s63, 9
	s_add_u32 s62, s62, s92
	s_add_u32 s24, s6, s62
	s_addc_u32 s25, s7, 0
	s_lshl_b32 s92, s2, 2
	s_add_u32 s92, s92, s63
	s_lshl_b32 s92, s92, 10
	s_add_u32 s92, s92, s21
	s_lshl_b32 s93, s92, 9
	s_add_u32 s26, s18, s93
	s_addc_u32 s27, s19, 0
	s_barrier
	s_add_u32 m0, s56, 0x0
	s_nop 0
	global_load_lds_dwordx4 v236, s[24:25]
	s_add_u32 m0, s56, 0x400
	s_nop 0
	global_load_lds_dwordx4 v237, s[24:25]
	s_add_u32 m0, s56, 0x2000
	s_nop 0
	global_load_lds_dwordx4 v238, s[26:27]
	s_add_u32 m0, s56, 0x2400
	s_nop 0
	global_load_lds_dwordx4 v239, s[26:27]
	s_add_u32 s24, s24, 64
	s_addc_u32 s25, s25, 0
	s_add_u32 s26, s26, 64
	s_addc_u32 s27, s27, 0
	s_add_u32 m0, s56, 0x4000
	s_nop 0
	global_load_lds_dwordx4 v236, s[24:25]
	s_add_u32 m0, s56, 0x4400
	s_nop 0
	global_load_lds_dwordx4 v237, s[24:25]
	s_add_u32 m0, s56, 0x6000
	s_nop 0
	global_load_lds_dwordx4 v238, s[26:27]
	s_add_u32 m0, s56, 0x6400
	s_nop 0
	global_load_lds_dwordx4 v239, s[26:27]
	s_add_u32 s24, s24, 64
	s_addc_u32 s25, s25, 0
	s_add_u32 s26, s26, 64
	s_addc_u32 s27, s27, 0
	s_add_u32 m0, s56, 0x8000
	s_nop 0
	global_load_lds_dwordx4 v236, s[24:25]
	s_add_u32 m0, s56, 0x8400
	s_nop 0
	global_load_lds_dwordx4 v237, s[24:25]
	s_add_u32 m0, s56, 0xa000
	s_nop 0
	global_load_lds_dwordx4 v238, s[26:27]
	s_add_u32 m0, s56, 0xa400
	s_nop 0
	global_load_lds_dwordx4 v239, s[26:27]
	s_add_u32 s24, s24, 64
	s_addc_u32 s25, s25, 0
	s_add_u32 s26, s26, 64
	s_addc_u32 s27, s27, 0
	s_add_u32 m0, s56, 0xc000
	s_nop 0
	global_load_lds_dwordx4 v236, s[24:25]
	s_add_u32 m0, s56, 0xc400
	s_nop 0
	global_load_lds_dwordx4 v237, s[24:25]
	s_add_u32 m0, s56, 0xe000
	s_nop 0
	global_load_lds_dwordx4 v238, s[26:27]
	s_add_u32 m0, s56, 0xe400
	s_nop 0
	global_load_lds_dwordx4 v239, s[26:27]
	s_add_u32 s24, s24, 64
	s_addc_u32 s25, s25, 0
	s_add_u32 s26, s26, 64
	s_addc_u32 s27, s27, 0
	s_waitcnt vmcnt(12)
	s_barrier
	ds_read_b128 v[168:171], v242 offset:0
	ds_read_b128 v[184:187], v243 offset:0
	ds_read_b128 v[172:175], v242 offset:1024
	ds_read_b128 v[188:191], v243 offset:256
	ds_read_b128 v[176:179], v242 offset:2048
	ds_read_b128 v[192:195], v243 offset:512
	ds_read_b128 v[180:183], v242 offset:3072
	ds_read_b128 v[196:199], v243 offset:768

; template <int NI> ...
;     ...
;   G_LOAD(a0, b0, 0);
;   G_LOAD(a1, b1, 32);
;   __syncthreads();
;   G_WRITE(a0, b0, 0);
;   __syncthreads();
;   for (int kt = 0; kt < nk; kt += 2) {
;     G_LOAD(a0, b0, min((kt + 2) * 32, klast));
;     G_COMPUTE(0);
;     G_WRITE(a1, b1, 1);
;     __syncthreads();
;     G_LOAD(a1, b1, min((kt + 3) * 32, klast));
;     G_COMPUTE(1);
;     G_WRITE(a0, b0, 0);
;     __syncthreads();
.Lmg4_nozero:
	s_waitcnt vmcnt(8) lgkmcnt(0)
	s_barrier
	s_add_u32 m0, s56, 0x0
	s_nop 0
	global_load_lds_dwordx4 v236, s[24:25]
	s_add_u32 m0, s56, 0x400
	s_nop 0
	global_load_lds_dwordx4 v237, s[24:25]
	s_add_u32 m0, s56, 0x2000
	s_nop 0
	global_load_lds_dwordx4 v238, s[26:27]
	s_add_u32 m0, s56, 0x2400
	s_nop 0
	global_load_lds_dwordx4 v239, s[26:27]
	s_add_u32 s24, s24, 64
	s_addc_u32 s25, s25, 0
	s_add_u32 s26, s26, 64
	s_addc_u32 s27, s27, 0
	v_mfma_f32_16x16x32_bf16 v[0:3], v[184:187], v[168:171], 0
	ds_read_b128 v[200:203], v242 offset:16384
	v_mfma_f32_16x16x32_bf16 v[4:7], v[188:191], v[168:171], 0
	ds_read_b128 v[216:219], v243 offset:16384
	v_mfma_f32_16x16x32_bf16 v[8:11], v[192:195], v[168:171], 0
	ds_read_b128 v[204:207], v242 offset:17408
	v_mfma_f32_16x16x32_bf16 v[12:15], v[196:199], v[168:171], 0
	ds_read_b128 v[220:223], v243 offset:16640
	v_mfma_f32_16x16x32_bf16 v[16:19], v[184:187], v[172:175], 0
	ds_read_b128 v[208:211], v242 offset:18432
	v_mfma_f32_16x16x32_bf16 v[20:23], v[188:191], v[172:175], 0
	ds_read_b128 v[228:231], v243 offset:16896
	v_mfma_f32_16x16x32_bf16 v[24:27], v[192:195], v[172:175], 0
	ds_read_b128 v[212:215], v242 offset:19456
	v_mfma_f32_16x16x32_bf16 v[28:31], v[196:199], v[172:175], 0
	ds_read_b128 v[232:235], v243 offset:17152
	v_mfma_f32_16x16x32_bf16 v[32:35], v[184:187], v[176:179], 0
	v_mfma_f32_16x16x32_bf16 v[36:39], v[188:191], v[176:179], 0
	v_mfma_f32_16x16x32_bf16 v[40:43], v[192:195], v[176:179], 0
	v_mfma_f32_16x16x32_bf16 v[44:47], v[196:199], v[176:179], 0
	v_mfma_f32_16x16x32_bf16 v[48:51], v[184:187], v[180:183], 0
	v_mfma_f32_16x16x32_bf16 v[52:55], v[188:191], v[180:183], 0
	v_mfma_f32_16x16x32_bf16 v[56:59], v[192:195], v[180:183], 0
	v_mfma_f32_16x16x32_bf16 v[60:63], v[196:199], v[180:183], 0
	s_waitcnt vmcnt(8) lgkmcnt(0)
	s_barrier
	s_add_u32 m0, s56, 0x4000
	s_nop 0
	global_load_lds_dwordx4 v236, s[24:25]
	s_add_u32 m0, s56, 0x4400
	s_nop 0
	global_load_lds_dwordx4 v237, s[24:25]
	s_add_u32 m0, s56, 0x6000
	s_nop 0
	global_load_lds_dwordx4 v238, s[26:27]
	s_add_u32 m0, s56, 0x6400
	s_nop 0
	global_load_lds_dwordx4 v239, s[26:27]
	s_add_u32 s24, s24, 64
	s_addc_u32 s25, s25, 0
	s_add_u32 s26, s26, 64
	s_addc_u32 s27, s27, 0
	v_mfma_f32_16x16x32_bf16 v[0:3], v[216:219], v[200:203], v[0:3]
	ds_read_b128 v[168:171], v242 offset:32768
	v_mfma_f32_16x16x32_bf16 v[4:7], v[220:223], v[200:203], v[4:7]
	ds_read_b128 v[184:187], v243 offset:32768
	v_mfma_f32_16x16x32_bf16 v[8:11], v[228:231], v[200:203], v[8:11]
	ds_read_b128 v[172:175], v242 offset:33792
	v_mfma_f32_16x16x32_bf16 v[12:15], v[232:235], v[200:203], v[12:15]
	ds_read_b128 v[188:191], v243 offset:33024
	v_mfma_f32_16x16x32_bf16 v[16:19], v[216:219], v[204:207], v[16:19]
	ds_read_b128 v[176:179], v242 offset:34816
	v_mfma_f32_16x16x32_bf16 v[20:23], v[220:223], v[204:207], v[20:23]
	ds_read_b128 v[192:195], v243 offset:33280
	v_mfma_f32_16x16x32_bf16 v[24:27], v[228:231], v[204:207], v[24:27]
	ds_read_b128 v[180:183], v242 offset:35840
	v_mfma_f32_16x16x32_bf16 v[28:31], v[232:235], v[204:207], v[28:31]
	ds_read_b128 v[196:199], v243 offset:33536
	v_mfma_f32_16x16x32_bf16 v[32:35], v[216:219], v[208:211], v[32:35]
	v_mfma_f32_16x16x32_bf16 v[36:39], v[220:223], v[208:211], v[36:39]
	v_mfma_f32_16x16x32_bf16 v[40:43], v[228:231], v[208:211], v[40:43]
	v_mfma_f32_16x16x32_bf16 v[44:47], v[232:235], v[208:211], v[44:47]
	v_mfma_f32_16x16x32_bf16 v[48:51], v[216:219], v[212:215], v[48:51]
	v_mfma_f32_16x16x32_bf16 v[52:55], v[220:223], v[212:215], v[52:55]
	v_mfma_f32_16x16x32_bf16 v[56:59], v[228:231], v[212:215], v[56:59]
	v_mfma_f32_16x16x32_bf16 v[60:63], v[232:235], v[212:215], v[60:63]
	s_waitcnt vmcnt(8) lgkmcnt(0)
	s_barrier
	s_add_u32 m0, s56, 0x8000
	s_nop 0
	global_load_lds_dwordx4 v236, s[24:25]
	s_add_u32 m0, s56, 0x8400
	s_nop 0
	global_load_lds_dwordx4 v237, s[24:25]
	s_add_u32 m0, s56, 0xa000
	s_nop 0
	global_load_lds_dwordx4 v238, s[26:27]
	s_add_u32 m0, s56, 0xa400
	s_nop 0
	global_load_lds_dwordx4 v239, s[26:27]
	s_add_u32 s24, s24, 64
	s_addc_u32 s25, s25, 0
	s_add_u32 s26, s26, 64
	s_addc_u32 s27, s27, 0
	v_mfma_f32_16x16x32_bf16 v[0:3], v[184:187], v[168:171], v[0:3]
	ds_read_b128 v[200:203], v242 offset:49152
	v_mfma_f32_16x16x32_bf16 v[4:7], v[188:191], v[168:171], v[4:7]
	ds_read_b128 v[216:219], v243 offset:49152
	v_mfma_f32_16x16x32_bf16 v[8:11], v[192:195], v[168:171], v[8:11]
	ds_read_b128 v[204:207], v242 offset:50176
	v_mfma_f32_16x16x32_bf16 v[12:15], v[196:199], v[168:171], v[12:15]
	ds_read_b128 v[220:223], v243 offset:49408
	v_mfma_f32_16x16x32_bf16 v[16:19], v[184:187], v[172:175], v[16:19]
	ds_read_b128 v[208:211], v242 offset:51200
	v_mfma_f32_16x16x32_bf16 v[20:23], v[188:191], v[172:175], v[20:23]
	ds_read_b128 v[228:231], v243 offset:49664
	v_mfma_f32_16x16x32_bf16 v[24:27], v[192:195], v[172:175], v[24:27]
	ds_read_b128 v[212:215], v242 offset:52224
	v_mfma_f32_16x16x32_bf16 v[28:31], v[196:199], v[172:175], v[28:31]
	ds_read_b128 v[232:235], v243 offset:49920
	v_mfma_f32_16x16x32_bf16 v[32:35], v[184:187], v[176:179], v[32:35]
	v_mfma_f32_16x16x32_bf16 v[36:39], v[188:191], v[176:179], v[36:39]
	v_mfma_f32_16x16x32_bf16 v[40:43], v[192:195], v[176:179], v[40:43]
	v_mfma_f32_16x16x32_bf16 v[44:47], v[196:199], v[176:179], v[44:47]
	v_mfma_f32_16x16x32_bf16 v[48:51], v[184:187], v[180:183], v[48:51]
	v_mfma_f32_16x16x32_bf16 v[52:55], v[188:191], v[180:183], v[52:55]
	v_mfma_f32_16x16x32_bf16 v[56:59], v[192:195], v[180:183], v[56:59]
	v_mfma_f32_16x16x32_bf16 v[60:63], v[196:199], v[180:183], v[60:63]
	s_waitcnt vmcnt(8) lgkmcnt(0)
	s_barrier
; template <int NI> ...
;     ...
;   G_LOAD(a0, b0, 0);
;   G_LOAD(a1, b1, 32);
;   __syncthreads();
;   G_WRITE(a0, b0, 0);
;   __syncthreads();
;   for (int kt = 0; kt < nk; kt += 2) {
;     G_LOAD(a0, b0, min((kt + 2) * 32, klast));
;     G_COMPUTE(0);
;     G_WRITE(a1, b1, 1);
;     __syncthreads();
;     G_LOAD(a1, b1, min((kt + 3) * 32, klast));
;     G_COMPUTE(1);
;     G_WRITE(a0, b0, 0);
;     __syncthreads();
; __device__ void phase_merge4(CParams& p, int l, int tm, int tn, char* smem) {
;     ...
;     gemm_mainloop<4>(p.hbuf + (size_t)row0 * DM, DM,
;                      p.WgT + (((size_t)l * 4 + kb) * 1024 + col0) * 1024, 1024, 1024, sA, sB, acc, tid2);
	s_add_u32 m0, s56, 0xc000
	s_nop 0
	global_load_lds_dwordx4 v236, s[24:25]
	s_add_u32 m0, s56, 0xc400
	s_nop 0
	global_load_lds_dwordx4 v237, s[24:25]
	s_add_u32 m0, s56, 0xe000
	s_nop 0
	global_load_lds_dwordx4 v238, s[26:27]
	s_add_u32 m0, s56, 0xe400
	s_nop 0
	global_load_lds_dwordx4 v239, s[26:27]
	s_add_u32 s24, s24, 64
	s_addc_u32 s25, s25, 0
	s_add_u32 s26, s26, 64
	s_addc_u32 s27, s27, 0
	v_mfma_f32_16x16x32_bf16 v[0:3], v[216:219], v[200:203], v[0:3]
	ds_read_b128 v[168:171], v242 offset:0
	v_mfma_f32_16x16x32_bf16 v[4:7], v[220:223], v[200:203], v[4:7]
	ds_read_b128 v[184:187], v243 offset:0
	v_mfma_f32_16x16x32_bf16 v[8:11], v[228:231], v[200:203], v[8:11]
	ds_read_b128 v[172:175], v242 offset:1024
	v_mfma_f32_16x16x32_bf16 v[12:15], v[232:235], v[200:203], v[12:15]
	ds_read_b128 v[188:191], v243 offset:256
	v_mfma_f32_16x16x32_bf16 v[16:19], v[216:219], v[204:207], v[16:19]
	ds_read_b128 v[176:179], v242 offset:2048
	v_mfma_f32_16x16x32_bf16 v[20:23], v[220:223], v[204:207], v[20:23]
	ds_read_b128 v[192:195], v243 offset:512
	v_mfma_f32_16x16x32_bf16 v[24:27], v[228:231], v[204:207], v[24:27]
	ds_read_b128 v[180:183], v242 offset:3072
	v_mfma_f32_16x16x32_bf16 v[28:31], v[232:235], v[204:207], v[28:31]
	ds_read_b128 v[196:199], v243 offset:768
	v_mfma_f32_16x16x32_bf16 v[32:35], v[216:219], v[208:211], v[32:35]
	v_mfma_f32_16x16x32_bf16 v[36:39], v[220:223], v[208:211], v[36:39]
	v_mfma_f32_16x16x32_bf16 v[40:43], v[228:231], v[208:211], v[40:43]
	v_mfma_f32_16x16x32_bf16 v[44:47], v[232:235], v[208:211], v[44:47]
	v_mfma_f32_16x16x32_bf16 v[48:51], v[216:219], v[212:215], v[48:51]
	v_mfma_f32_16x16x32_bf16 v[52:55], v[220:223], v[212:215], v[52:55]
	v_mfma_f32_16x16x32_bf16 v[56:59], v[228:231], v[212:215], v[56:59]
	v_mfma_f32_16x16x32_bf16 v[60:63], v[232:235], v[212:215], v[60:63]
	s_mov_b64 s[24:25], s[50:51]
	s_mov_b64 s[26:27], s[54:55]
	s_waitcnt vmcnt(8) lgkmcnt(0)
	s_barrier
	s_add_u32 m0, s56, 0x0
	s_nop 0
	global_load_lds_dwordx4 v236, s[24:25]
	s_add_u32 m0, s56, 0x400
	s_nop 0
	global_load_lds_dwordx4 v237, s[24:25]
	s_add_u32 m0, s56, 0x2000
	s_nop 0
	global_load_lds_dwordx4 v240, s[26:27]
	s_add_u32 m0, s56, 0x2400
	s_nop 0
	global_load_lds_dwordx4 v241, s[26:27]
	s_add_u32 s24, s24, 64
	s_addc_u32 s25, s25, 0
	s_add_u32 s26, s26, 64
	s_addc_u32 s27, s27, 0
	v_mfma_f32_16x16x32_bf16 v[0:3], v[184:187], v[168:171], v[0:3]
	ds_read_b128 v[200:203], v242 offset:16384
	v_mfma_f32_16x16x32_bf16 v[4:7], v[188:191], v[168:171], v[4:7]
	ds_read_b128 v[216:219], v243 offset:16384
	v_mfma_f32_16x16x32_bf16 v[8:11], v[192:195], v[168:171], v[8:11]
	ds_read_b128 v[204:207], v242 offset:17408
	v_mfma_f32_16x16x32_bf16 v[12:15], v[196:199], v[168:171], v[12:15]
	ds_read_b128 v[220:223], v243 offset:16640
	v_mfma_f32_16x16x32_bf16 v[16:19], v[184:187], v[172:175], v[16:19]
	ds_read_b128 v[208:211], v242 offset:18432
	v_mfma_f32_16x16x32_bf16 v[20:23], v[188:191], v[172:175], v[20:23]
	ds_read_b128 v[228:231], v243 offset:16896
	v_mfma_f32_16x16x32_bf16 v[24:27], v[192:195], v[172:175], v[24:27]
	ds_read_b128 v[212:215], v242 offset:19456
	v_mfma_f32_16x16x32_bf16 v[28:31], v[196:199], v[172:175], v[28:31]
	ds_read_b128 v[232:235], v243 offset:17152
	v_mfma_f32_16x16x32_bf16 v[32:35], v[184:187], v[176:179], v[32:35]
	v_mfma_f32_16x16x32_bf16 v[36:39], v[188:191], v[176:179], v[36:39]
	v_mfma_f32_16x16x32_bf16 v[40:43], v[192:195], v[176:179], v[40:43]
	v_mfma_f32_16x16x32_bf16 v[44:47], v[196:199], v[176:179], v[44:47]
	v_mfma_f32_16x16x32_bf16 v[48:51], v[184:187], v[180:183], v[48:51]
	v_mfma_f32_16x16x32_bf16 v[52:55], v[188:191], v[180:183], v[52:55]
	v_mfma_f32_16x16x32_bf16 v[56:59], v[192:195], v[180:183], v[56:59]
	v_mfma_f32_16x16x32_bf16 v[60:63], v[196:199], v[180:183], v[60:63]
	s_waitcnt vmcnt(8) lgkmcnt(0)
	s_barrier
	s_add_u32 m0, s56, 0x4000
	s_nop 0
	global_load_lds_dwordx4 v236, s[24:25]
	s_add_u32 m0, s56, 0x4400
	s_nop 0
	global_load_lds_dwordx4 v237, s[24:25]
	s_add_u32 m0, s56, 0x6000
	s_nop 0
	global_load_lds_dwordx4 v240, s[26:27]
	s_add_u32 m0, s56, 0x6400
	s_nop 0
	global_load_lds_dwordx4 v241, s[26:27]
	s_add_u32 s24, s24, 64
	s_addc_u32 s25, s25, 0
	s_add_u32 s26, s26, 64
	s_addc_u32 s27, s27, 0
	v_mfma_f32_16x16x32_bf16 v[0:3], v[216:219], v[200:203], v[0:3]
	ds_read_b128 v[168:171], v242 offset:32768
	v_mfma_f32_16x16x32_bf16 v[4:7], v[220:223], v[200:203], v[4:7]
	ds_read_b128 v[184:187], v243 offset:32768
	v_mfma_f32_16x16x32_bf16 v[8:11], v[228:231], v[200:203], v[8:11]
	ds_read_b128 v[172:175], v242 offset:33792
	v_mfma_f32_16x16x32_bf16 v[12:15], v[232:235], v[200:203], v[12:15]
	ds_read_b128 v[188:191], v243 offset:33024
	v_mfma_f32_16x16x32_bf16 v[16:19], v[216:219], v[204:207], v[16:19]
	ds_read_b128 v[176:179], v242 offset:34816
	v_mfma_f32_16x16x32_bf16 v[20:23], v[220:223], v[204:207], v[20:23]
	ds_read_b128 v[192:195], v243 offset:33280
	v_mfma_f32_16x16x32_bf16 v[24:27], v[228:231], v[204:207], v[24:27]
	ds_read_b128 v[180:183], v242 offset:35840
	v_mfma_f32_16x16x32_bf16 v[28:31], v[232:235], v[204:207], v[28:31]
	ds_read_b128 v[196:199], v243 offset:33536
	v_mfma_f32_16x16x32_bf16 v[32:35], v[216:219], v[208:211], v[32:35]
	v_mfma_f32_16x16x32_bf16 v[36:39], v[220:223], v[208:211], v[36:39]
	v_mfma_f32_16x16x32_bf16 v[40:43], v[228:231], v[208:211], v[40:43]
	v_mfma_f32_16x16x32_bf16 v[44:47], v[232:235], v[208:211], v[44:47]
	v_mfma_f32_16x16x32_bf16 v[48:51], v[216:219], v[212:215], v[48:51]
	v_mfma_f32_16x16x32_bf16 v[52:55], v[220:223], v[212:215], v[52:55]
	v_mfma_f32_16x16x32_bf16 v[56:59], v[228:231], v[212:215], v[56:59]
	v_mfma_f32_16x16x32_bf16 v[60:63], v[232:235], v[212:215], v[60:63]
	s_waitcnt vmcnt(8) lgkmcnt(0)
	s_barrier
; template <int NI> ...
;     ...
;   G_LOAD(a0, b0, 0);
;   G_LOAD(a1, b1, 32);
;   __syncthreads();
;   G_WRITE(a0, b0, 0);
;   __syncthreads();
;   for (int kt = 0; kt < nk; kt += 2) {
;     G_LOAD(a0, b0, min((kt + 2) * 32, klast));
;     G_COMPUTE(0);
;     G_WRITE(a1, b1, 1);
;     __syncthreads();
;     G_LOAD(a1, b1, min((kt + 3) * 32, klast));
;     G_COMPUTE(1);
;     G_WRITE(a0, b0, 0);
;     __syncthreads();
; __device__ void phase_merge4(CParams& p, int l, int tm, int tn, char* smem) {
;     ...
; #pragma unroll
;       for (int mi = 0; mi < 4; mi++)
; #pragma unroll
;         for (int ni = 0; ni < 4; ni++) {
;           pk[mi][ni][0] = (unsigned)f2bf(acc[mi][ni][0]) | ((unsigned)f2bf(acc[mi][ni][1]) << 16);
;           pk[mi][ni][1] = (unsigned)f2bf(acc[mi][ni][2]) | ((unsigned)f2bf(acc[mi][ni][3]) << 16);
;         }
	s_add_u32 m0, s56, 0x8000
	s_nop 0
	global_load_lds_dwordx4 v236, s[24:25]
	s_add_u32 m0, s56, 0x8400
	s_nop 0
	global_load_lds_dwordx4 v237, s[24:25]
	s_add_u32 m0, s56, 0xa000
	s_nop 0
	global_load_lds_dwordx4 v240, s[26:27]
	s_add_u32 m0, s56, 0xa400
	s_nop 0
	global_load_lds_dwordx4 v241, s[26:27]
	s_add_u32 s24, s24, 64
	s_addc_u32 s25, s25, 0
	s_add_u32 s26, s26, 64
	s_addc_u32 s27, s27, 0
	v_mfma_f32_16x16x32_bf16 v[0:3], v[184:187], v[168:171], v[0:3]
	ds_read_b128 v[200:203], v242 offset:49152
	v_mfma_f32_16x16x32_bf16 v[4:7], v[188:191], v[168:171], v[4:7]
	ds_read_b128 v[216:219], v243 offset:49152
	v_mfma_f32_16x16x32_bf16 v[8:11], v[192:195], v[168:171], v[8:11]
	ds_read_b128 v[204:207], v242 offset:50176
	v_mfma_f32_16x16x32_bf16 v[12:15], v[196:199], v[168:171], v[12:15]
	ds_read_b128 v[220:223], v243 offset:49408
	v_mfma_f32_16x16x32_bf16 v[16:19], v[184:187], v[172:175], v[16:19]
	ds_read_b128 v[208:211], v242 offset:51200
	v_mfma_f32_16x16x32_bf16 v[20:23], v[188:191], v[172:175], v[20:23]
	ds_read_b128 v[228:231], v243 offset:49664
	v_mfma_f32_16x16x32_bf16 v[24:27], v[192:195], v[172:175], v[24:27]
	ds_read_b128 v[212:215], v242 offset:52224
	v_mfma_f32_16x16x32_bf16 v[28:31], v[196:199], v[172:175], v[28:31]
	ds_read_b128 v[232:235], v243 offset:49920
	v_mfma_f32_16x16x32_bf16 v[32:35], v[184:187], v[176:179], v[32:35]
	v_mfma_f32_16x16x32_bf16 v[36:39], v[188:191], v[176:179], v[36:39]
	v_mfma_f32_16x16x32_bf16 v[40:43], v[192:195], v[176:179], v[40:43]
	v_mfma_f32_16x16x32_bf16 v[44:47], v[196:199], v[176:179], v[44:47]
	v_mfma_f32_16x16x32_bf16 v[48:51], v[184:187], v[180:183], v[48:51]
	v_mfma_f32_16x16x32_bf16 v[52:55], v[188:191], v[180:183], v[52:55]
	v_mfma_f32_16x16x32_bf16 v[56:59], v[192:195], v[180:183], v[56:59]
	v_mfma_f32_16x16x32_bf16 v[60:63], v[196:199], v[180:183], v[60:63]
	s_waitcnt vmcnt(8) lgkmcnt(0)
	s_barrier
	s_add_u32 m0, s56, 0xc000
	s_nop 0
	global_load_lds_dwordx4 v236, s[24:25]
	s_add_u32 m0, s56, 0xc400
	s_nop 0
	global_load_lds_dwordx4 v237, s[24:25]
	s_add_u32 m0, s56, 0xe000
	s_nop 0
	global_load_lds_dwordx4 v240, s[26:27]
	s_add_u32 m0, s56, 0xe400
	s_nop 0
	global_load_lds_dwordx4 v241, s[26:27]
	s_add_u32 s24, s24, 64
	s_addc_u32 s25, s25, 0
	s_add_u32 s26, s26, 64
	s_addc_u32 s27, s27, 0
	v_mfma_f32_16x16x32_bf16 v[0:3], v[216:219], v[200:203], v[0:3]
	ds_read_b128 v[168:171], v242 offset:0
	v_mfma_f32_16x16x32_bf16 v[4:7], v[220:223], v[200:203], v[4:7]
	ds_read_b128 v[184:187], v243 offset:0
	v_mfma_f32_16x16x32_bf16 v[8:11], v[228:231], v[200:203], v[8:11]
	ds_read_b128 v[172:175], v242 offset:1024
	v_mfma_f32_16x16x32_bf16 v[12:15], v[232:235], v[200:203], v[12:15]
	ds_read_b128 v[188:191], v243 offset:256
	v_mfma_f32_16x16x32_bf16 v[16:19], v[216:219], v[204:207], v[16:19]
	ds_read_b128 v[176:179], v242 offset:2048
	v_mfma_f32_16x16x32_bf16 v[20:23], v[220:223], v[204:207], v[20:23]
	ds_read_b128 v[192:195], v243 offset:512
	v_mfma_f32_16x16x32_bf16 v[24:27], v[228:231], v[204:207], v[24:27]
	ds_read_b128 v[180:183], v242 offset:3072
	v_mfma_f32_16x16x32_bf16 v[28:31], v[232:235], v[204:207], v[28:31]
	ds_read_b128 v[196:199], v243 offset:768
	v_mfma_f32_16x16x32_bf16 v[32:35], v[216:219], v[208:211], v[32:35]
	v_mfma_f32_16x16x32_bf16 v[36:39], v[220:223], v[208:211], v[36:39]
	v_mfma_f32_16x16x32_bf16 v[40:43], v[228:231], v[208:211], v[40:43]
	v_mfma_f32_16x16x32_bf16 v[44:47], v[232:235], v[208:211], v[44:47]
	v_mfma_f32_16x16x32_bf16 v[48:51], v[216:219], v[212:215], v[48:51]
	v_mfma_f32_16x16x32_bf16 v[52:55], v[220:223], v[212:215], v[52:55]
	v_mfma_f32_16x16x32_bf16 v[56:59], v[228:231], v[212:215], v[56:59]
	v_mfma_f32_16x16x32_bf16 v[60:63], v[232:235], v[212:215], v[60:63]
	s_nop 15
	s_nop 7
	v_cvt_pk_bf16_f32 v128, v0, v1
	v_cvt_pk_bf16_f32 v129, v2, v3
	v_cvt_pk_bf16_f32 v130, v4, v5
	v_cvt_pk_bf16_f32 v131, v6, v7
	v_cvt_pk_bf16_f32 v132, v8, v9
	v_cvt_pk_bf16_f32 v133, v10, v11
	v_cvt_pk_bf16_f32 v134, v12, v13
	v_cvt_pk_bf16_f32 v135, v14, v15
	v_cvt_pk_bf16_f32 v136, v16, v17
	v_cvt_pk_bf16_f32 v137, v18, v19
	v_cvt_pk_bf16_f32 v138, v20, v21
	v_cvt_pk_bf16_f32 v139, v22, v23
	v_cvt_pk_bf16_f32 v140, v24, v25
	v_cvt_pk_bf16_f32 v141, v26, v27
	v_cvt_pk_bf16_f32 v142, v28, v29
	v_cvt_pk_bf16_f32 v143, v30, v31
	v_cvt_pk_bf16_f32 v148, v32, v33
	v_cvt_pk_bf16_f32 v149, v34, v35
	v_cvt_pk_bf16_f32 v150, v36, v37
	v_cvt_pk_bf16_f32 v151, v38, v39
	v_cvt_pk_bf16_f32 v152, v40, v41
	v_cvt_pk_bf16_f32 v153, v42, v43
	v_cvt_pk_bf16_f32 v154, v44, v45
	v_cvt_pk_bf16_f32 v155, v46, v47
	v_cvt_pk_bf16_f32 v156, v48, v49
	v_cvt_pk_bf16_f32 v157, v50, v51
	v_cvt_pk_bf16_f32 v158, v52, v53
	v_cvt_pk_bf16_f32 v159, v54, v55
	v_cvt_pk_bf16_f32 v160, v56, v57
	v_cvt_pk_bf16_f32 v161, v58, v59
	v_cvt_pk_bf16_f32 v162, v60, v61
	v_cvt_pk_bf16_f32 v163, v62, v63
	s_waitcnt vmcnt(8) lgkmcnt(0)
	s_barrier
; template <int NI> ...
;     ...
;   G_LOAD(a0, b0, 0);
;   G_LOAD(a1, b1, 32);
;   __syncthreads();
;   G_WRITE(a0, b0, 0);
;   __syncthreads();
;   for (int kt = 0; kt < nk; kt += 2) {
;     G_LOAD(a0, b0, min((kt + 2) * 32, klast));
;     G_COMPUTE(0);
;     G_WRITE(a1, b1, 1);
;     __syncthreads();
;     G_LOAD(a1, b1, min((kt + 3) * 32, klast));
;     G_COMPUTE(1);
;     G_WRITE(a0, b0, 0);
;     __syncthreads();
	s_add_u32 m0, s56, 0x0
	s_nop 0
	global_load_lds_dwordx4 v236, s[24:25]
	s_add_u32 m0, s56, 0x400
	s_nop 0
	global_load_lds_dwordx4 v237, s[24:25]
	s_add_u32 m0, s56, 0x2000
	s_nop 0
	global_load_lds_dwordx4 v240, s[26:27]
	s_add_u32 m0, s56, 0x2400
	s_nop 0
	global_load_lds_dwordx4 v241, s[26:27]
	s_add_u32 s24, s24, 64
	s_addc_u32 s25, s25, 0
	s_add_u32 s26, s26, 64
	s_addc_u32 s27, s27, 0
	v_mfma_f32_16x16x32_bf16 v[0:3], v[184:187], v[168:171], 0
	ds_read_b128 v[200:203], v242 offset:16384
	v_mfma_f32_16x16x32_bf16 v[4:7], v[188:191], v[168:171], 0
	ds_read_b128 v[216:219], v243 offset:16384
	v_mfma_f32_16x16x32_bf16 v[8:11], v[192:195], v[168:171], 0
	ds_read_b128 v[204:207], v242 offset:17408
	v_mfma_f32_16x16x32_bf16 v[12:15], v[196:199], v[168:171], 0
	ds_read_b128 v[220:223], v243 offset:16640
	v_mfma_f32_16x16x32_bf16 v[16:19], v[184:187], v[172:175], 0
	ds_read_b128 v[208:211], v242 offset:18432
	v_mfma_f32_16x16x32_bf16 v[20:23], v[188:191], v[172:175], 0
	ds_read_b128 v[228:231], v243 offset:16896
	v_mfma_f32_16x16x32_bf16 v[24:27], v[192:195], v[172:175], 0
	ds_read_b128 v[212:215], v242 offset:19456
	v_mfma_f32_16x16x32_bf16 v[28:31], v[196:199], v[172:175], 0
	ds_read_b128 v[232:235], v243 offset:17152
	v_mfma_f32_16x16x32_bf16 v[32:35], v[184:187], v[176:179], 0
	v_mfma_f32_16x16x32_bf16 v[36:39], v[188:191], v[176:179], 0
	v_mfma_f32_16x16x32_bf16 v[40:43], v[192:195], v[176:179], 0
	v_mfma_f32_16x16x32_bf16 v[44:47], v[196:199], v[176:179], 0
	v_mfma_f32_16x16x32_bf16 v[48:51], v[184:187], v[180:183], 0
	v_mfma_f32_16x16x32_bf16 v[52:55], v[188:191], v[180:183], 0
	v_mfma_f32_16x16x32_bf16 v[56:59], v[192:195], v[180:183], 0
	v_mfma_f32_16x16x32_bf16 v[60:63], v[196:199], v[180:183], 0
	s_waitcnt vmcnt(8) lgkmcnt(0)
	s_barrier
	s_add_u32 m0, s56, 0x4000
	s_nop 0
	global_load_lds_dwordx4 v236, s[24:25]
	s_add_u32 m0, s56, 0x4400
	s_nop 0
	global_load_lds_dwordx4 v237, s[24:25]
	s_add_u32 m0, s56, 0x6000
	s_nop 0
	global_load_lds_dwordx4 v240, s[26:27]
	s_add_u32 m0, s56, 0x6400
	s_nop 0
	global_load_lds_dwordx4 v241, s[26:27]
	s_add_u32 s24, s24, 64
	s_addc_u32 s25, s25, 0
	s_add_u32 s26, s26, 64
	s_addc_u32 s27, s27, 0
	v_mfma_f32_16x16x32_bf16 v[0:3], v[216:219], v[200:203], v[0:3]
	ds_read_b128 v[168:171], v242 offset:32768
	v_mfma_f32_16x16x32_bf16 v[4:7], v[220:223], v[200:203], v[4:7]
	ds_read_b128 v[184:187], v243 offset:32768
	v_mfma_f32_16x16x32_bf16 v[8:11], v[228:231], v[200:203], v[8:11]
	ds_read_b128 v[172:175], v242 offset:33792
	v_mfma_f32_16x16x32_bf16 v[12:15], v[232:235], v[200:203], v[12:15]
	ds_read_b128 v[188:191], v243 offset:33024
	v_mfma_f32_16x16x32_bf16 v[16:19], v[216:219], v[204:207], v[16:19]
	ds_read_b128 v[176:179], v242 offset:34816
	v_mfma_f32_16x16x32_bf16 v[20:23], v[220:223], v[204:207], v[20:23]
	ds_read_b128 v[192:195], v243 offset:33280
	v_mfma_f32_16x16x32_bf16 v[24:27], v[228:231], v[204:207], v[24:27]
	ds_read_b128 v[180:183], v242 offset:35840
	v_mfma_f32_16x16x32_bf16 v[28:31], v[232:235], v[204:207], v[28:31]
	ds_read_b128 v[196:199], v243 offset:33536
	v_mfma_f32_16x16x32_bf16 v[32:35], v[216:219], v[208:211], v[32:35]
	v_mfma_f32_16x16x32_bf16 v[36:39], v[220:223], v[208:211], v[36:39]
	v_mfma_f32_16x16x32_bf16 v[40:43], v[228:231], v[208:211], v[40:43]
	v_mfma_f32_16x16x32_bf16 v[44:47], v[232:235], v[208:211], v[44:47]
	v_mfma_f32_16x16x32_bf16 v[48:51], v[216:219], v[212:215], v[48:51]
	v_mfma_f32_16x16x32_bf16 v[52:55], v[220:223], v[212:215], v[52:55]
	v_mfma_f32_16x16x32_bf16 v[56:59], v[228:231], v[212:215], v[56:59]
	v_mfma_f32_16x16x32_bf16 v[60:63], v[232:235], v[212:215], v[60:63]
	s_waitcnt vmcnt(8) lgkmcnt(0)
	s_barrier
	s_add_u32 m0, s56, 0x8000
	s_nop 0
	global_load_lds_dwordx4 v236, s[24:25]
	s_add_u32 m0, s56, 0x8400
	s_nop 0
	global_load_lds_dwordx4 v237, s[24:25]
	s_add_u32 m0, s56, 0xa000
	s_nop 0
	global_load_lds_dwordx4 v240, s[26:27]
	s_add_u32 m0, s56, 0xa400
	s_nop 0
	global_load_lds_dwordx4 v241, s[26:27]
	s_add_u32 s24, s24, 64
	s_addc_u32 s25, s25, 0
	s_add_u32 s26, s26, 64
	s_addc_u32 s27, s27, 0
	v_mfma_f32_16x16x32_bf16 v[0:3], v[184:187], v[168:171], v[0:3]
	ds_read_b128 v[200:203], v242 offset:49152
	v_mfma_f32_16x16x32_bf16 v[4:7], v[188:191], v[168:171], v[4:7]
	ds_read_b128 v[216:219], v243 offset:49152
	v_mfma_f32_16x16x32_bf16 v[8:11], v[192:195], v[168:171], v[8:11]
	ds_read_b128 v[204:207], v242 offset:50176
	v_mfma_f32_16x16x32_bf16 v[12:15], v[196:199], v[168:171], v[12:15]
	ds_read_b128 v[220:223], v243 offset:49408
	v_mfma_f32_16x16x32_bf16 v[16:19], v[184:187], v[172:175], v[16:19]
	ds_read_b128 v[208:211], v242 offset:51200
	v_mfma_f32_16x16x32_bf16 v[20:23], v[188:191], v[172:175], v[20:23]
	ds_read_b128 v[228:231], v243 offset:49664
	v_mfma_f32_16x16x32_bf16 v[24:27], v[192:195], v[172:175], v[24:27]
	ds_read_b128 v[212:215], v242 offset:52224
	v_mfma_f32_16x16x32_bf16 v[28:31], v[196:199], v[172:175], v[28:31]
	ds_read_b128 v[232:235], v243 offset:49920
	v_mfma_f32_16x16x32_bf16 v[32:35], v[184:187], v[176:179], v[32:35]
	v_mfma_f32_16x16x32_bf16 v[36:39], v[188:191], v[176:179], v[36:39]
	v_mfma_f32_16x16x32_bf16 v[40:43], v[192:195], v[176:179], v[40:43]
	v_mfma_f32_16x16x32_bf16 v[44:47], v[196:199], v[176:179], v[44:47]
	v_mfma_f32_16x16x32_bf16 v[48:51], v[184:187], v[180:183], v[48:51]
	v_mfma_f32_16x16x32_bf16 v[52:55], v[188:191], v[180:183], v[52:55]
	v_mfma_f32_16x16x32_bf16 v[56:59], v[192:195], v[180:183], v[56:59]
	v_mfma_f32_16x16x32_bf16 v[60:63], v[196:199], v[180:183], v[60:63]
	s_waitcnt vmcnt(8) lgkmcnt(0)
	s_barrier
; template <int NI> ...
;     ...
;   G_LOAD(a0, b0, 0);
;   G_LOAD(a1, b1, 32);
;   __syncthreads();
;   G_WRITE(a0, b0, 0);
;   __syncthreads();
;   for (int kt = 0; kt < nk; kt += 2) {
;     G_LOAD(a0, b0, min((kt + 2) * 32, klast));
;     G_COMPUTE(0);
;     G_WRITE(a1, b1, 1);
;     __syncthreads();
;     G_LOAD(a1, b1, min((kt + 3) * 32, klast));
;     G_COMPUTE(1);
;     G_WRITE(a0, b0, 0);
;     __syncthreads();
	s_add_u32 m0, s56, 0xc000
	s_nop 0
	global_load_lds_dwordx4 v236, s[24:25]
	s_add_u32 m0, s56, 0xc400
	s_nop 0
	global_load_lds_dwordx4 v237, s[24:25]
	s_add_u32 m0, s56, 0xe000
	s_nop 0
	global_load_lds_dwordx4 v240, s[26:27]
	s_add_u32 m0, s56, 0xe400
	s_nop 0
	global_load_lds_dwordx4 v241, s[26:27]
	s_add_u32 s24, s24, 64
	s_addc_u32 s25, s25, 0
	s_add_u32 s26, s26, 64
	s_addc_u32 s27, s27, 0
	v_mfma_f32_16x16x32_bf16 v[0:3], v[216:219], v[200:203], v[0:3]
	ds_read_b128 v[168:171], v242 offset:0
	v_mfma_f32_16x16x32_bf16 v[4:7], v[220:223], v[200:203], v[4:7]
	ds_read_b128 v[184:187], v243 offset:0
	v_mfma_f32_16x16x32_bf16 v[8:11], v[228:231], v[200:203], v[8:11]
	ds_read_b128 v[172:175], v242 offset:1024
	v_mfma_f32_16x16x32_bf16 v[12:15], v[232:235], v[200:203], v[12:15]
	ds_read_b128 v[188:191], v243 offset:256
	v_mfma_f32_16x16x32_bf16 v[16:19], v[216:219], v[204:207], v[16:19]
	ds_read_b128 v[176:179], v242 offset:2048
	v_mfma_f32_16x16x32_bf16 v[20:23], v[220:223], v[204:207], v[20:23]
	ds_read_b128 v[192:195], v243 offset:512
	v_mfma_f32_16x16x32_bf16 v[24:27], v[228:231], v[204:207], v[24:27]
	ds_read_b128 v[180:183], v242 offset:3072
	v_mfma_f32_16x16x32_bf16 v[28:31], v[232:235], v[204:207], v[28:31]
	ds_read_b128 v[196:199], v243 offset:768
	v_mfma_f32_16x16x32_bf16 v[32:35], v[216:219], v[208:211], v[32:35]
	v_mfma_f32_16x16x32_bf16 v[36:39], v[220:223], v[208:211], v[36:39]
	v_mfma_f32_16x16x32_bf16 v[40:43], v[228:231], v[208:211], v[40:43]
	v_mfma_f32_16x16x32_bf16 v[44:47], v[232:235], v[208:211], v[44:47]
	v_mfma_f32_16x16x32_bf16 v[48:51], v[216:219], v[212:215], v[48:51]
	v_mfma_f32_16x16x32_bf16 v[52:55], v[220:223], v[212:215], v[52:55]
	v_mfma_f32_16x16x32_bf16 v[56:59], v[228:231], v[212:215], v[56:59]
	v_mfma_f32_16x16x32_bf16 v[60:63], v[232:235], v[212:215], v[60:63]
	s_waitcnt vmcnt(8) lgkmcnt(0)
	s_barrier
	s_add_u32 m0, s56, 0x0
	s_nop 0
	global_load_lds_dwordx4 v236, s[24:25]
	s_add_u32 m0, s56, 0x400
	s_nop 0
	global_load_lds_dwordx4 v237, s[24:25]
	s_add_u32 m0, s56, 0x2000
	s_nop 0
	global_load_lds_dwordx4 v240, s[26:27]
	s_add_u32 m0, s56, 0x2400
	s_nop 0
	global_load_lds_dwordx4 v241, s[26:27]
	s_add_u32 s24, s24, 64
	s_addc_u32 s25, s25, 0
	s_add_u32 s26, s26, 64
	s_addc_u32 s27, s27, 0
	v_mfma_f32_16x16x32_bf16 v[0:3], v[184:187], v[168:171], v[0:3]
	ds_read_b128 v[200:203], v242 offset:16384
	v_mfma_f32_16x16x32_bf16 v[4:7], v[188:191], v[168:171], v[4:7]
	ds_read_b128 v[216:219], v243 offset:16384
	v_mfma_f32_16x16x32_bf16 v[8:11], v[192:195], v[168:171], v[8:11]
	ds_read_b128 v[204:207], v242 offset:17408
	v_mfma_f32_16x16x32_bf16 v[12:15], v[196:199], v[168:171], v[12:15]
	ds_read_b128 v[220:223], v243 offset:16640
	v_mfma_f32_16x16x32_bf16 v[16:19], v[184:187], v[172:175], v[16:19]
	ds_read_b128 v[208:211], v242 offset:18432
	v_mfma_f32_16x16x32_bf16 v[20:23], v[188:191], v[172:175], v[20:23]
	ds_read_b128 v[228:231], v243 offset:16896
	v_mfma_f32_16x16x32_bf16 v[24:27], v[192:195], v[172:175], v[24:27]
	ds_read_b128 v[212:215], v242 offset:19456
	v_mfma_f32_16x16x32_bf16 v[28:31], v[196:199], v[172:175], v[28:31]
	ds_read_b128 v[232:235], v243 offset:17152
	v_mfma_f32_16x16x32_bf16 v[32:35], v[184:187], v[176:179], v[32:35]
	v_mfma_f32_16x16x32_bf16 v[36:39], v[188:191], v[176:179], v[36:39]
	v_mfma_f32_16x16x32_bf16 v[40:43], v[192:195], v[176:179], v[40:43]
	v_mfma_f32_16x16x32_bf16 v[44:47], v[196:199], v[176:179], v[44:47]
	v_mfma_f32_16x16x32_bf16 v[48:51], v[184:187], v[180:183], v[48:51]
	v_mfma_f32_16x16x32_bf16 v[52:55], v[188:191], v[180:183], v[52:55]
	v_mfma_f32_16x16x32_bf16 v[56:59], v[192:195], v[180:183], v[56:59]
	v_mfma_f32_16x16x32_bf16 v[60:63], v[196:199], v[180:183], v[60:63]
	s_waitcnt vmcnt(8) lgkmcnt(0)
	s_barrier
	s_add_u32 m0, s56, 0x4000
	s_nop 0
	global_load_lds_dwordx4 v236, s[24:25]
	s_add_u32 m0, s56, 0x4400
	s_nop 0
	global_load_lds_dwordx4 v237, s[24:25]
	s_add_u32 m0, s56, 0x6000
	s_nop 0
	global_load_lds_dwordx4 v240, s[26:27]
	s_add_u32 m0, s56, 0x6400
	s_nop 0
	global_load_lds_dwordx4 v241, s[26:27]
	s_add_u32 s24, s24, 64
	s_addc_u32 s25, s25, 0
	s_add_u32 s26, s26, 64
	s_addc_u32 s27, s27, 0
	v_mfma_f32_16x16x32_bf16 v[0:3], v[216:219], v[200:203], v[0:3]
	ds_read_b128 v[168:171], v242 offset:32768
	v_mfma_f32_16x16x32_bf16 v[4:7], v[220:223], v[200:203], v[4:7]
	ds_read_b128 v[184:187], v243 offset:32768
	v_mfma_f32_16x16x32_bf16 v[8:11], v[228:231], v[200:203], v[8:11]
	ds_read_b128 v[172:175], v242 offset:33792
	v_mfma_f32_16x16x32_bf16 v[12:15], v[232:235], v[200:203], v[12:15]
	ds_read_b128 v[188:191], v243 offset:33024
	v_mfma_f32_16x16x32_bf16 v[16:19], v[216:219], v[204:207], v[16:19]
	ds_read_b128 v[176:179], v242 offset:34816
	v_mfma_f32_16x16x32_bf16 v[20:23], v[220:223], v[204:207], v[20:23]
	ds_read_b128 v[192:195], v243 offset:33280
	v_mfma_f32_16x16x32_bf16 v[24:27], v[228:231], v[204:207], v[24:27]
	ds_read_b128 v[180:183], v242 offset:35840
	v_mfma_f32_16x16x32_bf16 v[28:31], v[232:235], v[204:207], v[28:31]
	ds_read_b128 v[196:199], v243 offset:33536
	v_mfma_f32_16x16x32_bf16 v[32:35], v[216:219], v[208:211], v[32:35]
	v_mfma_f32_16x16x32_bf16 v[36:39], v[220:223], v[208:211], v[36:39]
	v_mfma_f32_16x16x32_bf16 v[40:43], v[228:231], v[208:211], v[40:43]
	v_mfma_f32_16x16x32_bf16 v[44:47], v[232:235], v[208:211], v[44:47]
	v_mfma_f32_16x16x32_bf16 v[48:51], v[216:219], v[212:215], v[48:51]
	v_mfma_f32_16x16x32_bf16 v[52:55], v[220:223], v[212:215], v[52:55]
	v_mfma_f32_16x16x32_bf16 v[56:59], v[228:231], v[212:215], v[56:59]
	v_mfma_f32_16x16x32_bf16 v[60:63], v[232:235], v[212:215], v[60:63]
	s_waitcnt vmcnt(8) lgkmcnt(0)
	s_barrier
; template <int NI> ...
;     ...
;   G_LOAD(a0, b0, 0);
;   G_LOAD(a1, b1, 32);
;   __syncthreads();
;   G_WRITE(a0, b0, 0);
;   __syncthreads();
;   for (int kt = 0; kt < nk; kt += 2) {
;     G_LOAD(a0, b0, min((kt + 2) * 32, klast));
;     G_COMPUTE(0);
;     G_WRITE(a1, b1, 1);
;     __syncthreads();
;     G_LOAD(a1, b1, min((kt + 3) * 32, klast));
;     G_COMPUTE(1);
;     G_WRITE(a0, b0, 0);
;     __syncthreads();
	s_add_u32 m0, s56, 0x8000
	s_nop 0
	global_load_lds_dwordx4 v236, s[24:25]
	s_add_u32 m0, s56, 0x8400
	s_nop 0
	global_load_lds_dwordx4 v237, s[24:25]
	s_add_u32 m0, s56, 0xa000
	s_nop 0
	global_load_lds_dwordx4 v240, s[26:27]
	s_add_u32 m0, s56, 0xa400
	s_nop 0
	global_load_lds_dwordx4 v241, s[26:27]
	s_add_u32 s24, s24, 64
	s_addc_u32 s25, s25, 0
	s_add_u32 s26, s26, 64
	s_addc_u32 s27, s27, 0
	v_mfma_f32_16x16x32_bf16 v[0:3], v[184:187], v[168:171], v[0:3]
	ds_read_b128 v[200:203], v242 offset:49152
	v_mfma_f32_16x16x32_bf16 v[4:7], v[188:191], v[168:171], v[4:7]
	ds_read_b128 v[216:219], v243 offset:49152
	v_mfma_f32_16x16x32_bf16 v[8:11], v[192:195], v[168:171], v[8:11]
	ds_read_b128 v[204:207], v242 offset:50176
	v_mfma_f32_16x16x32_bf16 v[12:15], v[196:199], v[168:171], v[12:15]
	ds_read_b128 v[220:223], v243 offset:49408
	v_mfma_f32_16x16x32_bf16 v[16:19], v[184:187], v[172:175], v[16:19]
	ds_read_b128 v[208:211], v242 offset:51200
	v_mfma_f32_16x16x32_bf16 v[20:23], v[188:191], v[172:175], v[20:23]
	ds_read_b128 v[228:231], v243 offset:49664
	v_mfma_f32_16x16x32_bf16 v[24:27], v[192:195], v[172:175], v[24:27]
	ds_read_b128 v[212:215], v242 offset:52224
	v_mfma_f32_16x16x32_bf16 v[28:31], v[196:199], v[172:175], v[28:31]
	ds_read_b128 v[232:235], v243 offset:49920
	v_mfma_f32_16x16x32_bf16 v[32:35], v[184:187], v[176:179], v[32:35]
	v_mfma_f32_16x16x32_bf16 v[36:39], v[188:191], v[176:179], v[36:39]
	v_mfma_f32_16x16x32_bf16 v[40:43], v[192:195], v[176:179], v[40:43]
	v_mfma_f32_16x16x32_bf16 v[44:47], v[196:199], v[176:179], v[44:47]
	v_mfma_f32_16x16x32_bf16 v[48:51], v[184:187], v[180:183], v[48:51]
	v_mfma_f32_16x16x32_bf16 v[52:55], v[188:191], v[180:183], v[52:55]
	v_mfma_f32_16x16x32_bf16 v[56:59], v[192:195], v[180:183], v[56:59]
	v_mfma_f32_16x16x32_bf16 v[60:63], v[196:199], v[180:183], v[60:63]
	s_waitcnt vmcnt(8) lgkmcnt(0)
	s_barrier
	s_add_u32 m0, s56, 0xc000
	s_nop 0
	global_load_lds_dwordx4 v236, s[24:25]
	s_add_u32 m0, s56, 0xc400
	s_nop 0
	global_load_lds_dwordx4 v237, s[24:25]
	s_add_u32 m0, s56, 0xe000
	s_nop 0
	global_load_lds_dwordx4 v240, s[26:27]
	s_add_u32 m0, s56, 0xe400
	s_nop 0
	global_load_lds_dwordx4 v241, s[26:27]
	s_add_u32 s24, s24, 64
	s_addc_u32 s25, s25, 0
	s_add_u32 s26, s26, 64
	s_addc_u32 s27, s27, 0
	v_mfma_f32_16x16x32_bf16 v[0:3], v[216:219], v[200:203], v[0:3]
	ds_read_b128 v[168:171], v242 offset:0
	v_mfma_f32_16x16x32_bf16 v[4:7], v[220:223], v[200:203], v[4:7]
	ds_read_b128 v[184:187], v243 offset:0
	v_mfma_f32_16x16x32_bf16 v[8:11], v[228:231], v[200:203], v[8:11]
	ds_read_b128 v[172:175], v242 offset:1024
	v_mfma_f32_16x16x32_bf16 v[12:15], v[232:235], v[200:203], v[12:15]
	ds_read_b128 v[188:191], v243 offset:256
	v_mfma_f32_16x16x32_bf16 v[16:19], v[216:219], v[204:207], v[16:19]
	ds_read_b128 v[176:179], v242 offset:2048
	v_mfma_f32_16x16x32_bf16 v[20:23], v[220:223], v[204:207], v[20:23]
	ds_read_b128 v[192:195], v243 offset:512
	v_mfma_f32_16x16x32_bf16 v[24:27], v[228:231], v[204:207], v[24:27]
	ds_read_b128 v[180:183], v242 offset:3072
	v_mfma_f32_16x16x32_bf16 v[28:31], v[232:235], v[204:207], v[28:31]
	ds_read_b128 v[196:199], v243 offset:768
	v_mfma_f32_16x16x32_bf16 v[32:35], v[216:219], v[208:211], v[32:35]
	v_mfma_f32_16x16x32_bf16 v[36:39], v[220:223], v[208:211], v[36:39]
	v_mfma_f32_16x16x32_bf16 v[40:43], v[228:231], v[208:211], v[40:43]
	v_mfma_f32_16x16x32_bf16 v[44:47], v[232:235], v[208:211], v[44:47]
	v_mfma_f32_16x16x32_bf16 v[48:51], v[216:219], v[212:215], v[48:51]
	v_mfma_f32_16x16x32_bf16 v[52:55], v[220:223], v[212:215], v[52:55]
	v_mfma_f32_16x16x32_bf16 v[56:59], v[228:231], v[212:215], v[56:59]
	v_mfma_f32_16x16x32_bf16 v[60:63], v[232:235], v[212:215], v[60:63]
	s_waitcnt vmcnt(8) lgkmcnt(0)
	s_barrier
	s_add_u32 m0, s56, 0x0
	s_nop 0
	global_load_lds_dwordx4 v236, s[24:25]
	s_add_u32 m0, s56, 0x400
	s_nop 0
	global_load_lds_dwordx4 v237, s[24:25]
	s_add_u32 m0, s56, 0x2000
	s_nop 0
	global_load_lds_dwordx4 v240, s[26:27]
	s_add_u32 m0, s56, 0x2400
	s_nop 0
	global_load_lds_dwordx4 v241, s[26:27]
	s_add_u32 s24, s24, 64
	s_addc_u32 s25, s25, 0
	s_add_u32 s26, s26, 64
	s_addc_u32 s27, s27, 0
	v_mfma_f32_16x16x32_bf16 v[0:3], v[184:187], v[168:171], v[0:3]
	ds_read_b128 v[200:203], v242 offset:16384
	v_mfma_f32_16x16x32_bf16 v[4:7], v[188:191], v[168:171], v[4:7]
	ds_read_b128 v[216:219], v243 offset:16384
	v_mfma_f32_16x16x32_bf16 v[8:11], v[192:195], v[168:171], v[8:11]
	ds_read_b128 v[204:207], v242 offset:17408
	v_mfma_f32_16x16x32_bf16 v[12:15], v[196:199], v[168:171], v[12:15]
	ds_read_b128 v[220:223], v243 offset:16640
	v_mfma_f32_16x16x32_bf16 v[16:19], v[184:187], v[172:175], v[16:19]
	ds_read_b128 v[208:211], v242 offset:18432
	v_mfma_f32_16x16x32_bf16 v[20:23], v[188:191], v[172:175], v[20:23]
	ds_read_b128 v[228:231], v243 offset:16896
	v_mfma_f32_16x16x32_bf16 v[24:27], v[192:195], v[172:175], v[24:27]
	ds_read_b128 v[212:215], v242 offset:19456
	v_mfma_f32_16x16x32_bf16 v[28:31], v[196:199], v[172:175], v[28:31]
	ds_read_b128 v[232:235], v243 offset:17152
	v_mfma_f32_16x16x32_bf16 v[32:35], v[184:187], v[176:179], v[32:35]
	v_mfma_f32_16x16x32_bf16 v[36:39], v[188:191], v[176:179], v[36:39]
	v_mfma_f32_16x16x32_bf16 v[40:43], v[192:195], v[176:179], v[40:43]
	v_mfma_f32_16x16x32_bf16 v[44:47], v[196:199], v[176:179], v[44:47]
	v_mfma_f32_16x16x32_bf16 v[48:51], v[184:187], v[180:183], v[48:51]
	v_mfma_f32_16x16x32_bf16 v[52:55], v[188:191], v[180:183], v[52:55]
	v_mfma_f32_16x16x32_bf16 v[56:59], v[192:195], v[180:183], v[56:59]
	v_mfma_f32_16x16x32_bf16 v[60:63], v[196:199], v[180:183], v[60:63]
	s_waitcnt vmcnt(8) lgkmcnt(0)
	s_barrier
; template <int NI> ...
;     ...
;   G_LOAD(a0, b0, 0);
;   G_LOAD(a1, b1, 32);
;   __syncthreads();
;   G_WRITE(a0, b0, 0);
;   __syncthreads();
;   for (int kt = 0; kt < nk; kt += 2) {
;     G_LOAD(a0, b0, min((kt + 2) * 32, klast));
;     G_COMPUTE(0);
;     G_WRITE(a1, b1, 1);
;     __syncthreads();
;     G_LOAD(a1, b1, min((kt + 3) * 32, klast));
;     G_COMPUTE(1);
;     G_WRITE(a0, b0, 0);
;     __syncthreads();
	s_add_u32 m0, s56, 0x4000
	s_nop 0
	global_load_lds_dwordx4 v236, s[24:25]
	s_add_u32 m0, s56, 0x4400
	s_nop 0
	global_load_lds_dwordx4 v237, s[24:25]
	s_add_u32 m0, s56, 0x6000
	s_nop 0
	global_load_lds_dwordx4 v240, s[26:27]
	s_add_u32 m0, s56, 0x6400
	s_nop 0
	global_load_lds_dwordx4 v241, s[26:27]
	s_add_u32 s24, s24, 64
	s_addc_u32 s25, s25, 0
	s_add_u32 s26, s26, 64
	s_addc_u32 s27, s27, 0
	v_mfma_f32_16x16x32_bf16 v[0:3], v[216:219], v[200:203], v[0:3]
	ds_read_b128 v[168:171], v242 offset:32768
	v_mfma_f32_16x16x32_bf16 v[4:7], v[220:223], v[200:203], v[4:7]
	ds_read_b128 v[184:187], v243 offset:32768
	v_mfma_f32_16x16x32_bf16 v[8:11], v[228:231], v[200:203], v[8:11]
	ds_read_b128 v[172:175], v242 offset:33792
	v_mfma_f32_16x16x32_bf16 v[12:15], v[232:235], v[200:203], v[12:15]
	ds_read_b128 v[188:191], v243 offset:33024
	v_mfma_f32_16x16x32_bf16 v[16:19], v[216:219], v[204:207], v[16:19]
	ds_read_b128 v[176:179], v242 offset:34816
	v_mfma_f32_16x16x32_bf16 v[20:23], v[220:223], v[204:207], v[20:23]
	ds_read_b128 v[192:195], v243 offset:33280
	v_mfma_f32_16x16x32_bf16 v[24:27], v[228:231], v[204:207], v[24:27]
	ds_read_b128 v[180:183], v242 offset:35840
	v_mfma_f32_16x16x32_bf16 v[28:31], v[232:235], v[204:207], v[28:31]
	ds_read_b128 v[196:199], v243 offset:33536
	v_mfma_f32_16x16x32_bf16 v[32:35], v[216:219], v[208:211], v[32:35]
	v_mfma_f32_16x16x32_bf16 v[36:39], v[220:223], v[208:211], v[36:39]
	v_mfma_f32_16x16x32_bf16 v[40:43], v[228:231], v[208:211], v[40:43]
	v_mfma_f32_16x16x32_bf16 v[44:47], v[232:235], v[208:211], v[44:47]
	v_mfma_f32_16x16x32_bf16 v[48:51], v[216:219], v[212:215], v[48:51]
	v_mfma_f32_16x16x32_bf16 v[52:55], v[220:223], v[212:215], v[52:55]
	v_mfma_f32_16x16x32_bf16 v[56:59], v[228:231], v[212:215], v[56:59]
	v_mfma_f32_16x16x32_bf16 v[60:63], v[232:235], v[212:215], v[60:63]
	s_waitcnt vmcnt(8) lgkmcnt(0)
	s_barrier
	s_add_u32 m0, s56, 0x8000
	s_nop 0
	global_load_lds_dwordx4 v236, s[24:25]
	s_add_u32 m0, s56, 0x8400
	s_nop 0
	global_load_lds_dwordx4 v237, s[24:25]
	s_add_u32 m0, s56, 0xa000
	s_nop 0
	global_load_lds_dwordx4 v240, s[26:27]
	s_add_u32 m0, s56, 0xa400
	s_nop 0
	global_load_lds_dwordx4 v241, s[26:27]
	s_add_u32 s24, s24, 64
	s_addc_u32 s25, s25, 0
	s_add_u32 s26, s26, 64
	s_addc_u32 s27, s27, 0
	v_mfma_f32_16x16x32_bf16 v[0:3], v[184:187], v[168:171], v[0:3]
	ds_read_b128 v[200:203], v242 offset:49152
	v_mfma_f32_16x16x32_bf16 v[4:7], v[188:191], v[168:171], v[4:7]
	ds_read_b128 v[216:219], v243 offset:49152
	v_mfma_f32_16x16x32_bf16 v[8:11], v[192:195], v[168:171], v[8:11]
	ds_read_b128 v[204:207], v242 offset:50176
	v_mfma_f32_16x16x32_bf16 v[12:15], v[196:199], v[168:171], v[12:15]
	ds_read_b128 v[220:223], v243 offset:49408
	v_mfma_f32_16x16x32_bf16 v[16:19], v[184:187], v[172:175], v[16:19]
	ds_read_b128 v[208:211], v242 offset:51200
	v_mfma_f32_16x16x32_bf16 v[20:23], v[188:191], v[172:175], v[20:23]
	ds_read_b128 v[228:231], v243 offset:49664
	v_mfma_f32_16x16x32_bf16 v[24:27], v[192:195], v[172:175], v[24:27]
	ds_read_b128 v[212:215], v242 offset:52224
	v_mfma_f32_16x16x32_bf16 v[28:31], v[196:199], v[172:175], v[28:31]
	ds_read_b128 v[232:235], v243 offset:49920
	v_mfma_f32_16x16x32_bf16 v[32:35], v[184:187], v[176:179], v[32:35]
	v_mfma_f32_16x16x32_bf16 v[36:39], v[188:191], v[176:179], v[36:39]
	v_mfma_f32_16x16x32_bf16 v[40:43], v[192:195], v[176:179], v[40:43]
	v_mfma_f32_16x16x32_bf16 v[44:47], v[196:199], v[176:179], v[44:47]
	v_mfma_f32_16x16x32_bf16 v[48:51], v[184:187], v[180:183], v[48:51]
	v_mfma_f32_16x16x32_bf16 v[52:55], v[188:191], v[180:183], v[52:55]
	v_mfma_f32_16x16x32_bf16 v[56:59], v[192:195], v[180:183], v[56:59]
	v_mfma_f32_16x16x32_bf16 v[60:63], v[196:199], v[180:183], v[60:63]
	s_waitcnt vmcnt(8) lgkmcnt(0)
	s_barrier
	s_add_u32 m0, s56, 0xc000
	s_nop 0
	global_load_lds_dwordx4 v236, s[24:25]
	s_add_u32 m0, s56, 0xc400
	s_nop 0
	global_load_lds_dwordx4 v237, s[24:25]
	s_add_u32 m0, s56, 0xe000
	s_nop 0
	global_load_lds_dwordx4 v240, s[26:27]
	s_add_u32 m0, s56, 0xe400
	s_nop 0
	global_load_lds_dwordx4 v241, s[26:27]
	s_add_u32 s24, s24, 64
	s_addc_u32 s25, s25, 0
	s_add_u32 s26, s26, 64
	s_addc_u32 s27, s27, 0
	v_mfma_f32_16x16x32_bf16 v[0:3], v[216:219], v[200:203], v[0:3]
	ds_read_b128 v[168:171], v242 offset:0
	v_mfma_f32_16x16x32_bf16 v[4:7], v[220:223], v[200:203], v[4:7]
	ds_read_b128 v[184:187], v243 offset:0
	v_mfma_f32_16x16x32_bf16 v[8:11], v[228:231], v[200:203], v[8:11]
	ds_read_b128 v[172:175], v242 offset:1024
	v_mfma_f32_16x16x32_bf16 v[12:15], v[232:235], v[200:203], v[12:15]
	ds_read_b128 v[188:191], v243 offset:256
	v_mfma_f32_16x16x32_bf16 v[16:19], v[216:219], v[204:207], v[16:19]
	ds_read_b128 v[176:179], v242 offset:2048
	v_mfma_f32_16x16x32_bf16 v[20:23], v[220:223], v[204:207], v[20:23]
	ds_read_b128 v[192:195], v243 offset:512
	v_mfma_f32_16x16x32_bf16 v[24:27], v[228:231], v[204:207], v[24:27]
	ds_read_b128 v[180:183], v242 offset:3072
	v_mfma_f32_16x16x32_bf16 v[28:31], v[232:235], v[204:207], v[28:31]
	ds_read_b128 v[196:199], v243 offset:768
	v_mfma_f32_16x16x32_bf16 v[32:35], v[216:219], v[208:211], v[32:35]
	v_mfma_f32_16x16x32_bf16 v[36:39], v[220:223], v[208:211], v[36:39]
	v_mfma_f32_16x16x32_bf16 v[40:43], v[228:231], v[208:211], v[40:43]
	v_mfma_f32_16x16x32_bf16 v[44:47], v[232:235], v[208:211], v[44:47]
	v_mfma_f32_16x16x32_bf16 v[48:51], v[216:219], v[212:215], v[48:51]
	v_mfma_f32_16x16x32_bf16 v[52:55], v[220:223], v[212:215], v[52:55]
	v_mfma_f32_16x16x32_bf16 v[56:59], v[228:231], v[212:215], v[56:59]
	v_mfma_f32_16x16x32_bf16 v[60:63], v[232:235], v[212:215], v[60:63]
	s_waitcnt vmcnt(8) lgkmcnt(0)
	s_barrier
; template <int NI> ...
;     ...
;   G_LOAD(a0, b0, 0);
;   G_LOAD(a1, b1, 32);
;   __syncthreads();
;   G_WRITE(a0, b0, 0);
;   __syncthreads();
;   for (int kt = 0; kt < nk; kt += 2) {
;     G_LOAD(a0, b0, min((kt + 2) * 32, klast));
;     G_COMPUTE(0);
;     G_WRITE(a1, b1, 1);
;     __syncthreads();
;     G_LOAD(a1, b1, min((kt + 3) * 32, klast));
;     G_COMPUTE(1);
;     G_WRITE(a0, b0, 0);
;     __syncthreads();
	s_add_u32 m0, s56, 0x0
	s_nop 0
	global_load_lds_dwordx4 v236, s[24:25]
	s_add_u32 m0, s56, 0x400
	s_nop 0
	global_load_lds_dwordx4 v237, s[24:25]
	s_add_u32 m0, s56, 0x2000
	s_nop 0
	global_load_lds_dwordx4 v240, s[26:27]
	s_add_u32 m0, s56, 0x2400
	s_nop 0
	global_load_lds_dwordx4 v241, s[26:27]
	s_add_u32 s24, s24, 64
	s_addc_u32 s25, s25, 0
	s_add_u32 s26, s26, 64
	s_addc_u32 s27, s27, 0
	v_mfma_f32_16x16x32_bf16 v[0:3], v[184:187], v[168:171], v[0:3]
	ds_read_b128 v[200:203], v242 offset:16384
	v_mfma_f32_16x16x32_bf16 v[4:7], v[188:191], v[168:171], v[4:7]
	ds_read_b128 v[216:219], v243 offset:16384
	v_mfma_f32_16x16x32_bf16 v[8:11], v[192:195], v[168:171], v[8:11]
	ds_read_b128 v[204:207], v242 offset:17408
	v_mfma_f32_16x16x32_bf16 v[12:15], v[196:199], v[168:171], v[12:15]
	ds_read_b128 v[220:223], v243 offset:16640
	v_mfma_f32_16x16x32_bf16 v[16:19], v[184:187], v[172:175], v[16:19]
	ds_read_b128 v[208:211], v242 offset:18432
	v_mfma_f32_16x16x32_bf16 v[20:23], v[188:191], v[172:175], v[20:23]
	ds_read_b128 v[228:231], v243 offset:16896
	v_mfma_f32_16x16x32_bf16 v[24:27], v[192:195], v[172:175], v[24:27]
	ds_read_b128 v[212:215], v242 offset:19456
	v_mfma_f32_16x16x32_bf16 v[28:31], v[196:199], v[172:175], v[28:31]
	ds_read_b128 v[232:235], v243 offset:17152
	v_mfma_f32_16x16x32_bf16 v[32:35], v[184:187], v[176:179], v[32:35]
	v_mfma_f32_16x16x32_bf16 v[36:39], v[188:191], v[176:179], v[36:39]
	v_mfma_f32_16x16x32_bf16 v[40:43], v[192:195], v[176:179], v[40:43]
	v_mfma_f32_16x16x32_bf16 v[44:47], v[196:199], v[176:179], v[44:47]
	v_mfma_f32_16x16x32_bf16 v[48:51], v[184:187], v[180:183], v[48:51]
	v_mfma_f32_16x16x32_bf16 v[52:55], v[188:191], v[180:183], v[52:55]
	v_mfma_f32_16x16x32_bf16 v[56:59], v[192:195], v[180:183], v[56:59]
	v_mfma_f32_16x16x32_bf16 v[60:63], v[196:199], v[180:183], v[60:63]
	s_waitcnt vmcnt(8) lgkmcnt(0)
	s_barrier
	s_add_u32 m0, s56, 0x4000
	s_nop 0
	global_load_lds_dwordx4 v236, s[24:25]
	s_add_u32 m0, s56, 0x4400
	s_nop 0
	global_load_lds_dwordx4 v237, s[24:25]
	s_add_u32 m0, s56, 0x6000
	s_nop 0
	global_load_lds_dwordx4 v240, s[26:27]
	s_add_u32 m0, s56, 0x6400
	s_nop 0
	global_load_lds_dwordx4 v241, s[26:27]
	s_add_u32 s24, s24, 64
	s_addc_u32 s25, s25, 0
	s_add_u32 s26, s26, 64
	s_addc_u32 s27, s27, 0
	v_mfma_f32_16x16x32_bf16 v[0:3], v[216:219], v[200:203], v[0:3]
	ds_read_b128 v[168:171], v242 offset:32768
	v_mfma_f32_16x16x32_bf16 v[4:7], v[220:223], v[200:203], v[4:7]
	ds_read_b128 v[184:187], v243 offset:32768
	v_mfma_f32_16x16x32_bf16 v[8:11], v[228:231], v[200:203], v[8:11]
	ds_read_b128 v[172:175], v242 offset:33792
	v_mfma_f32_16x16x32_bf16 v[12:15], v[232:235], v[200:203], v[12:15]
	ds_read_b128 v[188:191], v243 offset:33024
	v_mfma_f32_16x16x32_bf16 v[16:19], v[216:219], v[204:207], v[16:19]
	ds_read_b128 v[176:179], v242 offset:34816
	v_mfma_f32_16x16x32_bf16 v[20:23], v[220:223], v[204:207], v[20:23]
	ds_read_b128 v[192:195], v243 offset:33280
	v_mfma_f32_16x16x32_bf16 v[24:27], v[228:231], v[204:207], v[24:27]
	ds_read_b128 v[180:183], v242 offset:35840
	v_mfma_f32_16x16x32_bf16 v[28:31], v[232:235], v[204:207], v[28:31]
	ds_read_b128 v[196:199], v243 offset:33536
	v_mfma_f32_16x16x32_bf16 v[32:35], v[216:219], v[208:211], v[32:35]
	v_mfma_f32_16x16x32_bf16 v[36:39], v[220:223], v[208:211], v[36:39]
	v_mfma_f32_16x16x32_bf16 v[40:43], v[228:231], v[208:211], v[40:43]
	v_mfma_f32_16x16x32_bf16 v[44:47], v[232:235], v[208:211], v[44:47]
	v_mfma_f32_16x16x32_bf16 v[48:51], v[216:219], v[212:215], v[48:51]
	v_mfma_f32_16x16x32_bf16 v[52:55], v[220:223], v[212:215], v[52:55]
	v_mfma_f32_16x16x32_bf16 v[56:59], v[228:231], v[212:215], v[56:59]
	v_mfma_f32_16x16x32_bf16 v[60:63], v[232:235], v[212:215], v[60:63]
	s_waitcnt vmcnt(8) lgkmcnt(0)
	s_barrier
	s_add_u32 m0, s56, 0x8000
	s_nop 0
	global_load_lds_dwordx4 v236, s[24:25]
	s_add_u32 m0, s56, 0x8400
	s_nop 0
	global_load_lds_dwordx4 v237, s[24:25]
	s_add_u32 m0, s56, 0xa000
	s_nop 0
	global_load_lds_dwordx4 v240, s[26:27]
	s_add_u32 m0, s56, 0xa400
	s_nop 0
	global_load_lds_dwordx4 v241, s[26:27]
	s_add_u32 s24, s24, 64
	s_addc_u32 s25, s25, 0
	s_add_u32 s26, s26, 64
	s_addc_u32 s27, s27, 0
	v_mfma_f32_16x16x32_bf16 v[0:3], v[184:187], v[168:171], v[0:3]
	ds_read_b128 v[200:203], v242 offset:49152
	v_mfma_f32_16x16x32_bf16 v[4:7], v[188:191], v[168:171], v[4:7]
	ds_read_b128 v[216:219], v243 offset:49152
	v_mfma_f32_16x16x32_bf16 v[8:11], v[192:195], v[168:171], v[8:11]
	ds_read_b128 v[204:207], v242 offset:50176
	v_mfma_f32_16x16x32_bf16 v[12:15], v[196:199], v[168:171], v[12:15]
	ds_read_b128 v[220:223], v243 offset:49408
	v_mfma_f32_16x16x32_bf16 v[16:19], v[184:187], v[172:175], v[16:19]
	ds_read_b128 v[208:211], v242 offset:51200
	v_mfma_f32_16x16x32_bf16 v[20:23], v[188:191], v[172:175], v[20:23]
	ds_read_b128 v[228:231], v243 offset:49664
	v_mfma_f32_16x16x32_bf16 v[24:27], v[192:195], v[172:175], v[24:27]
	ds_read_b128 v[212:215], v242 offset:52224
	v_mfma_f32_16x16x32_bf16 v[28:31], v[196:199], v[172:175], v[28:31]
	ds_read_b128 v[232:235], v243 offset:49920
	v_mfma_f32_16x16x32_bf16 v[32:35], v[184:187], v[176:179], v[32:35]
	v_mfma_f32_16x16x32_bf16 v[36:39], v[188:191], v[176:179], v[36:39]
	v_mfma_f32_16x16x32_bf16 v[40:43], v[192:195], v[176:179], v[40:43]
	v_mfma_f32_16x16x32_bf16 v[44:47], v[196:199], v[176:179], v[44:47]
	v_mfma_f32_16x16x32_bf16 v[48:51], v[184:187], v[180:183], v[48:51]
	v_mfma_f32_16x16x32_bf16 v[52:55], v[188:191], v[180:183], v[52:55]
	v_mfma_f32_16x16x32_bf16 v[56:59], v[192:195], v[180:183], v[56:59]
	v_mfma_f32_16x16x32_bf16 v[60:63], v[196:199], v[180:183], v[60:63]
	s_waitcnt vmcnt(8) lgkmcnt(0)
	s_barrier
; template <int NI> ...
;     ...
;   G_LOAD(a0, b0, 0);
;   G_LOAD(a1, b1, 32);
;   __syncthreads();
;   G_WRITE(a0, b0, 0);
;   __syncthreads();
;   for (int kt = 0; kt < nk; kt += 2) {
;     G_LOAD(a0, b0, min((kt + 2) * 32, klast));
;     G_COMPUTE(0);
;     G_WRITE(a1, b1, 1);
;     __syncthreads();
;     G_LOAD(a1, b1, min((kt + 3) * 32, klast));
;     G_COMPUTE(1);
;     G_WRITE(a0, b0, 0);
;     __syncthreads();
	s_add_u32 m0, s56, 0xc000
	s_nop 0
	global_load_lds_dwordx4 v236, s[24:25]
	s_add_u32 m0, s56, 0xc400
	s_nop 0
	global_load_lds_dwordx4 v237, s[24:25]
	s_add_u32 m0, s56, 0xe000
	s_nop 0
	global_load_lds_dwordx4 v240, s[26:27]
	s_add_u32 m0, s56, 0xe400
	s_nop 0
	global_load_lds_dwordx4 v241, s[26:27]
	s_add_u32 s24, s24, 64
	s_addc_u32 s25, s25, 0
	s_add_u32 s26, s26, 64
	s_addc_u32 s27, s27, 0
	v_mfma_f32_16x16x32_bf16 v[0:3], v[216:219], v[200:203], v[0:3]
	ds_read_b128 v[168:171], v242 offset:0
	v_mfma_f32_16x16x32_bf16 v[4:7], v[220:223], v[200:203], v[4:7]
	ds_read_b128 v[184:187], v243 offset:0
	v_mfma_f32_16x16x32_bf16 v[8:11], v[228:231], v[200:203], v[8:11]
	ds_read_b128 v[172:175], v242 offset:1024
	v_mfma_f32_16x16x32_bf16 v[12:15], v[232:235], v[200:203], v[12:15]
	ds_read_b128 v[188:191], v243 offset:256
	v_mfma_f32_16x16x32_bf16 v[16:19], v[216:219], v[204:207], v[16:19]
	ds_read_b128 v[176:179], v242 offset:2048
	v_mfma_f32_16x16x32_bf16 v[20:23], v[220:223], v[204:207], v[20:23]
	ds_read_b128 v[192:195], v243 offset:512
	v_mfma_f32_16x16x32_bf16 v[24:27], v[228:231], v[204:207], v[24:27]
	ds_read_b128 v[180:183], v242 offset:3072
	v_mfma_f32_16x16x32_bf16 v[28:31], v[232:235], v[204:207], v[28:31]
	ds_read_b128 v[196:199], v243 offset:768
	v_mfma_f32_16x16x32_bf16 v[32:35], v[216:219], v[208:211], v[32:35]
	v_mfma_f32_16x16x32_bf16 v[36:39], v[220:223], v[208:211], v[36:39]
	v_mfma_f32_16x16x32_bf16 v[40:43], v[228:231], v[208:211], v[40:43]
	v_mfma_f32_16x16x32_bf16 v[44:47], v[232:235], v[208:211], v[44:47]
	v_mfma_f32_16x16x32_bf16 v[48:51], v[216:219], v[212:215], v[48:51]
	v_mfma_f32_16x16x32_bf16 v[52:55], v[220:223], v[212:215], v[52:55]
	v_mfma_f32_16x16x32_bf16 v[56:59], v[228:231], v[212:215], v[56:59]
	v_mfma_f32_16x16x32_bf16 v[60:63], v[232:235], v[212:215], v[60:63]
	s_waitcnt vmcnt(8) lgkmcnt(0)
	s_barrier
	s_add_u32 m0, s56, 0x0
	s_nop 0
	global_load_lds_dwordx4 v236, s[24:25]
	s_add_u32 m0, s56, 0x400
	s_nop 0
	global_load_lds_dwordx4 v237, s[24:25]
	s_add_u32 m0, s56, 0x2000
	s_nop 0
	global_load_lds_dwordx4 v240, s[26:27]
	s_add_u32 m0, s56, 0x2400
	s_nop 0
	global_load_lds_dwordx4 v241, s[26:27]
	s_add_u32 s24, s24, 64
	s_addc_u32 s25, s25, 0
	s_add_u32 s26, s26, 64
	s_addc_u32 s27, s27, 0
	v_mfma_f32_16x16x32_bf16 v[0:3], v[184:187], v[168:171], v[0:3]
	ds_read_b128 v[200:203], v242 offset:16384
	v_mfma_f32_16x16x32_bf16 v[4:7], v[188:191], v[168:171], v[4:7]
	ds_read_b128 v[216:219], v243 offset:16384
	v_mfma_f32_16x16x32_bf16 v[8:11], v[192:195], v[168:171], v[8:11]
	ds_read_b128 v[204:207], v242 offset:17408
	v_mfma_f32_16x16x32_bf16 v[12:15], v[196:199], v[168:171], v[12:15]
	ds_read_b128 v[220:223], v243 offset:16640
	v_mfma_f32_16x16x32_bf16 v[16:19], v[184:187], v[172:175], v[16:19]
	ds_read_b128 v[208:211], v242 offset:18432
	v_mfma_f32_16x16x32_bf16 v[20:23], v[188:191], v[172:175], v[20:23]
	ds_read_b128 v[228:231], v243 offset:16896
	v_mfma_f32_16x16x32_bf16 v[24:27], v[192:195], v[172:175], v[24:27]
	ds_read_b128 v[212:215], v242 offset:19456
	v_mfma_f32_16x16x32_bf16 v[28:31], v[196:199], v[172:175], v[28:31]
	ds_read_b128 v[232:235], v243 offset:17152
	v_mfma_f32_16x16x32_bf16 v[32:35], v[184:187], v[176:179], v[32:35]
	v_mfma_f32_16x16x32_bf16 v[36:39], v[188:191], v[176:179], v[36:39]
	v_mfma_f32_16x16x32_bf16 v[40:43], v[192:195], v[176:179], v[40:43]
	v_mfma_f32_16x16x32_bf16 v[44:47], v[196:199], v[176:179], v[44:47]
	v_mfma_f32_16x16x32_bf16 v[48:51], v[184:187], v[180:183], v[48:51]
	v_mfma_f32_16x16x32_bf16 v[52:55], v[188:191], v[180:183], v[52:55]
	v_mfma_f32_16x16x32_bf16 v[56:59], v[192:195], v[180:183], v[56:59]
	v_mfma_f32_16x16x32_bf16 v[60:63], v[196:199], v[180:183], v[60:63]
	s_waitcnt vmcnt(8) lgkmcnt(0)
	s_barrier
	s_add_u32 m0, s56, 0x4000
	s_nop 0
	global_load_lds_dwordx4 v236, s[24:25]
	s_add_u32 m0, s56, 0x4400
	s_nop 0
	global_load_lds_dwordx4 v237, s[24:25]
	s_add_u32 m0, s56, 0x6000
	s_nop 0
	global_load_lds_dwordx4 v240, s[26:27]
	s_add_u32 m0, s56, 0x6400
	s_nop 0
	global_load_lds_dwordx4 v241, s[26:27]
	s_add_u32 s24, s24, 64
	s_addc_u32 s25, s25, 0
	s_add_u32 s26, s26, 64
	s_addc_u32 s27, s27, 0
	v_mfma_f32_16x16x32_bf16 v[0:3], v[216:219], v[200:203], v[0:3]
	ds_read_b128 v[168:171], v242 offset:32768
	v_mfma_f32_16x16x32_bf16 v[4:7], v[220:223], v[200:203], v[4:7]
	ds_read_b128 v[184:187], v243 offset:32768
	v_mfma_f32_16x16x32_bf16 v[8:11], v[228:231], v[200:203], v[8:11]
	ds_read_b128 v[172:175], v242 offset:33792
	v_mfma_f32_16x16x32_bf16 v[12:15], v[232:235], v[200:203], v[12:15]
	ds_read_b128 v[188:191], v243 offset:33024
	v_mfma_f32_16x16x32_bf16 v[16:19], v[216:219], v[204:207], v[16:19]
	ds_read_b128 v[176:179], v242 offset:34816
	v_mfma_f32_16x16x32_bf16 v[20:23], v[220:223], v[204:207], v[20:23]
	ds_read_b128 v[192:195], v243 offset:33280
	v_mfma_f32_16x16x32_bf16 v[24:27], v[228:231], v[204:207], v[24:27]
	ds_read_b128 v[180:183], v242 offset:35840
	v_mfma_f32_16x16x32_bf16 v[28:31], v[232:235], v[204:207], v[28:31]
	ds_read_b128 v[196:199], v243 offset:33536
	v_mfma_f32_16x16x32_bf16 v[32:35], v[216:219], v[208:211], v[32:35]
	v_mfma_f32_16x16x32_bf16 v[36:39], v[220:223], v[208:211], v[36:39]
	v_mfma_f32_16x16x32_bf16 v[40:43], v[228:231], v[208:211], v[40:43]
	v_mfma_f32_16x16x32_bf16 v[44:47], v[232:235], v[208:211], v[44:47]
	v_mfma_f32_16x16x32_bf16 v[48:51], v[216:219], v[212:215], v[48:51]
	v_mfma_f32_16x16x32_bf16 v[52:55], v[220:223], v[212:215], v[52:55]
	v_mfma_f32_16x16x32_bf16 v[56:59], v[228:231], v[212:215], v[56:59]
	v_mfma_f32_16x16x32_bf16 v[60:63], v[232:235], v[212:215], v[60:63]
	s_waitcnt vmcnt(8) lgkmcnt(0)
	s_barrier
; template <int NI> ...
;     ...
;   G_LOAD(a0, b0, 0);
;   G_LOAD(a1, b1, 32);
;   __syncthreads();
;   G_WRITE(a0, b0, 0);
;   __syncthreads();
;   for (int kt = 0; kt < nk; kt += 2) {
;     G_LOAD(a0, b0, min((kt + 2) * 32, klast));
;     G_COMPUTE(0);
;     G_WRITE(a1, b1, 1);
;     __syncthreads();
;     G_LOAD(a1, b1, min((kt + 3) * 32, klast));
;     G_COMPUTE(1);
;     G_WRITE(a0, b0, 0);
;     __syncthreads();
	s_add_u32 m0, s56, 0x8000
	s_nop 0
	global_load_lds_dwordx4 v236, s[24:25]
	s_add_u32 m0, s56, 0x8400
	s_nop 0
	global_load_lds_dwordx4 v237, s[24:25]
	s_add_u32 m0, s56, 0xa000
	s_nop 0
	global_load_lds_dwordx4 v240, s[26:27]
	s_add_u32 m0, s56, 0xa400
	s_nop 0
	global_load_lds_dwordx4 v241, s[26:27]
	s_add_u32 s24, s24, 64
	s_addc_u32 s25, s25, 0
	s_add_u32 s26, s26, 64
	s_addc_u32 s27, s27, 0
	v_mfma_f32_16x16x32_bf16 v[0:3], v[184:187], v[168:171], v[0:3]
	ds_read_b128 v[200:203], v242 offset:49152
	v_mfma_f32_16x16x32_bf16 v[4:7], v[188:191], v[168:171], v[4:7]
	ds_read_b128 v[216:219], v243 offset:49152
	v_mfma_f32_16x16x32_bf16 v[8:11], v[192:195], v[168:171], v[8:11]
	ds_read_b128 v[204:207], v242 offset:50176
	v_mfma_f32_16x16x32_bf16 v[12:15], v[196:199], v[168:171], v[12:15]
	ds_read_b128 v[220:223], v243 offset:49408
	v_mfma_f32_16x16x32_bf16 v[16:19], v[184:187], v[172:175], v[16:19]
	ds_read_b128 v[208:211], v242 offset:51200
	v_mfma_f32_16x16x32_bf16 v[20:23], v[188:191], v[172:175], v[20:23]
	ds_read_b128 v[228:231], v243 offset:49664
	v_mfma_f32_16x16x32_bf16 v[24:27], v[192:195], v[172:175], v[24:27]
	ds_read_b128 v[212:215], v242 offset:52224
	v_mfma_f32_16x16x32_bf16 v[28:31], v[196:199], v[172:175], v[28:31]
	ds_read_b128 v[232:235], v243 offset:49920
	v_mfma_f32_16x16x32_bf16 v[32:35], v[184:187], v[176:179], v[32:35]
	v_mfma_f32_16x16x32_bf16 v[36:39], v[188:191], v[176:179], v[36:39]
	v_mfma_f32_16x16x32_bf16 v[40:43], v[192:195], v[176:179], v[40:43]
	v_mfma_f32_16x16x32_bf16 v[44:47], v[196:199], v[176:179], v[44:47]
	v_mfma_f32_16x16x32_bf16 v[48:51], v[184:187], v[180:183], v[48:51]
	v_mfma_f32_16x16x32_bf16 v[52:55], v[188:191], v[180:183], v[52:55]
	v_mfma_f32_16x16x32_bf16 v[56:59], v[192:195], v[180:183], v[56:59]
	v_mfma_f32_16x16x32_bf16 v[60:63], v[196:199], v[180:183], v[60:63]
	s_waitcnt vmcnt(8) lgkmcnt(0)
	s_barrier
	s_add_u32 m0, s56, 0xc000
	s_nop 0
	global_load_lds_dwordx4 v236, s[24:25]
	s_add_u32 m0, s56, 0xc400
	s_nop 0
	global_load_lds_dwordx4 v237, s[24:25]
	s_add_u32 m0, s56, 0xe000
	s_nop 0
	global_load_lds_dwordx4 v240, s[26:27]
	s_add_u32 m0, s56, 0xe400
	s_nop 0
	global_load_lds_dwordx4 v241, s[26:27]
	s_add_u32 s24, s24, 64
	s_addc_u32 s25, s25, 0
	s_add_u32 s26, s26, 64
	s_addc_u32 s27, s27, 0
	v_mfma_f32_16x16x32_bf16 v[0:3], v[216:219], v[200:203], v[0:3]
	ds_read_b128 v[168:171], v242 offset:0
	v_mfma_f32_16x16x32_bf16 v[4:7], v[220:223], v[200:203], v[4:7]
	ds_read_b128 v[184:187], v243 offset:0
	v_mfma_f32_16x16x32_bf16 v[8:11], v[228:231], v[200:203], v[8:11]
	ds_read_b128 v[172:175], v242 offset:1024
	v_mfma_f32_16x16x32_bf16 v[12:15], v[232:235], v[200:203], v[12:15]
	ds_read_b128 v[188:191], v243 offset:256
	v_mfma_f32_16x16x32_bf16 v[16:19], v[216:219], v[204:207], v[16:19]
	ds_read_b128 v[176:179], v242 offset:2048
	v_mfma_f32_16x16x32_bf16 v[20:23], v[220:223], v[204:207], v[20:23]
	ds_read_b128 v[192:195], v243 offset:512
	v_mfma_f32_16x16x32_bf16 v[24:27], v[228:231], v[204:207], v[24:27]
	ds_read_b128 v[180:183], v242 offset:3072
	v_mfma_f32_16x16x32_bf16 v[28:31], v[232:235], v[204:207], v[28:31]
	ds_read_b128 v[196:199], v243 offset:768
	v_mfma_f32_16x16x32_bf16 v[32:35], v[216:219], v[208:211], v[32:35]
	v_mfma_f32_16x16x32_bf16 v[36:39], v[220:223], v[208:211], v[36:39]
	v_mfma_f32_16x16x32_bf16 v[40:43], v[228:231], v[208:211], v[40:43]
	v_mfma_f32_16x16x32_bf16 v[44:47], v[232:235], v[208:211], v[44:47]
	v_mfma_f32_16x16x32_bf16 v[48:51], v[216:219], v[212:215], v[48:51]
	v_mfma_f32_16x16x32_bf16 v[52:55], v[220:223], v[212:215], v[52:55]
	v_mfma_f32_16x16x32_bf16 v[56:59], v[228:231], v[212:215], v[56:59]
	v_mfma_f32_16x16x32_bf16 v[60:63], v[232:235], v[212:215], v[60:63]
	s_waitcnt vmcnt(8) lgkmcnt(0)
	s_barrier
	s_add_u32 m0, s56, 0x0
	s_nop 0
	global_load_lds_dwordx4 v236, s[24:25]
	s_add_u32 m0, s56, 0x400
	s_nop 0
	global_load_lds_dwordx4 v237, s[24:25]
	s_add_u32 m0, s56, 0x2000
	s_nop 0
	global_load_lds_dwordx4 v240, s[26:27]
	s_add_u32 m0, s56, 0x2400
	s_nop 0
	global_load_lds_dwordx4 v241, s[26:27]
	s_add_u32 s24, s24, 64
	s_addc_u32 s25, s25, 0
	s_add_u32 s26, s26, 64
	s_addc_u32 s27, s27, 0
	v_mfma_f32_16x16x32_bf16 v[0:3], v[184:187], v[168:171], v[0:3]
	ds_read_b128 v[200:203], v242 offset:16384
	v_mfma_f32_16x16x32_bf16 v[4:7], v[188:191], v[168:171], v[4:7]
	ds_read_b128 v[216:219], v243 offset:16384
	v_mfma_f32_16x16x32_bf16 v[8:11], v[192:195], v[168:171], v[8:11]
	ds_read_b128 v[204:207], v242 offset:17408
	v_mfma_f32_16x16x32_bf16 v[12:15], v[196:199], v[168:171], v[12:15]
	ds_read_b128 v[220:223], v243 offset:16640
	v_mfma_f32_16x16x32_bf16 v[16:19], v[184:187], v[172:175], v[16:19]
	ds_read_b128 v[208:211], v242 offset:18432
	v_mfma_f32_16x16x32_bf16 v[20:23], v[188:191], v[172:175], v[20:23]
	ds_read_b128 v[228:231], v243 offset:16896
	v_mfma_f32_16x16x32_bf16 v[24:27], v[192:195], v[172:175], v[24:27]
	ds_read_b128 v[212:215], v242 offset:19456
	v_mfma_f32_16x16x32_bf16 v[28:31], v[196:199], v[172:175], v[28:31]
	ds_read_b128 v[232:235], v243 offset:17152
	v_mfma_f32_16x16x32_bf16 v[32:35], v[184:187], v[176:179], v[32:35]
	v_mfma_f32_16x16x32_bf16 v[36:39], v[188:191], v[176:179], v[36:39]
	v_mfma_f32_16x16x32_bf16 v[40:43], v[192:195], v[176:179], v[40:43]
	v_mfma_f32_16x16x32_bf16 v[44:47], v[196:199], v[176:179], v[44:47]
	v_mfma_f32_16x16x32_bf16 v[48:51], v[184:187], v[180:183], v[48:51]
	v_mfma_f32_16x16x32_bf16 v[52:55], v[188:191], v[180:183], v[52:55]
	v_mfma_f32_16x16x32_bf16 v[56:59], v[192:195], v[180:183], v[56:59]
	v_mfma_f32_16x16x32_bf16 v[60:63], v[196:199], v[180:183], v[60:63]
	s_waitcnt vmcnt(8) lgkmcnt(0)
	s_barrier
; template <int NI> ...
;     ...
;   G_LOAD(a0, b0, 0);
;   G_LOAD(a1, b1, 32);
;   __syncthreads();
;   G_WRITE(a0, b0, 0);
;   __syncthreads();
;   for (int kt = 0; kt < nk; kt += 2) {
;     G_LOAD(a0, b0, min((kt + 2) * 32, klast));
;     G_COMPUTE(0);
;     G_WRITE(a1, b1, 1);
;     __syncthreads();
;     G_LOAD(a1, b1, min((kt + 3) * 32, klast));
;     G_COMPUTE(1);
;     G_WRITE(a0, b0, 0);
;     __syncthreads();
	s_add_u32 m0, s56, 0x4000
	s_nop 0
	global_load_lds_dwordx4 v236, s[24:25]
	s_add_u32 m0, s56, 0x4400
	s_nop 0
	global_load_lds_dwordx4 v237, s[24:25]
	s_add_u32 m0, s56, 0x6000
	s_nop 0
	global_load_lds_dwordx4 v240, s[26:27]
	s_add_u32 m0, s56, 0x6400
	s_nop 0
	global_load_lds_dwordx4 v241, s[26:27]
	s_add_u32 s24, s24, 64
	s_addc_u32 s25, s25, 0
	s_add_u32 s26, s26, 64
	s_addc_u32 s27, s27, 0
	v_mfma_f32_16x16x32_bf16 v[0:3], v[216:219], v[200:203], v[0:3]
	ds_read_b128 v[168:171], v242 offset:32768
	v_mfma_f32_16x16x32_bf16 v[4:7], v[220:223], v[200:203], v[4:7]
	ds_read_b128 v[184:187], v243 offset:32768
	v_mfma_f32_16x16x32_bf16 v[8:11], v[228:231], v[200:203], v[8:11]
	ds_read_b128 v[172:175], v242 offset:33792
	v_mfma_f32_16x16x32_bf16 v[12:15], v[232:235], v[200:203], v[12:15]
	ds_read_b128 v[188:191], v243 offset:33024
	v_mfma_f32_16x16x32_bf16 v[16:19], v[216:219], v[204:207], v[16:19]
	ds_read_b128 v[176:179], v242 offset:34816
	v_mfma_f32_16x16x32_bf16 v[20:23], v[220:223], v[204:207], v[20:23]
	ds_read_b128 v[192:195], v243 offset:33280
	v_mfma_f32_16x16x32_bf16 v[24:27], v[228:231], v[204:207], v[24:27]
	ds_read_b128 v[180:183], v242 offset:35840
	v_mfma_f32_16x16x32_bf16 v[28:31], v[232:235], v[204:207], v[28:31]
	ds_read_b128 v[196:199], v243 offset:33536
	v_mfma_f32_16x16x32_bf16 v[32:35], v[216:219], v[208:211], v[32:35]
	v_mfma_f32_16x16x32_bf16 v[36:39], v[220:223], v[208:211], v[36:39]
	v_mfma_f32_16x16x32_bf16 v[40:43], v[228:231], v[208:211], v[40:43]
	v_mfma_f32_16x16x32_bf16 v[44:47], v[232:235], v[208:211], v[44:47]
	v_mfma_f32_16x16x32_bf16 v[48:51], v[216:219], v[212:215], v[48:51]
	v_mfma_f32_16x16x32_bf16 v[52:55], v[220:223], v[212:215], v[52:55]
	v_mfma_f32_16x16x32_bf16 v[56:59], v[228:231], v[212:215], v[56:59]
	v_mfma_f32_16x16x32_bf16 v[60:63], v[232:235], v[212:215], v[60:63]
	s_waitcnt vmcnt(8) lgkmcnt(0)
	s_barrier
	s_add_u32 m0, s56, 0x8000
	s_nop 0
	global_load_lds_dwordx4 v236, s[24:25]
	s_add_u32 m0, s56, 0x8400
	s_nop 0
	global_load_lds_dwordx4 v237, s[24:25]
	s_add_u32 m0, s56, 0xa000
	s_nop 0
	global_load_lds_dwordx4 v240, s[26:27]
	s_add_u32 m0, s56, 0xa400
	s_nop 0
	global_load_lds_dwordx4 v241, s[26:27]
	s_add_u32 s24, s24, 64
	s_addc_u32 s25, s25, 0
	s_add_u32 s26, s26, 64
	s_addc_u32 s27, s27, 0
	v_mfma_f32_16x16x32_bf16 v[0:3], v[184:187], v[168:171], v[0:3]
	ds_read_b128 v[200:203], v242 offset:49152
	v_mfma_f32_16x16x32_bf16 v[4:7], v[188:191], v[168:171], v[4:7]
	ds_read_b128 v[216:219], v243 offset:49152
	v_mfma_f32_16x16x32_bf16 v[8:11], v[192:195], v[168:171], v[8:11]
	ds_read_b128 v[204:207], v242 offset:50176
	v_mfma_f32_16x16x32_bf16 v[12:15], v[196:199], v[168:171], v[12:15]
	ds_read_b128 v[220:223], v243 offset:49408
	v_mfma_f32_16x16x32_bf16 v[16:19], v[184:187], v[172:175], v[16:19]
	ds_read_b128 v[208:211], v242 offset:51200
	v_mfma_f32_16x16x32_bf16 v[20:23], v[188:191], v[172:175], v[20:23]
	ds_read_b128 v[228:231], v243 offset:49664
	v_mfma_f32_16x16x32_bf16 v[24:27], v[192:195], v[172:175], v[24:27]
	ds_read_b128 v[212:215], v242 offset:52224
	v_mfma_f32_16x16x32_bf16 v[28:31], v[196:199], v[172:175], v[28:31]
	ds_read_b128 v[232:235], v243 offset:49920
	v_mfma_f32_16x16x32_bf16 v[32:35], v[184:187], v[176:179], v[32:35]
	v_mfma_f32_16x16x32_bf16 v[36:39], v[188:191], v[176:179], v[36:39]
	v_mfma_f32_16x16x32_bf16 v[40:43], v[192:195], v[176:179], v[40:43]
	v_mfma_f32_16x16x32_bf16 v[44:47], v[196:199], v[176:179], v[44:47]
	v_mfma_f32_16x16x32_bf16 v[48:51], v[184:187], v[180:183], v[48:51]
	v_mfma_f32_16x16x32_bf16 v[52:55], v[188:191], v[180:183], v[52:55]
	v_mfma_f32_16x16x32_bf16 v[56:59], v[192:195], v[180:183], v[56:59]
	v_mfma_f32_16x16x32_bf16 v[60:63], v[196:199], v[180:183], v[60:63]
	s_waitcnt vmcnt(8) lgkmcnt(0)
	s_barrier
	s_add_u32 m0, s56, 0xc000
	s_nop 0
	global_load_lds_dwordx4 v236, s[24:25]
	s_add_u32 m0, s56, 0xc400
	s_nop 0
	global_load_lds_dwordx4 v237, s[24:25]
	s_add_u32 m0, s56, 0xe000
	s_nop 0
	global_load_lds_dwordx4 v240, s[26:27]
	s_add_u32 m0, s56, 0xe400
	s_nop 0
	global_load_lds_dwordx4 v241, s[26:27]
	s_add_u32 s24, s24, 64
	s_addc_u32 s25, s25, 0
	s_add_u32 s26, s26, 64
	s_addc_u32 s27, s27, 0
	v_mfma_f32_16x16x32_bf16 v[0:3], v[216:219], v[200:203], v[0:3]
	ds_read_b128 v[168:171], v242 offset:0
	v_mfma_f32_16x16x32_bf16 v[4:7], v[220:223], v[200:203], v[4:7]
	ds_read_b128 v[184:187], v243 offset:0
	v_mfma_f32_16x16x32_bf16 v[8:11], v[228:231], v[200:203], v[8:11]
	ds_read_b128 v[172:175], v242 offset:1024
	v_mfma_f32_16x16x32_bf16 v[12:15], v[232:235], v[200:203], v[12:15]
	ds_read_b128 v[188:191], v243 offset:256
	v_mfma_f32_16x16x32_bf16 v[16:19], v[216:219], v[204:207], v[16:19]
	ds_read_b128 v[176:179], v242 offset:2048
	v_mfma_f32_16x16x32_bf16 v[20:23], v[220:223], v[204:207], v[20:23]
	ds_read_b128 v[192:195], v243 offset:512
	v_mfma_f32_16x16x32_bf16 v[24:27], v[228:231], v[204:207], v[24:27]
	ds_read_b128 v[180:183], v242 offset:3072
	v_mfma_f32_16x16x32_bf16 v[28:31], v[232:235], v[204:207], v[28:31]
	ds_read_b128 v[196:199], v243 offset:768
	v_mfma_f32_16x16x32_bf16 v[32:35], v[216:219], v[208:211], v[32:35]
	v_mfma_f32_16x16x32_bf16 v[36:39], v[220:223], v[208:211], v[36:39]
	v_mfma_f32_16x16x32_bf16 v[40:43], v[228:231], v[208:211], v[40:43]
	v_mfma_f32_16x16x32_bf16 v[44:47], v[232:235], v[208:211], v[44:47]
	v_mfma_f32_16x16x32_bf16 v[48:51], v[216:219], v[212:215], v[48:51]
	v_mfma_f32_16x16x32_bf16 v[52:55], v[220:223], v[212:215], v[52:55]
	v_mfma_f32_16x16x32_bf16 v[56:59], v[228:231], v[212:215], v[56:59]
	v_mfma_f32_16x16x32_bf16 v[60:63], v[232:235], v[212:215], v[60:63]
	s_waitcnt vmcnt(8) lgkmcnt(0)
	s_barrier
; template <int NI> ...
;     ...
;   G_LOAD(a0, b0, 0);
;   G_LOAD(a1, b1, 32);
;   __syncthreads();
;   G_WRITE(a0, b0, 0);
;   __syncthreads();
;   for (int kt = 0; kt < nk; kt += 2) {
;     G_LOAD(a0, b0, min((kt + 2) * 32, klast));
;     G_COMPUTE(0);
;     G_WRITE(a1, b1, 1);
;     __syncthreads();
;     G_LOAD(a1, b1, min((kt + 3) * 32, klast));
;     G_COMPUTE(1);
;     G_WRITE(a0, b0, 0);
;     __syncthreads();
	s_add_u32 m0, s56, 0x0
	s_nop 0
	global_load_lds_dwordx4 v236, s[24:25]
	s_add_u32 m0, s56, 0x400
	s_nop 0
	global_load_lds_dwordx4 v237, s[24:25]
	s_add_u32 m0, s56, 0x2000
	s_nop 0
	global_load_lds_dwordx4 v240, s[26:27]
	s_add_u32 m0, s56, 0x2400
	s_nop 0
	global_load_lds_dwordx4 v241, s[26:27]
	s_add_u32 s24, s24, 64
	s_addc_u32 s25, s25, 0
	s_add_u32 s26, s26, 64
	s_addc_u32 s27, s27, 0
	v_mfma_f32_16x16x32_bf16 v[0:3], v[184:187], v[168:171], v[0:3]
	ds_read_b128 v[200:203], v242 offset:16384
	v_mfma_f32_16x16x32_bf16 v[4:7], v[188:191], v[168:171], v[4:7]
	ds_read_b128 v[216:219], v243 offset:16384
	v_mfma_f32_16x16x32_bf16 v[8:11], v[192:195], v[168:171], v[8:11]
	ds_read_b128 v[204:207], v242 offset:17408
	v_mfma_f32_16x16x32_bf16 v[12:15], v[196:199], v[168:171], v[12:15]
	ds_read_b128 v[220:223], v243 offset:16640
	v_mfma_f32_16x16x32_bf16 v[16:19], v[184:187], v[172:175], v[16:19]
	ds_read_b128 v[208:211], v242 offset:18432
	v_mfma_f32_16x16x32_bf16 v[20:23], v[188:191], v[172:175], v[20:23]
	ds_read_b128 v[228:231], v243 offset:16896
	v_mfma_f32_16x16x32_bf16 v[24:27], v[192:195], v[172:175], v[24:27]
	ds_read_b128 v[212:215], v242 offset:19456
	v_mfma_f32_16x16x32_bf16 v[28:31], v[196:199], v[172:175], v[28:31]
	ds_read_b128 v[232:235], v243 offset:17152
	v_mfma_f32_16x16x32_bf16 v[32:35], v[184:187], v[176:179], v[32:35]
	v_mfma_f32_16x16x32_bf16 v[36:39], v[188:191], v[176:179], v[36:39]
	v_mfma_f32_16x16x32_bf16 v[40:43], v[192:195], v[176:179], v[40:43]
	v_mfma_f32_16x16x32_bf16 v[44:47], v[196:199], v[176:179], v[44:47]
	v_mfma_f32_16x16x32_bf16 v[48:51], v[184:187], v[180:183], v[48:51]
	v_mfma_f32_16x16x32_bf16 v[52:55], v[188:191], v[180:183], v[52:55]
	v_mfma_f32_16x16x32_bf16 v[56:59], v[192:195], v[180:183], v[56:59]
	v_mfma_f32_16x16x32_bf16 v[60:63], v[196:199], v[180:183], v[60:63]
	s_waitcnt vmcnt(8) lgkmcnt(0)
	s_barrier
	s_add_u32 m0, s56, 0x4000
	s_nop 0
	global_load_lds_dwordx4 v236, s[24:25]
	s_add_u32 m0, s56, 0x4400
	s_nop 0
	global_load_lds_dwordx4 v237, s[24:25]
	s_add_u32 m0, s56, 0x6000
	s_nop 0
	global_load_lds_dwordx4 v240, s[26:27]
	s_add_u32 m0, s56, 0x6400
	s_nop 0
	global_load_lds_dwordx4 v241, s[26:27]
	s_add_u32 s24, s24, 64
	s_addc_u32 s25, s25, 0
	s_add_u32 s26, s26, 64
	s_addc_u32 s27, s27, 0
	v_mfma_f32_16x16x32_bf16 v[0:3], v[216:219], v[200:203], v[0:3]
	ds_read_b128 v[168:171], v242 offset:32768
	v_mfma_f32_16x16x32_bf16 v[4:7], v[220:223], v[200:203], v[4:7]
	ds_read_b128 v[184:187], v243 offset:32768
	v_mfma_f32_16x16x32_bf16 v[8:11], v[228:231], v[200:203], v[8:11]
	ds_read_b128 v[172:175], v242 offset:33792
	v_mfma_f32_16x16x32_bf16 v[12:15], v[232:235], v[200:203], v[12:15]
	ds_read_b128 v[188:191], v243 offset:33024
	v_mfma_f32_16x16x32_bf16 v[16:19], v[216:219], v[204:207], v[16:19]
	ds_read_b128 v[176:179], v242 offset:34816
	v_mfma_f32_16x16x32_bf16 v[20:23], v[220:223], v[204:207], v[20:23]
	ds_read_b128 v[192:195], v243 offset:33280
	v_mfma_f32_16x16x32_bf16 v[24:27], v[228:231], v[204:207], v[24:27]
	ds_read_b128 v[180:183], v242 offset:35840
	v_mfma_f32_16x16x32_bf16 v[28:31], v[232:235], v[204:207], v[28:31]
	ds_read_b128 v[196:199], v243 offset:33536
	v_mfma_f32_16x16x32_bf16 v[32:35], v[216:219], v[208:211], v[32:35]
	v_mfma_f32_16x16x32_bf16 v[36:39], v[220:223], v[208:211], v[36:39]
	v_mfma_f32_16x16x32_bf16 v[40:43], v[228:231], v[208:211], v[40:43]
	v_mfma_f32_16x16x32_bf16 v[44:47], v[232:235], v[208:211], v[44:47]
	v_mfma_f32_16x16x32_bf16 v[48:51], v[216:219], v[212:215], v[48:51]
	v_mfma_f32_16x16x32_bf16 v[52:55], v[220:223], v[212:215], v[52:55]
	v_mfma_f32_16x16x32_bf16 v[56:59], v[228:231], v[212:215], v[56:59]
	v_mfma_f32_16x16x32_bf16 v[60:63], v[232:235], v[212:215], v[60:63]
	s_waitcnt vmcnt(8) lgkmcnt(0)
	s_barrier
	s_add_u32 m0, s56, 0x8000
	s_nop 0
	global_load_lds_dwordx4 v236, s[24:25]
	s_add_u32 m0, s56, 0x8400
	s_nop 0
	global_load_lds_dwordx4 v237, s[24:25]
	s_add_u32 m0, s56, 0xa000
	s_nop 0
	global_load_lds_dwordx4 v240, s[26:27]
	s_add_u32 m0, s56, 0xa400
	s_nop 0
	global_load_lds_dwordx4 v241, s[26:27]
	s_add_u32 s24, s24, 64
	s_addc_u32 s25, s25, 0
	s_add_u32 s26, s26, 64
	s_addc_u32 s27, s27, 0
	v_mfma_f32_16x16x32_bf16 v[0:3], v[184:187], v[168:171], v[0:3]
	ds_read_b128 v[200:203], v242 offset:49152
	v_mfma_f32_16x16x32_bf16 v[4:7], v[188:191], v[168:171], v[4:7]
	ds_read_b128 v[216:219], v243 offset:49152
	v_mfma_f32_16x16x32_bf16 v[8:11], v[192:195], v[168:171], v[8:11]
	ds_read_b128 v[204:207], v242 offset:50176
	v_mfma_f32_16x16x32_bf16 v[12:15], v[196:199], v[168:171], v[12:15]
	ds_read_b128 v[220:223], v243 offset:49408
	v_mfma_f32_16x16x32_bf16 v[16:19], v[184:187], v[172:175], v[16:19]
	ds_read_b128 v[208:211], v242 offset:51200
	v_mfma_f32_16x16x32_bf16 v[20:23], v[188:191], v[172:175], v[20:23]
	ds_read_b128 v[228:231], v243 offset:49664
	v_mfma_f32_16x16x32_bf16 v[24:27], v[192:195], v[172:175], v[24:27]
	ds_read_b128 v[212:215], v242 offset:52224
	v_mfma_f32_16x16x32_bf16 v[28:31], v[196:199], v[172:175], v[28:31]
	ds_read_b128 v[232:235], v243 offset:49920
	v_mfma_f32_16x16x32_bf16 v[32:35], v[184:187], v[176:179], v[32:35]
	v_mfma_f32_16x16x32_bf16 v[36:39], v[188:191], v[176:179], v[36:39]
	v_mfma_f32_16x16x32_bf16 v[40:43], v[192:195], v[176:179], v[40:43]
	v_mfma_f32_16x16x32_bf16 v[44:47], v[196:199], v[176:179], v[44:47]
	v_mfma_f32_16x16x32_bf16 v[48:51], v[184:187], v[180:183], v[48:51]
	v_mfma_f32_16x16x32_bf16 v[52:55], v[188:191], v[180:183], v[52:55]
	v_mfma_f32_16x16x32_bf16 v[56:59], v[192:195], v[180:183], v[56:59]
	v_mfma_f32_16x16x32_bf16 v[60:63], v[196:199], v[180:183], v[60:63]
	s_waitcnt vmcnt(8) lgkmcnt(0)
	s_barrier
; template <int NI> ...
;     ...
;   G_LOAD(a0, b0, 0);
;   G_LOAD(a1, b1, 32);
;   __syncthreads();
;   G_WRITE(a0, b0, 0);
;   __syncthreads();
;   for (int kt = 0; kt < nk; kt += 2) {
;     G_LOAD(a0, b0, min((kt + 2) * 32, klast));
;     G_COMPUTE(0);
;     G_WRITE(a1, b1, 1);
;     __syncthreads();
;     G_LOAD(a1, b1, min((kt + 3) * 32, klast));
;     G_COMPUTE(1);
;     G_WRITE(a0, b0, 0);
;     __syncthreads();
; __device__ void phase_merge4(CParams& p, int l, int tm, int tn, char* smem) {
;     ...
;   for (int kb0 = 0; kb0 < 4; kb0++) {
;     int kb = kb0;
;     asm volatile("" : "+s"(kb));
;     int tid2 = tid;
;     asm volatile("" : "+v"(tid2));
;     unsigned pk[4][4][2];
;     {
;       f32x4 acc[4][4];
;       zero_acc<4>(acc);
;       gemm_mainloop<4>(p.br + (size_t)row0 * 1024 + kb * 256, 1024,
;                        p.WbT + (((size_t)l * 4 + kb) * 1024 + col0) * 256, 256, 256, sA, sB, acc, tid2);
	s_add_u32 m0, s56, 0xc000
	s_nop 0
	global_load_lds_dwordx4 v236, s[24:25]
	s_add_u32 m0, s56, 0xc400
	s_nop 0
	global_load_lds_dwordx4 v237, s[24:25]
	s_add_u32 m0, s56, 0xe000
	s_nop 0
	global_load_lds_dwordx4 v240, s[26:27]
	s_add_u32 m0, s56, 0xe400
	s_nop 0
	global_load_lds_dwordx4 v241, s[26:27]
	s_add_u32 s24, s24, 64
	s_addc_u32 s25, s25, 0
	s_add_u32 s26, s26, 64
	s_addc_u32 s27, s27, 0
	v_mfma_f32_16x16x32_bf16 v[0:3], v[216:219], v[200:203], v[0:3]
	ds_read_b128 v[168:171], v242 offset:0
	v_mfma_f32_16x16x32_bf16 v[4:7], v[220:223], v[200:203], v[4:7]
	ds_read_b128 v[184:187], v243 offset:0
	v_mfma_f32_16x16x32_bf16 v[8:11], v[228:231], v[200:203], v[8:11]
	ds_read_b128 v[172:175], v242 offset:1024
	v_mfma_f32_16x16x32_bf16 v[12:15], v[232:235], v[200:203], v[12:15]
	ds_read_b128 v[188:191], v243 offset:256
	v_mfma_f32_16x16x32_bf16 v[16:19], v[216:219], v[204:207], v[16:19]
	ds_read_b128 v[176:179], v242 offset:2048
	v_mfma_f32_16x16x32_bf16 v[20:23], v[220:223], v[204:207], v[20:23]
	ds_read_b128 v[192:195], v243 offset:512
	v_mfma_f32_16x16x32_bf16 v[24:27], v[228:231], v[204:207], v[24:27]
	ds_read_b128 v[180:183], v242 offset:3072
	v_mfma_f32_16x16x32_bf16 v[28:31], v[232:235], v[204:207], v[28:31]
	ds_read_b128 v[196:199], v243 offset:768
	v_mfma_f32_16x16x32_bf16 v[32:35], v[216:219], v[208:211], v[32:35]
	v_mfma_f32_16x16x32_bf16 v[36:39], v[220:223], v[208:211], v[36:39]
	v_mfma_f32_16x16x32_bf16 v[40:43], v[228:231], v[208:211], v[40:43]
	v_mfma_f32_16x16x32_bf16 v[44:47], v[232:235], v[208:211], v[44:47]
	v_mfma_f32_16x16x32_bf16 v[48:51], v[216:219], v[212:215], v[48:51]
	v_mfma_f32_16x16x32_bf16 v[52:55], v[220:223], v[212:215], v[52:55]
	v_mfma_f32_16x16x32_bf16 v[56:59], v[228:231], v[212:215], v[56:59]
	v_mfma_f32_16x16x32_bf16 v[60:63], v[232:235], v[212:215], v[60:63]
	s_mov_b64 s[24:25], s[28:29]
	s_mov_b64 s[26:27], s[44:45]
	s_waitcnt vmcnt(8) lgkmcnt(0)
	s_barrier
	s_add_u32 m0, s56, 0x0
	s_nop 0
	global_load_lds_dwordx4 v236, s[24:25]
	s_add_u32 m0, s56, 0x400
	s_nop 0
	global_load_lds_dwordx4 v237, s[24:25]
	s_add_u32 m0, s56, 0x2000
	s_nop 0
	global_load_lds_dwordx4 v238, s[26:27]
	s_add_u32 m0, s56, 0x2400
	s_nop 0
	global_load_lds_dwordx4 v239, s[26:27]
	s_add_u32 s24, s24, 64
	s_addc_u32 s25, s25, 0
	s_add_u32 s26, s26, 64
	s_addc_u32 s27, s27, 0
	v_mfma_f32_16x16x32_bf16 v[0:3], v[184:187], v[168:171], v[0:3]
	ds_read_b128 v[200:203], v242 offset:16384
	v_mfma_f32_16x16x32_bf16 v[4:7], v[188:191], v[168:171], v[4:7]
	ds_read_b128 v[216:219], v243 offset:16384
	v_mfma_f32_16x16x32_bf16 v[8:11], v[192:195], v[168:171], v[8:11]
	ds_read_b128 v[204:207], v242 offset:17408
	v_mfma_f32_16x16x32_bf16 v[12:15], v[196:199], v[168:171], v[12:15]
	ds_read_b128 v[220:223], v243 offset:16640
	v_mfma_f32_16x16x32_bf16 v[16:19], v[184:187], v[172:175], v[16:19]
	ds_read_b128 v[208:211], v242 offset:18432
	v_mfma_f32_16x16x32_bf16 v[20:23], v[188:191], v[172:175], v[20:23]
	ds_read_b128 v[228:231], v243 offset:16896
	v_mfma_f32_16x16x32_bf16 v[24:27], v[192:195], v[172:175], v[24:27]
	ds_read_b128 v[212:215], v242 offset:19456
	v_mfma_f32_16x16x32_bf16 v[28:31], v[196:199], v[172:175], v[28:31]
	ds_read_b128 v[232:235], v243 offset:17152
	v_mfma_f32_16x16x32_bf16 v[32:35], v[184:187], v[176:179], v[32:35]
	v_mfma_f32_16x16x32_bf16 v[36:39], v[188:191], v[176:179], v[36:39]
	v_mfma_f32_16x16x32_bf16 v[40:43], v[192:195], v[176:179], v[40:43]
	v_mfma_f32_16x16x32_bf16 v[44:47], v[196:199], v[176:179], v[44:47]
	v_mfma_f32_16x16x32_bf16 v[48:51], v[184:187], v[180:183], v[48:51]
	v_mfma_f32_16x16x32_bf16 v[52:55], v[188:191], v[180:183], v[52:55]
	v_mfma_f32_16x16x32_bf16 v[56:59], v[192:195], v[180:183], v[56:59]
	v_mfma_f32_16x16x32_bf16 v[60:63], v[196:199], v[180:183], v[60:63]
	s_waitcnt vmcnt(8) lgkmcnt(0)
	s_barrier
	s_add_u32 m0, s56, 0x4000
	s_nop 0
	global_load_lds_dwordx4 v236, s[24:25]
	s_add_u32 m0, s56, 0x4400
	s_nop 0
	global_load_lds_dwordx4 v237, s[24:25]
	s_add_u32 m0, s56, 0x6000
	s_nop 0
	global_load_lds_dwordx4 v238, s[26:27]
	s_add_u32 m0, s56, 0x6400
	s_nop 0
	global_load_lds_dwordx4 v239, s[26:27]
	s_add_u32 s24, s24, 64
	s_addc_u32 s25, s25, 0
	s_add_u32 s26, s26, 64
	s_addc_u32 s27, s27, 0
	v_mfma_f32_16x16x32_bf16 v[0:3], v[216:219], v[200:203], v[0:3]
	ds_read_b128 v[168:171], v242 offset:32768
	v_mfma_f32_16x16x32_bf16 v[4:7], v[220:223], v[200:203], v[4:7]
	ds_read_b128 v[184:187], v243 offset:32768
	v_mfma_f32_16x16x32_bf16 v[8:11], v[228:231], v[200:203], v[8:11]
	ds_read_b128 v[172:175], v242 offset:33792
	v_mfma_f32_16x16x32_bf16 v[12:15], v[232:235], v[200:203], v[12:15]
	ds_read_b128 v[188:191], v243 offset:33024
	v_mfma_f32_16x16x32_bf16 v[16:19], v[216:219], v[204:207], v[16:19]
	ds_read_b128 v[176:179], v242 offset:34816
	v_mfma_f32_16x16x32_bf16 v[20:23], v[220:223], v[204:207], v[20:23]
	ds_read_b128 v[192:195], v243 offset:33280
	v_mfma_f32_16x16x32_bf16 v[24:27], v[228:231], v[204:207], v[24:27]
	ds_read_b128 v[180:183], v242 offset:35840
	v_mfma_f32_16x16x32_bf16 v[28:31], v[232:235], v[204:207], v[28:31]
	ds_read_b128 v[196:199], v243 offset:33536
	v_mfma_f32_16x16x32_bf16 v[32:35], v[216:219], v[208:211], v[32:35]
	v_mfma_f32_16x16x32_bf16 v[36:39], v[220:223], v[208:211], v[36:39]
	v_mfma_f32_16x16x32_bf16 v[40:43], v[228:231], v[208:211], v[40:43]
	v_mfma_f32_16x16x32_bf16 v[44:47], v[232:235], v[208:211], v[44:47]
	v_mfma_f32_16x16x32_bf16 v[48:51], v[216:219], v[212:215], v[48:51]
	v_mfma_f32_16x16x32_bf16 v[52:55], v[220:223], v[212:215], v[52:55]
	v_mfma_f32_16x16x32_bf16 v[56:59], v[228:231], v[212:215], v[56:59]
	v_mfma_f32_16x16x32_bf16 v[60:63], v[232:235], v[212:215], v[60:63]
	s_waitcnt vmcnt(8) lgkmcnt(0)
	s_barrier
; __device__ __forceinline__ float sigmoidf_(float v) { return 1.f / (1.f + __expf(-v)); }
; template <int NI> ...
;     ...
;   G_LOAD(a0, b0, 0);
;   G_LOAD(a1, b1, 32);
;   __syncthreads();
;   G_WRITE(a0, b0, 0);
;   __syncthreads();
;   for (int kt = 0; kt < nk; kt += 2) {
;     G_LOAD(a0, b0, min((kt + 2) * 32, klast));
;     G_COMPUTE(0);
;     G_WRITE(a1, b1, 1);
;     __syncthreads();
;     G_LOAD(a1, b1, min((kt + 3) * 32, klast));
;     G_COMPUTE(1);
;     G_WRITE(a0, b0, 0);
;     __syncthreads();
; __device__ void phase_merge4(CParams& p, int l, int tm, int tn, char* smem) {
;     ...
; #pragma unroll
;     for (int mi = 0; mi < 4; mi++)
; #pragma unroll
;       for (int ni = 0; ni < 4; ni++) {
;         unsigned p0 = pk[mi][ni][0], p1 = pk[mi][ni][1], m0 = mer[mi][ni][0], m1 = mer[mi][ni][1];
;         float r0 = __uint_as_float(m0 << 16) + sigmoidf_(acc[mi][ni][0]) * __uint_as_float(p0 << 16);
;         float r1 = __uint_as_float(m0 & 0xffff0000u) + sigmoidf_(acc[mi][ni][1]) * __uint_as_float(p0 & 0xffff0000u);
;         float r2 = __uint_as_float(m1 << 16) + sigmoidf_(acc[mi][ni][2]) * __uint_as_float(p1 << 16);
;         float r3 = __uint_as_float(m1 & 0xffff0000u) + sigmoidf_(acc[mi][ni][3]) * __uint_as_float(p1 & 0xffff0000u);
	s_add_u32 m0, s56, 0x8000
	s_nop 0
	global_load_lds_dwordx4 v236, s[24:25]
	s_add_u32 m0, s56, 0x8400
	s_nop 0
	global_load_lds_dwordx4 v237, s[24:25]
	s_add_u32 m0, s56, 0xa000
	s_nop 0
	global_load_lds_dwordx4 v238, s[26:27]
	s_add_u32 m0, s56, 0xa400
	s_nop 0
	global_load_lds_dwordx4 v239, s[26:27]
	s_add_u32 s24, s24, 64
	s_addc_u32 s25, s25, 0
	s_add_u32 s26, s26, 64
	s_addc_u32 s27, s27, 0
	v_mfma_f32_16x16x32_bf16 v[0:3], v[184:187], v[168:171], v[0:3]
	ds_read_b128 v[200:203], v242 offset:49152
	v_mfma_f32_16x16x32_bf16 v[4:7], v[188:191], v[168:171], v[4:7]
	ds_read_b128 v[216:219], v243 offset:49152
	v_mfma_f32_16x16x32_bf16 v[8:11], v[192:195], v[168:171], v[8:11]
	ds_read_b128 v[204:207], v242 offset:50176
	v_mfma_f32_16x16x32_bf16 v[12:15], v[196:199], v[168:171], v[12:15]
	ds_read_b128 v[220:223], v243 offset:49408
	v_mfma_f32_16x16x32_bf16 v[16:19], v[184:187], v[172:175], v[16:19]
	ds_read_b128 v[208:211], v242 offset:51200
	v_mfma_f32_16x16x32_bf16 v[20:23], v[188:191], v[172:175], v[20:23]
	ds_read_b128 v[228:231], v243 offset:49664
	v_mfma_f32_16x16x32_bf16 v[24:27], v[192:195], v[172:175], v[24:27]
	ds_read_b128 v[212:215], v242 offset:52224
	v_mfma_f32_16x16x32_bf16 v[28:31], v[196:199], v[172:175], v[28:31]
	ds_read_b128 v[232:235], v243 offset:49920
	v_mfma_f32_16x16x32_bf16 v[32:35], v[184:187], v[176:179], v[32:35]
	v_mfma_f32_16x16x32_bf16 v[36:39], v[188:191], v[176:179], v[36:39]
	v_mfma_f32_16x16x32_bf16 v[40:43], v[192:195], v[176:179], v[40:43]
	v_mfma_f32_16x16x32_bf16 v[44:47], v[196:199], v[176:179], v[44:47]
	v_mfma_f32_16x16x32_bf16 v[48:51], v[184:187], v[180:183], v[48:51]
	v_mfma_f32_16x16x32_bf16 v[52:55], v[188:191], v[180:183], v[52:55]
	v_mfma_f32_16x16x32_bf16 v[56:59], v[192:195], v[180:183], v[56:59]
	v_mfma_f32_16x16x32_bf16 v[60:63], v[196:199], v[180:183], v[60:63]
	s_waitcnt vmcnt(8) lgkmcnt(0)
	s_barrier
	s_add_u32 m0, s56, 0xc000
	s_nop 0
	global_load_lds_dwordx4 v236, s[24:25]
	s_add_u32 m0, s56, 0xc400
	s_nop 0
	global_load_lds_dwordx4 v237, s[24:25]
	s_add_u32 m0, s56, 0xe000
	s_nop 0
	global_load_lds_dwordx4 v238, s[26:27]
	s_add_u32 m0, s56, 0xe400
	s_nop 0
	global_load_lds_dwordx4 v239, s[26:27]
	s_add_u32 s24, s24, 64
	s_addc_u32 s25, s25, 0
	s_add_u32 s26, s26, 64
	s_addc_u32 s27, s27, 0
	v_mfma_f32_16x16x32_bf16 v[0:3], v[216:219], v[200:203], v[0:3]
	ds_read_b128 v[168:171], v242 offset:0
	v_mfma_f32_16x16x32_bf16 v[4:7], v[220:223], v[200:203], v[4:7]
	ds_read_b128 v[184:187], v243 offset:0
	v_mfma_f32_16x16x32_bf16 v[8:11], v[228:231], v[200:203], v[8:11]
	ds_read_b128 v[172:175], v242 offset:1024
	v_mfma_f32_16x16x32_bf16 v[12:15], v[232:235], v[200:203], v[12:15]
	ds_read_b128 v[188:191], v243 offset:256
	v_mfma_f32_16x16x32_bf16 v[16:19], v[216:219], v[204:207], v[16:19]
	ds_read_b128 v[176:179], v242 offset:2048
	v_mfma_f32_16x16x32_bf16 v[20:23], v[220:223], v[204:207], v[20:23]
	ds_read_b128 v[192:195], v243 offset:512
	v_mfma_f32_16x16x32_bf16 v[24:27], v[228:231], v[204:207], v[24:27]
	ds_read_b128 v[180:183], v242 offset:3072
	v_mfma_f32_16x16x32_bf16 v[28:31], v[232:235], v[204:207], v[28:31]
	ds_read_b128 v[196:199], v243 offset:768
	v_mfma_f32_16x16x32_bf16 v[32:35], v[216:219], v[208:211], v[32:35]
	v_mfma_f32_16x16x32_bf16 v[36:39], v[220:223], v[208:211], v[36:39]
	v_mfma_f32_16x16x32_bf16 v[40:43], v[228:231], v[208:211], v[40:43]
	v_mfma_f32_16x16x32_bf16 v[44:47], v[232:235], v[208:211], v[44:47]
	v_mfma_f32_16x16x32_bf16 v[48:51], v[216:219], v[212:215], v[48:51]
	v_mfma_f32_16x16x32_bf16 v[52:55], v[220:223], v[212:215], v[52:55]
	v_mfma_f32_16x16x32_bf16 v[56:59], v[228:231], v[212:215], v[56:59]
	v_mfma_f32_16x16x32_bf16 v[60:63], v[232:235], v[212:215], v[60:63]
	s_nop 15
	s_nop 7
	v_mul_f32_e32 v200, 0xbfb8aa3b, v0
	v_mul_f32_e32 v201, 0xbfb8aa3b, v1
	v_mul_f32_e32 v202, 0xbfb8aa3b, v2
	v_mul_f32_e32 v203, 0xbfb8aa3b, v3
	v_mul_f32_e32 v204, 0xbfb8aa3b, v4
	v_mul_f32_e32 v205, 0xbfb8aa3b, v5
	v_mul_f32_e32 v206, 0xbfb8aa3b, v6
	v_mul_f32_e32 v207, 0xbfb8aa3b, v7
	v_exp_f32_e32 v200, v200
	v_exp_f32_e32 v201, v201
	v_exp_f32_e32 v202, v202
	v_exp_f32_e32 v203, v203
	v_exp_f32_e32 v204, v204
	v_exp_f32_e32 v205, v205
	v_exp_f32_e32 v206, v206
	v_exp_f32_e32 v207, v207
	v_add_f32_e32 v200, 1.0, v200
	v_add_f32_e32 v201, 1.0, v201
	v_add_f32_e32 v202, 1.0, v202
	v_add_f32_e32 v203, 1.0, v203
	v_add_f32_e32 v204, 1.0, v204
	v_add_f32_e32 v205, 1.0, v205
	v_add_f32_e32 v206, 1.0, v206
	v_add_f32_e32 v207, 1.0, v207
	v_rcp_f32_e32 v200, v200
	v_rcp_f32_e32 v201, v201
	v_rcp_f32_e32 v202, v202
	v_rcp_f32_e32 v203, v203
	v_rcp_f32_e32 v204, v204
	v_rcp_f32_e32 v205, v205
	v_rcp_f32_e32 v206, v206
	v_rcp_f32_e32 v207, v207
	v_lshlrev_b32_e32 v208, 16, v128
	v_and_b32_e32 v209, 0xffff0000, v128
	v_lshlrev_b32_e32 v210, 16, v129
	v_and_b32_e32 v211, 0xffff0000, v129
	v_lshlrev_b32_e32 v212, 16, v130
	v_and_b32_e32 v213, 0xffff0000, v130
	v_lshlrev_b32_e32 v214, 16, v131
	v_and_b32_e32 v215, 0xffff0000, v131
	v_fmac_f32_e32 v64, v200, v208
	v_fmac_f32_e32 v65, v201, v209
	v_fmac_f32_e32 v66, v202, v210
	v_fmac_f32_e32 v67, v203, v211
	v_fmac_f32_e32 v68, v204, v212
	v_fmac_f32_e32 v69, v205, v213
	v_fmac_f32_e32 v70, v206, v214
	v_fmac_f32_e32 v71, v207, v215
	v_mul_f32_e32 v200, 0xbfb8aa3b, v8
	v_mul_f32_e32 v201, 0xbfb8aa3b, v9
	v_mul_f32_e32 v202, 0xbfb8aa3b, v10
	v_mul_f32_e32 v203, 0xbfb8aa3b, v11
	v_mul_f32_e32 v204, 0xbfb8aa3b, v12
	v_mul_f32_e32 v205, 0xbfb8aa3b, v13
	v_mul_f32_e32 v206, 0xbfb8aa3b, v14
	v_mul_f32_e32 v207, 0xbfb8aa3b, v15
	v_exp_f32_e32 v200, v200
	v_exp_f32_e32 v201, v201
	v_exp_f32_e32 v202, v202
	v_exp_f32_e32 v203, v203
; __device__ __forceinline__ float sigmoidf_(float v) { return 1.f / (1.f + __expf(-v)); }
; __device__ void phase_merge4(CParams& p, int l, int tm, int tn, char* smem) {
;     ...
; #pragma unroll
;     for (int mi = 0; mi < 4; mi++)
; #pragma unroll
;       for (int ni = 0; ni < 4; ni++) {
;         unsigned p0 = pk[mi][ni][0], p1 = pk[mi][ni][1], m0 = mer[mi][ni][0], m1 = mer[mi][ni][1];
;         float r0 = __uint_as_float(m0 << 16) + sigmoidf_(acc[mi][ni][0]) * __uint_as_float(p0 << 16);
;         float r1 = __uint_as_float(m0 & 0xffff0000u) + sigmoidf_(acc[mi][ni][1]) * __uint_as_float(p0 & 0xffff0000u);
;         float r2 = __uint_as_float(m1 << 16) + sigmoidf_(acc[mi][ni][2]) * __uint_as_float(p1 << 16);
;         float r3 = __uint_as_float(m1 & 0xffff0000u) + sigmoidf_(acc[mi][ni][3]) * __uint_as_float(p1 & 0xffff0000u);
	v_exp_f32_e32 v204, v204
	v_exp_f32_e32 v205, v205
	v_exp_f32_e32 v206, v206
	v_exp_f32_e32 v207, v207
	v_add_f32_e32 v200, 1.0, v200
	v_add_f32_e32 v201, 1.0, v201
	v_add_f32_e32 v202, 1.0, v202
	v_add_f32_e32 v203, 1.0, v203
	v_add_f32_e32 v204, 1.0, v204
	v_add_f32_e32 v205, 1.0, v205
	v_add_f32_e32 v206, 1.0, v206
	v_add_f32_e32 v207, 1.0, v207
	v_rcp_f32_e32 v200, v200
	v_rcp_f32_e32 v201, v201
	v_rcp_f32_e32 v202, v202
	v_rcp_f32_e32 v203, v203
	v_rcp_f32_e32 v204, v204
	v_rcp_f32_e32 v205, v205
	v_rcp_f32_e32 v206, v206
	v_rcp_f32_e32 v207, v207
	v_lshlrev_b32_e32 v208, 16, v132
	v_and_b32_e32 v209, 0xffff0000, v132
	v_lshlrev_b32_e32 v210, 16, v133
	v_and_b32_e32 v211, 0xffff0000, v133
	v_lshlrev_b32_e32 v212, 16, v134
	v_and_b32_e32 v213, 0xffff0000, v134
	v_lshlrev_b32_e32 v214, 16, v135
	v_and_b32_e32 v215, 0xffff0000, v135
	v_fmac_f32_e32 v72, v200, v208
	v_fmac_f32_e32 v73, v201, v209
	v_fmac_f32_e32 v74, v202, v210
	v_fmac_f32_e32 v75, v203, v211
	v_fmac_f32_e32 v76, v204, v212
	v_fmac_f32_e32 v77, v205, v213
	v_fmac_f32_e32 v78, v206, v214
	v_fmac_f32_e32 v79, v207, v215
	v_mul_f32_e32 v200, 0xbfb8aa3b, v16
	v_mul_f32_e32 v201, 0xbfb8aa3b, v17
	v_mul_f32_e32 v202, 0xbfb8aa3b, v18
	v_mul_f32_e32 v203, 0xbfb8aa3b, v19
	v_mul_f32_e32 v204, 0xbfb8aa3b, v20
	v_mul_f32_e32 v205, 0xbfb8aa3b, v21
	v_mul_f32_e32 v206, 0xbfb8aa3b, v22
	v_mul_f32_e32 v207, 0xbfb8aa3b, v23
	v_exp_f32_e32 v200, v200
	v_exp_f32_e32 v201, v201
	v_exp_f32_e32 v202, v202
	v_exp_f32_e32 v203, v203
	v_exp_f32_e32 v204, v204
	v_exp_f32_e32 v205, v205
	v_exp_f32_e32 v206, v206
	v_exp_f32_e32 v207, v207
	v_add_f32_e32 v200, 1.0, v200
	v_add_f32_e32 v201, 1.0, v201
	v_add_f32_e32 v202, 1.0, v202
	v_add_f32_e32 v203, 1.0, v203
	v_add_f32_e32 v204, 1.0, v204
	v_add_f32_e32 v205, 1.0, v205
	v_add_f32_e32 v206, 1.0, v206
	v_add_f32_e32 v207, 1.0, v207
	v_rcp_f32_e32 v200, v200
	v_rcp_f32_e32 v201, v201
	v_rcp_f32_e32 v202, v202
	v_rcp_f32_e32 v203, v203
	v_rcp_f32_e32 v204, v204
	v_rcp_f32_e32 v205, v205
	v_rcp_f32_e32 v206, v206
	v_rcp_f32_e32 v207, v207
	v_lshlrev_b32_e32 v208, 16, v136
	v_and_b32_e32 v209, 0xffff0000, v136
	v_lshlrev_b32_e32 v210, 16, v137
	v_and_b32_e32 v211, 0xffff0000, v137
	v_lshlrev_b32_e32 v212, 16, v138
	v_and_b32_e32 v213, 0xffff0000, v138
	v_lshlrev_b32_e32 v214, 16, v139
	v_and_b32_e32 v215, 0xffff0000, v139
	v_fmac_f32_e32 v80, v200, v208
	v_fmac_f32_e32 v81, v201, v209
	v_fmac_f32_e32 v82, v202, v210
	v_fmac_f32_e32 v83, v203, v211
	v_fmac_f32_e32 v84, v204, v212
	v_fmac_f32_e32 v85, v205, v213
	v_fmac_f32_e32 v86, v206, v214
	v_fmac_f32_e32 v87, v207, v215
	v_mul_f32_e32 v200, 0xbfb8aa3b, v24
	v_mul_f32_e32 v201, 0xbfb8aa3b, v25
	v_mul_f32_e32 v202, 0xbfb8aa3b, v26
	v_mul_f32_e32 v203, 0xbfb8aa3b, v27
	v_mul_f32_e32 v204, 0xbfb8aa3b, v28
	v_mul_f32_e32 v205, 0xbfb8aa3b, v29
	v_mul_f32_e32 v206, 0xbfb8aa3b, v30
	v_mul_f32_e32 v207, 0xbfb8aa3b, v31
	v_exp_f32_e32 v200, v200
	v_exp_f32_e32 v201, v201
	v_exp_f32_e32 v202, v202
	v_exp_f32_e32 v203, v203
	v_exp_f32_e32 v204, v204
	v_exp_f32_e32 v205, v205
	v_exp_f32_e32 v206, v206
	v_exp_f32_e32 v207, v207
	v_add_f32_e32 v200, 1.0, v200
	v_add_f32_e32 v201, 1.0, v201
	v_add_f32_e32 v202, 1.0, v202
	v_add_f32_e32 v203, 1.0, v203
	v_add_f32_e32 v204, 1.0, v204
	v_add_f32_e32 v205, 1.0, v205
	v_add_f32_e32 v206, 1.0, v206
	v_add_f32_e32 v207, 1.0, v207
	v_rcp_f32_e32 v200, v200
	v_rcp_f32_e32 v201, v201
	v_rcp_f32_e32 v202, v202
	v_rcp_f32_e32 v203, v203
	v_rcp_f32_e32 v204, v204
	v_rcp_f32_e32 v205, v205
	v_rcp_f32_e32 v206, v206
	v_rcp_f32_e32 v207, v207
	v_lshlrev_b32_e32 v208, 16, v140
	v_and_b32_e32 v209, 0xffff0000, v140
	v_lshlrev_b32_e32 v210, 16, v141
	v_and_b32_e32 v211, 0xffff0000, v141
	v_lshlrev_b32_e32 v212, 16, v142
	v_and_b32_e32 v213, 0xffff0000, v142
	v_lshlrev_b32_e32 v214, 16, v143
	v_and_b32_e32 v215, 0xffff0000, v143
	v_fmac_f32_e32 v88, v200, v208
	v_fmac_f32_e32 v89, v201, v209
	v_fmac_f32_e32 v90, v202, v210
	v_fmac_f32_e32 v91, v203, v211
	v_fmac_f32_e32 v92, v204, v212
	v_fmac_f32_e32 v93, v205, v213
	v_fmac_f32_e32 v94, v206, v214
	v_fmac_f32_e32 v95, v207, v215
	v_mul_f32_e32 v200, 0xbfb8aa3b, v32
	v_mul_f32_e32 v201, 0xbfb8aa3b, v33
	v_mul_f32_e32 v202, 0xbfb8aa3b, v34
	v_mul_f32_e32 v203, 0xbfb8aa3b, v35
	v_mul_f32_e32 v204, 0xbfb8aa3b, v36
	v_mul_f32_e32 v205, 0xbfb8aa3b, v37
	v_mul_f32_e32 v206, 0xbfb8aa3b, v38
	v_mul_f32_e32 v207, 0xbfb8aa3b, v39
	v_exp_f32_e32 v200, v200
	v_exp_f32_e32 v201, v201
	v_exp_f32_e32 v202, v202
	v_exp_f32_e32 v203, v203
	v_exp_f32_e32 v204, v204
	v_exp_f32_e32 v205, v205
	v_exp_f32_e32 v206, v206
	v_exp_f32_e32 v207, v207
	v_add_f32_e32 v200, 1.0, v200
	v_add_f32_e32 v201, 1.0, v201
	v_add_f32_e32 v202, 1.0, v202
	v_add_f32_e32 v203, 1.0, v203
	v_add_f32_e32 v204, 1.0, v204
	v_add_f32_e32 v205, 1.0, v205
	v_add_f32_e32 v206, 1.0, v206
	v_add_f32_e32 v207, 1.0, v207
	v_rcp_f32_e32 v200, v200
	v_rcp_f32_e32 v201, v201
	v_rcp_f32_e32 v202, v202
	v_rcp_f32_e32 v203, v203
	v_rcp_f32_e32 v204, v204
	v_rcp_f32_e32 v205, v205
	v_rcp_f32_e32 v206, v206
	v_rcp_f32_e32 v207, v207
	v_lshlrev_b32_e32 v208, 16, v148
	v_and_b32_e32 v209, 0xffff0000, v148
	v_lshlrev_b32_e32 v210, 16, v149
	v_and_b32_e32 v211, 0xffff0000, v149
	v_lshlrev_b32_e32 v212, 16, v150
	v_and_b32_e32 v213, 0xffff0000, v150
	v_lshlrev_b32_e32 v214, 16, v151
	v_and_b32_e32 v215, 0xffff0000, v151
	v_fmac_f32_e32 v96, v200, v208
	v_fmac_f32_e32 v97, v201, v209
	v_fmac_f32_e32 v98, v202, v210
	v_fmac_f32_e32 v99, v203, v211
	v_fmac_f32_e32 v100, v204, v212
	v_fmac_f32_e32 v101, v205, v213
	v_fmac_f32_e32 v102, v206, v214
	v_fmac_f32_e32 v103, v207, v215
	v_mul_f32_e32 v200, 0xbfb8aa3b, v40
; __device__ __forceinline__ float sigmoidf_(float v) { return 1.f / (1.f + __expf(-v)); }
; template <int NI>
; __device__ void phase_merge(CParams& p, int l, int tm, int tn, char* smem) {
;     ...
;     for (int mi = 0; mi < 4; mi++)
; #pragma unroll
;       for (int ni = 0; ni < NI; ni++) {
;         unsigned p0 = pk[mi][ni][0], p1 = pk[mi][ni][1];
;         mer[mi][ni][0] += sigmoidf_(acc[mi][ni][0]) * __uint_as_float(p0 << 16);
;         mer[mi][ni][1] += sigmoidf_(acc[mi][ni][1]) * __uint_as_float(p0 & 0xffff0000u);
;         mer[mi][ni][2] += sigmoidf_(acc[mi][ni][2]) * __uint_as_float(p1 << 16);
;         mer[mi][ni][3] += sigmoidf_(acc[mi][ni][3]) * __uint_as_float(p1 & 0xffff0000u);
;       }
;   }
;   {
;     const int lane = tid & 63, wid = tid >> 6, wr = wid >> 1, wc = wid & 1;
; #pragma unroll
;     for (int mi = 0; mi < 4; mi++)
; #pragma unroll
;       for (int ni = 0; ni < NI; ni++)
; #pragma unroll
;         for (int j = 0; j < 4; j++) {
;           int rl = wr * 64 + mi * 16 + (lane >> 4) * 4 + j;
;           int cl = wc * (16 * NI) + ni * 16 + (lane & 15);
;           p.merged[(size_t)(row0 + rl) * 1024 + col0 + cl] = f2bf(mer[mi][ni][j]);
;         }
	v_mul_f32_e32 v201, 0xbfb8aa3b, v41
	v_mul_f32_e32 v202, 0xbfb8aa3b, v42
	v_mul_f32_e32 v203, 0xbfb8aa3b, v43
	v_mul_f32_e32 v204, 0xbfb8aa3b, v44
	v_mul_f32_e32 v205, 0xbfb8aa3b, v45
	v_mul_f32_e32 v206, 0xbfb8aa3b, v46
	v_mul_f32_e32 v207, 0xbfb8aa3b, v47
	v_exp_f32_e32 v200, v200
	v_exp_f32_e32 v201, v201
	v_exp_f32_e32 v202, v202
	v_exp_f32_e32 v203, v203
	v_exp_f32_e32 v204, v204
	v_exp_f32_e32 v205, v205
	v_exp_f32_e32 v206, v206
	v_exp_f32_e32 v207, v207
	v_add_f32_e32 v200, 1.0, v200
	v_add_f32_e32 v201, 1.0, v201
	v_add_f32_e32 v202, 1.0, v202
	v_add_f32_e32 v203, 1.0, v203
	v_add_f32_e32 v204, 1.0, v204
	v_add_f32_e32 v205, 1.0, v205
	v_add_f32_e32 v206, 1.0, v206
	v_add_f32_e32 v207, 1.0, v207
	v_rcp_f32_e32 v200, v200
	v_rcp_f32_e32 v201, v201
	v_rcp_f32_e32 v202, v202
	v_rcp_f32_e32 v203, v203
	v_rcp_f32_e32 v204, v204
	v_rcp_f32_e32 v205, v205
	v_rcp_f32_e32 v206, v206
	v_rcp_f32_e32 v207, v207
	v_lshlrev_b32_e32 v208, 16, v152
	v_and_b32_e32 v209, 0xffff0000, v152
	v_lshlrev_b32_e32 v210, 16, v153
	v_and_b32_e32 v211, 0xffff0000, v153
	v_lshlrev_b32_e32 v212, 16, v154
	v_and_b32_e32 v213, 0xffff0000, v154
	v_lshlrev_b32_e32 v214, 16, v155
	v_and_b32_e32 v215, 0xffff0000, v155
	v_fmac_f32_e32 v104, v200, v208
	v_fmac_f32_e32 v105, v201, v209
	v_fmac_f32_e32 v106, v202, v210
	v_fmac_f32_e32 v107, v203, v211
	v_fmac_f32_e32 v108, v204, v212
	v_fmac_f32_e32 v109, v205, v213
	v_fmac_f32_e32 v110, v206, v214
	v_fmac_f32_e32 v111, v207, v215
	v_mul_f32_e32 v200, 0xbfb8aa3b, v48
	v_mul_f32_e32 v201, 0xbfb8aa3b, v49
	v_mul_f32_e32 v202, 0xbfb8aa3b, v50
	v_mul_f32_e32 v203, 0xbfb8aa3b, v51
	v_mul_f32_e32 v204, 0xbfb8aa3b, v52
	v_mul_f32_e32 v205, 0xbfb8aa3b, v53
	v_mul_f32_e32 v206, 0xbfb8aa3b, v54
	v_mul_f32_e32 v207, 0xbfb8aa3b, v55
	v_exp_f32_e32 v200, v200
	v_exp_f32_e32 v201, v201
	v_exp_f32_e32 v202, v202
	v_exp_f32_e32 v203, v203
	v_exp_f32_e32 v204, v204
	v_exp_f32_e32 v205, v205
	v_exp_f32_e32 v206, v206
	v_exp_f32_e32 v207, v207
	v_add_f32_e32 v200, 1.0, v200
	v_add_f32_e32 v201, 1.0, v201
	v_add_f32_e32 v202, 1.0, v202
	v_add_f32_e32 v203, 1.0, v203
	v_add_f32_e32 v204, 1.0, v204
	v_add_f32_e32 v205, 1.0, v205
	v_add_f32_e32 v206, 1.0, v206
	v_add_f32_e32 v207, 1.0, v207
	v_rcp_f32_e32 v200, v200
	v_rcp_f32_e32 v201, v201
	v_rcp_f32_e32 v202, v202
	v_rcp_f32_e32 v203, v203
	v_rcp_f32_e32 v204, v204
	v_rcp_f32_e32 v205, v205
	v_rcp_f32_e32 v206, v206
	v_rcp_f32_e32 v207, v207
	v_lshlrev_b32_e32 v208, 16, v156
	v_and_b32_e32 v209, 0xffff0000, v156
	v_lshlrev_b32_e32 v210, 16, v157
	v_and_b32_e32 v211, 0xffff0000, v157
	v_lshlrev_b32_e32 v212, 16, v158
	v_and_b32_e32 v213, 0xffff0000, v158
	v_lshlrev_b32_e32 v214, 16, v159
	v_and_b32_e32 v215, 0xffff0000, v159
	v_fmac_f32_e32 v112, v200, v208
	v_fmac_f32_e32 v113, v201, v209
	v_fmac_f32_e32 v114, v202, v210
	v_fmac_f32_e32 v115, v203, v211
	v_fmac_f32_e32 v116, v204, v212
	v_fmac_f32_e32 v117, v205, v213
	v_fmac_f32_e32 v118, v206, v214
	v_fmac_f32_e32 v119, v207, v215
	v_mul_f32_e32 v200, 0xbfb8aa3b, v56
	v_mul_f32_e32 v201, 0xbfb8aa3b, v57
	v_mul_f32_e32 v202, 0xbfb8aa3b, v58
	v_mul_f32_e32 v203, 0xbfb8aa3b, v59
	v_mul_f32_e32 v204, 0xbfb8aa3b, v60
	v_mul_f32_e32 v205, 0xbfb8aa3b, v61
	v_mul_f32_e32 v206, 0xbfb8aa3b, v62
	v_mul_f32_e32 v207, 0xbfb8aa3b, v63
	v_exp_f32_e32 v200, v200
	v_exp_f32_e32 v201, v201
	v_exp_f32_e32 v202, v202
	v_exp_f32_e32 v203, v203
	v_exp_f32_e32 v204, v204
	v_exp_f32_e32 v205, v205
	v_exp_f32_e32 v206, v206
	v_exp_f32_e32 v207, v207
	v_add_f32_e32 v200, 1.0, v200
	v_add_f32_e32 v201, 1.0, v201
	v_add_f32_e32 v202, 1.0, v202
	v_add_f32_e32 v203, 1.0, v203
	v_add_f32_e32 v204, 1.0, v204
	v_add_f32_e32 v205, 1.0, v205
	v_add_f32_e32 v206, 1.0, v206
	v_add_f32_e32 v207, 1.0, v207
	v_rcp_f32_e32 v200, v200
	v_rcp_f32_e32 v201, v201
	v_rcp_f32_e32 v202, v202
	v_rcp_f32_e32 v203, v203
	v_rcp_f32_e32 v204, v204
	v_rcp_f32_e32 v205, v205
	v_rcp_f32_e32 v206, v206
	v_rcp_f32_e32 v207, v207
	v_lshlrev_b32_e32 v208, 16, v160
	v_and_b32_e32 v209, 0xffff0000, v160
	v_lshlrev_b32_e32 v210, 16, v161
	v_and_b32_e32 v211, 0xffff0000, v161
	v_lshlrev_b32_e32 v212, 16, v162
	v_and_b32_e32 v213, 0xffff0000, v162
	v_lshlrev_b32_e32 v214, 16, v163
	v_and_b32_e32 v215, 0xffff0000, v163
	v_fmac_f32_e32 v120, v200, v208
	v_fmac_f32_e32 v121, v201, v209
	v_fmac_f32_e32 v122, v202, v210
	v_fmac_f32_e32 v123, v203, v211
	v_fmac_f32_e32 v124, v204, v212
	v_fmac_f32_e32 v125, v205, v213
	v_fmac_f32_e32 v126, v206, v214
	v_fmac_f32_e32 v127, v207, v215
	s_and_b32 s63, s22, 3
	s_cmp_lg_u32 s63, 3
	s_cbranch_scc1 .Lmg4_nostore
	s_lshl_b32 s62, s23, 11
	s_lshl_b32 s92, s21, 1
	s_add_u32 s62, s62, s92
	s_add_u32 s58, s8, s62
	s_addc_u32 s59, s9, 0
	v_cvt_pk_bf16_f32 v200, v64, v65
	v_cvt_pk_bf16_f32 v201, v66, v67
	v_cvt_pk_bf16_f32 v202, v68, v69
	v_cvt_pk_bf16_f32 v203, v70, v71
	global_store_dwordx4 v244, v[200:203], s[58:59] offset:0
	v_cvt_pk_bf16_f32 v204, v72, v73
	v_cvt_pk_bf16_f32 v205, v74, v75
	v_cvt_pk_bf16_f32 v206, v76, v77
	v_cvt_pk_bf16_f32 v207, v78, v79
	global_store_dwordx4 v244, v[204:207], s[58:59] offset:16
	s_add_u32 s58, s58, 0x8000
	s_addc_u32 s59, s59, 0
	v_cvt_pk_bf16_f32 v208, v80, v81
	v_cvt_pk_bf16_f32 v209, v82, v83
	v_cvt_pk_bf16_f32 v210, v84, v85
	v_cvt_pk_bf16_f32 v211, v86, v87
	global_store_dwordx4 v244, v[208:211], s[58:59] offset:0
	v_cvt_pk_bf16_f32 v212, v88, v89
	v_cvt_pk_bf16_f32 v213, v90, v91
	v_cvt_pk_bf16_f32 v214, v92, v93
	v_cvt_pk_bf16_f32 v215, v94, v95
	global_store_dwordx4 v244, v[212:215], s[58:59] offset:16
	s_add_u32 s58, s58, 0x8000
	s_addc_u32 s59, s59, 0
	v_cvt_pk_bf16_f32 v216, v96, v97
	v_cvt_pk_bf16_f32 v217, v98, v99
	v_cvt_pk_bf16_f32 v218, v100, v101
	v_cvt_pk_bf16_f32 v219, v102, v103
	global_store_dwordx4 v244, v[216:219], s[58:59] offset:0
	v_cvt_pk_bf16_f32 v220, v104, v105
	v_cvt_pk_bf16_f32 v221, v106, v107
	v_cvt_pk_bf16_f32 v222, v108, v109
	v_cvt_pk_bf16_f32 v223, v110, v111
	global_store_dwordx4 v244, v[220:223], s[58:59] offset:16
	s_add_u32 s58, s58, 0x8000
	s_addc_u32 s59, s59, 0
	v_cvt_pk_bf16_f32 v228, v112, v113
	v_cvt_pk_bf16_f32 v229, v114, v115
	v_cvt_pk_bf16_f32 v230, v116, v117
	v_cvt_pk_bf16_f32 v231, v118, v119
	global_store_dwordx4 v244, v[228:231], s[58:59] offset:0
	v_cvt_pk_bf16_f32 v232, v120, v121
	v_cvt_pk_bf16_f32 v233, v122, v123
	v_cvt_pk_bf16_f32 v234, v124, v125
	v_cvt_pk_bf16_f32 v235, v126, v127
	global_store_dwordx4 v244, v[232:235], s[58:59] offset:16
	s_waitcnt vmcnt(0)

; __device__ __forceinline__ int otid() { int t = threadIdx.x; asm volatile("" : "+v"(t)); return t; }
; template <int NI> ...
;     ...
;   const int lane = tid & 63, wid = tid >> 6, wr = wid >> 1, wc = wid & 1;
;   const int lrow = tid >> 2, lch = (tid & 3) * 8;
;   const int l15 = lane & 15, lq = lane >> 4;
;   const bf16_t* pa = A + (size_t)lrow * lda + lch;
;   const bf16_t* pb = B + (size_t)lrow * ldb + lch;
;   const size_t a64 = (size_t)64 * lda, b64 = (size_t)64 * ldb;
;   u32x4 a0[2], a1[2], b0[NB], b1[NB];
;   const int nk = K >> 5;
;   const int klast = K - 32;
;   const int wofs = lrow * GROW + lch;
;   const int raofs = (wr * 64 + l15) * GROW + lq * 8;
;   const int rbofs = 128 * GROW + (wc * (16 * NI) + l15) * GROW + lq * 8;
; __device__ void phase_proj_res(CParams& p, int l, int tm, int tn, char* smem, const bf16_t* A, int K,
;                                const bf16_t* Bt, int gate_off, float gscale) {
;   const int tid = otid();
;   bf16_t* sA = (bf16_t*)smem;
;   bf16_t* sB = sA + 128 * LDSS;
;   int row0 = tm * 128, col0 = tn * 128;
;   f32x4 acc[4][4];
;   zero_acc<4>(acc);
;   gemm_mainloop<4>(A + (size_t)row0 * K, K, Bt + (size_t)col0 * K, K, K, sA, sB, acc, tid);
;   const float* md = p.mod + ((size_t)l * 3 + modvec_of_tok(row0)) * 6144 + gate_off;
.LBB0_946:
	s_or_b64 exec, exec, s[22:23]
	s_mov_b64 s[42:43], s[34:35]
	s_waitcnt lgkmcnt(0)
	s_barrier
	s_lshl_b64 s[6:7], s[0:1], 21
	s_load_dwordx2 s[8:9], s[42:43], 0x118
	s_load_dwordx2 s[22:23], s[42:43], 0x1d8
	s_load_dwordx2 s[24:25], s[42:43], 0x160
	s_load_dwordx2 s[44:45], s[42:43], 0x148
	s_load_dwordx2 s[48:49], s[42:43], 0xf8
	s_waitcnt lgkmcnt(0)
	s_add_u32 s2, s8, s6
	s_addc_u32 s4, s9, s7
	v_readlane_b32 s6, v225, 63
	v_readlane_b32 s7, v224, 0
	s_add_u32 s50, s2, s6
	s_addc_u32 s51, s4, s7
	s_mov_b32 s2, 0
	s_mov_b64 exec, -1
	ds_read_b128 v[236:239], v145 offset:40960
	s_load_dwordx2 s[0:1], s[34:35], 0x1d8
	s_load_dwordx2 s[6:7], s[34:35], 0x118
	s_load_dwordx2 s[18:19], s[34:35], 0xf8
	s_load_dwordx2 s[22:23], s[34:35], 0x160
	v_readlane_b32 s2, v224, 26
	v_readlane_b32 s4, v225, 4
	v_readfirstlane_b32 s32, v147
	v_and_b32_e32 v250, 63, v147
	s_nop 3
	s_lshr_b32 s32, s32, 6
	s_lshl_b32 s24, s32, 11
	s_lshl_b32 s25, s32, 12
	v_lshrrev_b32_e32 v251, 2, v250
	v_and_b32_e32 v252, 3, v250
	v_lshrrev_b32_e32 v253, 4, v250
	v_sub_u32_e32 v253, 0, v253
	v_and_b32_e32 v253, 3, v253
	v_xor_b32_e32 v253, v252, v253
	v_lshlrev_b32_e32 v253, 4, v253
	s_lshl_b32 s29, s32, 5
	v_add_u32_e32 v252, s29, v251
	s_mov_b32 s44, 0x800
	v_mul_lo_u32 v240, v252, s44
	v_add_u32_e32 v240, v240, v253
	v_add_u32_e32 v241, 0x8000, v240
	s_lshl_b32 s29, s32, 6
	v_add_u32_e32 v252, s29, v251
	s_mov_b32 s44, 0x800
	v_mul_lo_u32 v242, v252, s44
	v_add_u32_e32 v242, v242, v253
	v_add_u32_e32 v243, 0x8000, v242
	v_add_u32_e32 v244, 0x10000, v242
	v_add_u32_e32 v245, 0x18000, v242
	v_and_b32_e32 v251, 15, v250
	v_lshrrev_b32_e32 v252, 2, v251
	v_sub_u32_e32 v252, 0, v252
	v_and_b32_e32 v252, 3, v252
	v_lshrrev_b32_e32 v253, 4, v250
	v_xor_b32_e32 v252, v253, v252
	v_lshlrev_b32_e32 v252, 4, v252
	s_lshr_b32 s29, s32, 1
	s_and_b32 s44, s32, 1
	s_lshl_b32 s45, s29, 6
	s_lshl_b32 s50, s44, 7
	v_add_u32_e32 v246, s45, v251
	v_lshl_add_u32 v246, v246, 6, v252
	v_add_u32_e32 v247, s50, v251
	v_lshl_add_u32 v247, v247, 6, v252
	v_add_u32_e32 v247, 0x2000, v247
	v_lshl_add_u32 v249, v253, 2, s50
	v_lshlrev_b32_e32 v249, 2, v249
	v_add_u32_e32 v248, s45, v251
	v_lshl_add_u32 v248, v248, 12, v249
	s_waitcnt lgkmcnt(0)
	s_mov_b32 s51, 0
	s_and_b32 s29, s4, 7
	s_lshl_b32 s29, s29, 4
	s_lshr_b32 s44, s4, 5
	s_add_u32 s29, s29, s44
	s_lshl_b32 s26, s29, 7
	s_lshr_b32 s44, s4, 3
	s_and_b32 s44, s44, 3
	s_lshl_b32 s27, s44, 8
	s_mul_i32 s29, s26, 0x800
	s_add_u32 s8, s0, s29
	s_addc_u32 s9, s1, 0
	s_mul_i32 s29, s2, 0x200000
	s_mul_i32 s44, s27, 0x800
	s_add_u32 s29, s29, s44
	s_add_u32 s12, s6, s29
	s_addc_u32 s13, s7, 0
	s_barrier
; template <int NI> ...
;     ...
;   G_LOAD(a0, b0, 0);
;   G_LOAD(a1, b1, 32);
;   __syncthreads();
;   G_WRITE(a0, b0, 0);
;   __syncthreads();
; template <int NI>
; __device__ __forceinline__ void zero_acc(f32x4 (&acc)[4][NI]) {
; #pragma unroll
;   for (int a = 0; a < 4; a++)
; #pragma unroll
;     for (int b = 0; b < NI; b++) acc[a][b] = f32x4{0.f, 0.f, 0.f, 0.f};
	s_add_u32 m0, s24, 0x0
	s_nop 0
	global_load_lds_dwordx4 v240, s[8:9]
	s_add_u32 m0, s24, 0x400
	s_nop 0
	global_load_lds_dwordx4 v241, s[8:9]
	s_add_u32 m0, s25, 0x2000
	s_nop 0
	global_load_lds_dwordx4 v242, s[12:13]
	s_add_u32 m0, s25, 0x2400
	s_nop 0
	global_load_lds_dwordx4 v243, s[12:13]
	s_add_u32 m0, s25, 0x2800
	s_nop 0
	global_load_lds_dwordx4 v244, s[12:13]
	s_add_u32 m0, s25, 0x2c00
	s_nop 0
	global_load_lds_dwordx4 v245, s[12:13]
	s_add_u32 s8, s8, 64
	s_addc_u32 s9, s9, 0
	s_add_u32 s12, s12, 64
	s_addc_u32 s13, s13, 0
	s_add_u32 m0, s24, 0x6000
	s_nop 0
	global_load_lds_dwordx4 v240, s[8:9]
	s_add_u32 m0, s24, 0x6400
	s_nop 0
	global_load_lds_dwordx4 v241, s[8:9]
	s_add_u32 m0, s25, 0x8000
	s_nop 0
	global_load_lds_dwordx4 v242, s[12:13]
	s_add_u32 m0, s25, 0x8400
	s_nop 0
	global_load_lds_dwordx4 v243, s[12:13]
	s_add_u32 m0, s25, 0x8800
	s_nop 0
	global_load_lds_dwordx4 v244, s[12:13]
	s_add_u32 m0, s25, 0x8c00
	s_nop 0
	global_load_lds_dwordx4 v245, s[12:13]
	s_add_u32 s8, s8, 64
	s_addc_u32 s9, s9, 0
	s_add_u32 s12, s12, 64
	s_addc_u32 s13, s13, 0
	s_add_u32 m0, s24, 0xc000
	s_nop 0
	global_load_lds_dwordx4 v240, s[8:9]
	s_add_u32 m0, s24, 0xc400
	s_nop 0
	global_load_lds_dwordx4 v241, s[8:9]
	s_add_u32 m0, s25, 0xe000
	s_nop 0
	global_load_lds_dwordx4 v242, s[12:13]
	s_add_u32 m0, s25, 0xe400
	s_nop 0
	global_load_lds_dwordx4 v243, s[12:13]
	s_add_u32 m0, s25, 0xe800
	s_nop 0
	global_load_lds_dwordx4 v244, s[12:13]
	s_add_u32 m0, s25, 0xec00
	s_nop 0
	global_load_lds_dwordx4 v245, s[12:13]
	s_add_u32 s8, s8, 64
	s_addc_u32 s9, s9, 0
	s_add_u32 s12, s12, 64
	s_addc_u32 s13, s13, 0
	v_mov_b32_e32 v0, 0
	v_mov_b32_e32 v1, 0
	v_mov_b32_e32 v2, 0
	v_mov_b32_e32 v3, 0
	v_mov_b32_e32 v4, 0
	v_mov_b32_e32 v5, 0
	v_mov_b32_e32 v6, 0
	v_mov_b32_e32 v7, 0
	v_mov_b32_e32 v8, 0
	v_mov_b32_e32 v9, 0
	v_mov_b32_e32 v10, 0
	v_mov_b32_e32 v11, 0
	v_mov_b32_e32 v12, 0
	v_mov_b32_e32 v13, 0
	v_mov_b32_e32 v14, 0
	v_mov_b32_e32 v15, 0
	v_mov_b32_e32 v16, 0
	v_mov_b32_e32 v17, 0
	v_mov_b32_e32 v18, 0
	v_mov_b32_e32 v19, 0
	v_mov_b32_e32 v20, 0
	v_mov_b32_e32 v21, 0
	v_mov_b32_e32 v22, 0
	v_mov_b32_e32 v23, 0
	v_mov_b32_e32 v24, 0
	v_mov_b32_e32 v25, 0
	v_mov_b32_e32 v26, 0
	v_mov_b32_e32 v27, 0
	v_mov_b32_e32 v28, 0
	v_mov_b32_e32 v29, 0
	v_mov_b32_e32 v30, 0
	v_mov_b32_e32 v31, 0
	v_mov_b32_e32 v32, 0
	v_mov_b32_e32 v33, 0
	v_mov_b32_e32 v34, 0
	v_mov_b32_e32 v35, 0
	v_mov_b32_e32 v36, 0
	v_mov_b32_e32 v37, 0
	v_mov_b32_e32 v38, 0
	v_mov_b32_e32 v39, 0
	v_mov_b32_e32 v40, 0
	v_mov_b32_e32 v41, 0
	v_mov_b32_e32 v42, 0
	v_mov_b32_e32 v43, 0
	v_mov_b32_e32 v44, 0
	v_mov_b32_e32 v45, 0
	v_mov_b32_e32 v46, 0
	v_mov_b32_e32 v47, 0
	v_mov_b32_e32 v48, 0
	v_mov_b32_e32 v49, 0
	v_mov_b32_e32 v50, 0
	v_mov_b32_e32 v51, 0
	v_mov_b32_e32 v52, 0
	v_mov_b32_e32 v53, 0
	v_mov_b32_e32 v54, 0
	v_mov_b32_e32 v55, 0
	v_mov_b32_e32 v56, 0
	v_mov_b32_e32 v57, 0
	v_mov_b32_e32 v58, 0
	v_mov_b32_e32 v59, 0
	v_mov_b32_e32 v60, 0
	v_mov_b32_e32 v61, 0
	v_mov_b32_e32 v62, 0
	v_mov_b32_e32 v63, 0
	v_mov_b32_e32 v64, 0
	v_mov_b32_e32 v65, 0
	v_mov_b32_e32 v66, 0
	v_mov_b32_e32 v67, 0
	v_mov_b32_e32 v68, 0
	v_mov_b32_e32 v69, 0
	v_mov_b32_e32 v70, 0
	v_mov_b32_e32 v71, 0
	v_mov_b32_e32 v72, 0
	v_mov_b32_e32 v73, 0
	v_mov_b32_e32 v74, 0
	v_mov_b32_e32 v75, 0
	v_mov_b32_e32 v76, 0
	v_mov_b32_e32 v77, 0
	v_mov_b32_e32 v78, 0
	v_mov_b32_e32 v79, 0
	v_mov_b32_e32 v80, 0
	v_mov_b32_e32 v81, 0
	v_mov_b32_e32 v82, 0
	v_mov_b32_e32 v83, 0
	v_mov_b32_e32 v84, 0
	v_mov_b32_e32 v85, 0
	v_mov_b32_e32 v86, 0
	v_mov_b32_e32 v87, 0
	v_mov_b32_e32 v88, 0
	v_mov_b32_e32 v89, 0
	v_mov_b32_e32 v90, 0
	v_mov_b32_e32 v91, 0
	v_mov_b32_e32 v92, 0
	v_mov_b32_e32 v93, 0
	v_mov_b32_e32 v94, 0
	v_mov_b32_e32 v95, 0
	v_mov_b32_e32 v96, 0
	v_mov_b32_e32 v97, 0
	v_mov_b32_e32 v98, 0
	v_mov_b32_e32 v99, 0
	v_mov_b32_e32 v100, 0
	v_mov_b32_e32 v101, 0
	v_mov_b32_e32 v102, 0
	v_mov_b32_e32 v103, 0
	v_mov_b32_e32 v104, 0
	v_mov_b32_e32 v105, 0
	v_mov_b32_e32 v106, 0
	v_mov_b32_e32 v107, 0
	v_mov_b32_e32 v108, 0
	v_mov_b32_e32 v109, 0
	v_mov_b32_e32 v110, 0
	v_mov_b32_e32 v111, 0
	v_mov_b32_e32 v112, 0
	v_mov_b32_e32 v113, 0
	v_mov_b32_e32 v114, 0
	v_mov_b32_e32 v115, 0
	v_mov_b32_e32 v116, 0
	v_mov_b32_e32 v117, 0
	v_mov_b32_e32 v118, 0
	v_mov_b32_e32 v119, 0
	v_mov_b32_e32 v120, 0
	v_mov_b32_e32 v121, 0
	v_mov_b32_e32 v122, 0
	v_mov_b32_e32 v123, 0
	v_mov_b32_e32 v124, 0
	v_mov_b32_e32 v125, 0
	v_mov_b32_e32 v126, 0
	v_mov_b32_e32 v127, 0
	s_waitcnt vmcnt(12)
.Loutp_tile:
	s_barrier
	ds_read_b128 v[128:131], v246 offset:0
	ds_read_b128 v[148:151], v247 offset:0
	ds_read_b128 v[152:155], v247 offset:1024
	ds_read_b128 v[132:135], v246 offset:1024
	ds_read_b128 v[156:159], v247 offset:2048
	ds_read_b128 v[160:163], v247 offset:3072
	ds_read_b128 v[136:139], v246 offset:2048
	ds_read_b128 v[168:171], v247 offset:4096
	ds_read_b128 v[172:175], v247 offset:5120
	ds_read_b128 v[140:143], v246 offset:3072
	ds_read_b128 v[176:179], v247 offset:6144
	ds_read_b128 v[180:183], v247 offset:7168
	s_mov_b32 s28, 0

; __device__ __forceinline__ int otid() { int t = threadIdx.x; asm volatile("" : "+v"(t)); return t; }
; __device__ __forceinline__ void gemm_mainloop8(const bf16_t* __restrict__ A, int lda,
;                                                const bf16_t* __restrict__ B, int ldb, int K,
;                                                bf16_t* sbase, f32x4 (&acc)[4][8], const int tid) {
;   const int lane = tid & 63, wid = tid >> 6, wr = wid >> 1, wc = wid & 1;
;   const int lrow = tid >> 2, lch = (tid & 3) * 8;
;   const int l15 = lane & 15, lq = lane >> 4;
;   const bf16_t* pa = A + (size_t)lrow * lda + lch;
;   const bf16_t* pb = B + (size_t)lrow * ldb + lch;
;   const size_t a64 = (size_t)64 * lda, b64 = (size_t)64 * ldb;
;   u32x4 ra[2], rb[4];
;   const int nk = K >> 5;
;   const int wofs = lrow * GROW + lch;
;   const int raofs = (wr * 64 + l15) * GROW + lq * 8;
;   const int rbofs = 128 * GROW + (wc * 128 + l15) * GROW + lq * 8;
; __device__ void phase_mlp1_big(CParams& p, int l, int tm, int tn, char* smem) {
;   const int tid = otid();
;   int row0 = tm * 128, col0 = tn * 256;
;   f32x4 acc[4][8];
;   zero_acc<8>(acc);
;   gemm_mainloop8(p.hbuf + (size_t)row0 * DM, DM, p.W1T + ((size_t)l * DFF + col0) * DM, DM, DM, (bf16_t*)smem, acc, tid);
.LBB0_1064:
	s_or_b64 exec, exec, s[22:23]
	s_mov_b64 s[22:23], s[34:35]
	s_waitcnt lgkmcnt(0)
	s_barrier
	s_load_dwordx2 s[6:7], s[22:23], 0x120
	s_lshl_b64 s[18:19], s[0:1], 23
	s_load_dwordx2 s[24:25], s[22:23], 0x150
	s_load_dwordx2 s[8:9], s[22:23], 0x1e0
	v_readlane_b32 s16, v224, 4
	v_readlane_b32 s17, v224, 5
	s_waitcnt lgkmcnt(0)
	s_add_u32 s2, s6, s18
	s_addc_u32 s4, s7, s19
	s_add_u32 s42, s2, s16
	s_addc_u32 s43, s4, s17
	v_readlane_b32 s0, v224, 13
	v_readlane_b32 s1, v224, 14
	s_add_u32 s44, s8, s0
	s_addc_u32 s45, s9, s1
	s_add_u32 s2, s6, s16
	s_addc_u32 s4, s7, s17
	s_add_u32 s48, s2, s18
	s_addc_u32 s49, s4, s19
	s_mov_b64 exec, -1
	ds_read_b128 v[236:239], v145 offset:40960
	s_load_dwordx2 s[0:1], s[34:35], 0x150
	s_load_dwordx2 s[6:7], s[34:35], 0x120
	s_load_dwordx2 s[24:25], s[34:35], 0x1e0
	s_load_dwordx2 s[26:27], s[34:35], 0x160
	v_readlane_b32 s2, v224, 26
	v_readlane_b32 s4, v225, 4
	v_readfirstlane_b32 s8, v147
	v_and_b32_e32 v250, 63, v147
	s_nop 3
	s_lshr_b32 s8, s8, 6
	s_lshl_b32 s10, s8, 11
	s_lshl_b32 s32, s8, 12
	v_lshrrev_b32_e32 v251, 2, v250
	v_and_b32_e32 v252, 3, v250
	v_lshrrev_b32_e32 v253, 4, v250
	v_sub_u32_e32 v253, 0, v253
	v_and_b32_e32 v253, 3, v253
	v_xor_b32_e32 v253, v252, v253
	v_lshlrev_b32_e32 v253, 4, v253
	s_lshl_b32 s43, s8, 5
	v_add_u32_e32 v252, s43, v251
	s_mov_b32 s44, 0x800
	v_mul_lo_u32 v240, v252, s44
	v_add_u32_e32 v240, v240, v253
	v_add_u32_e32 v241, 0x8000, v240
	s_lshl_b32 s43, s8, 6
	v_add_u32_e32 v252, s43, v251
	s_mov_b32 s44, 0x800
	v_mul_lo_u32 v242, v252, s44
	v_and_b32_e32 v253, 3, v250
	v_xor_b32_e32 v252, 1, v253
	v_lshlrev_b32_e32 v252, 4, v252
	v_add_u32_e32 v252, 0x18000, v252
	v_add_u32_e32 v245, v242, v252
	v_xor_b32_e32 v252, 2, v253
	v_lshlrev_b32_e32 v252, 4, v252
	v_add_u32_e32 v252, 0x10000, v252
	v_add_u32_e32 v244, v242, v252
	v_xor_b32_e32 v252, 3, v253
	v_lshlrev_b32_e32 v252, 4, v252
	v_add_u32_e32 v252, 0x8000, v252
	v_add_u32_e32 v243, v242, v252
	v_xor_b32_e32 v252, 0, v253
	v_lshlrev_b32_e32 v252, 4, v252
	v_add_u32_e32 v252, 0x0, v252
	v_add_u32_e32 v242, v242, v252
	v_and_b32_e32 v251, 15, v250
	v_lshrrev_b32_e32 v252, 2, v251
	v_sub_u32_e32 v252, 0, v252
	v_and_b32_e32 v252, 3, v252
	v_lshrrev_b32_e32 v253, 4, v250
	v_xor_b32_e32 v252, v253, v252
	v_lshlrev_b32_e32 v252, 4, v252
	s_lshr_b32 s43, s8, 1
	s_and_b32 s44, s8, 1
	s_lshl_b32 s45, s43, 6
	s_lshl_b32 s50, s44, 7
	v_add_u32_e32 v246, s45, v251
	v_lshl_add_u32 v246, v246, 6, v252
	v_and_b32_e32 v247, 3, v251
	v_lshrrev_b32_e32 v249, 2, v251
	v_lshl_add_u32 v247, v249, 4, v247
	v_add_u32_e32 v247, s50, v247
	v_lshl_add_u32 v247, v247, 6, v252
	v_add_u32_e32 v247, 0x2000, v247
	v_lshl_add_u32 v249, v253, 4, s50
	v_lshlrev_b32_e32 v249, 1, v249
	v_add_u32_e32 v248, s45, v251
	v_lshl_add_u32 v248, v248, 13, v249
	s_waitcnt lgkmcnt(0)
	s_mov_b32 s51, 0
	s_lshl_b32 s43, s51, 3
	s_and_b32 s44, s4, 7
	s_add_u32 s43, s43, s44
	s_lshr_b32 s44, s43, 1
	s_lshl_b32 s44, s44, 3
	s_lshr_b32 s45, s4, 6
	s_add_u32 s44, s44, s45
	s_lshl_b32 s28, s44, 7
	s_and_b32 s43, s43, 1
	s_lshl_b32 s43, s43, 3
	s_lshr_b32 s45, s4, 3
	s_and_b32 s45, s45, 7
	s_add_u32 s43, s43, s45
	s_lshl_b32 s29, s43, 8
	s_mul_i32 s43, s28, 0x800
	s_add_u32 s12, s0, s43
	s_addc_u32 s13, s1, 0
	s_mul_i32 s43, s2, 0x800000
	s_mul_i32 s44, s29, 0x800
	s_add_u32 s43, s43, s44
	s_add_u32 s16, s6, s43
	s_addc_u32 s17, s7, 0
	s_barrier
	s_add_u32 m0, s10, 0x0
	s_nop 0
	global_load_lds_dwordx4 v240, s[12:13]
	s_add_u32 m0, s10, 0x400
	s_nop 0
	global_load_lds_dwordx4 v241, s[12:13]
	s_add_u32 m0, s32, 0x2000
	s_nop 0
	global_load_lds_dwordx4 v242, s[16:17]
	s_add_u32 m0, s32, 0x2400
	s_nop 0
	global_load_lds_dwordx4 v243, s[16:17]
	s_add_u32 m0, s32, 0x2800
	s_nop 0
	global_load_lds_dwordx4 v244, s[16:17]
	s_add_u32 m0, s32, 0x2c00
	s_nop 0
	global_load_lds_dwordx4 v245, s[16:17]
	s_add_u32 s12, s12, 64
	s_addc_u32 s13, s13, 0
	s_add_u32 s16, s16, 64
	s_addc_u32 s17, s17, 0
	s_add_u32 m0, s10, 0x6000
	s_nop 0
	global_load_lds_dwordx4 v240, s[12:13]
	s_add_u32 m0, s10, 0x6400
	s_nop 0
	global_load_lds_dwordx4 v241, s[12:13]
	s_add_u32 m0, s32, 0x8000
	s_nop 0
	global_load_lds_dwordx4 v242, s[16:17]
	s_add_u32 m0, s32, 0x8400
	s_nop 0
	global_load_lds_dwordx4 v243, s[16:17]
	s_add_u32 m0, s32, 0x8800
	s_nop 0
	global_load_lds_dwordx4 v244, s[16:17]
	s_add_u32 m0, s32, 0x8c00
	s_nop 0
	global_load_lds_dwordx4 v245, s[16:17]
	s_add_u32 s12, s12, 64
	s_addc_u32 s13, s13, 0
	s_add_u32 s16, s16, 64
	s_addc_u32 s17, s17, 0
	s_add_u32 m0, s10, 0xc000
	s_nop 0
	global_load_lds_dwordx4 v240, s[12:13]
	s_add_u32 m0, s10, 0xc400
	s_nop 0
	global_load_lds_dwordx4 v241, s[12:13]
	s_add_u32 m0, s32, 0xe000
	s_nop 0
	global_load_lds_dwordx4 v242, s[16:17]
	s_add_u32 m0, s32, 0xe400
	s_nop 0
	global_load_lds_dwordx4 v243, s[16:17]
	s_add_u32 m0, s32, 0xe800
	s_nop 0
	global_load_lds_dwordx4 v244, s[16:17]
	s_add_u32 m0, s32, 0xec00
	s_nop 0
	global_load_lds_dwordx4 v245, s[16:17]
	s_add_u32 s12, s12, 64
	s_addc_u32 s13, s13, 0
	s_add_u32 s16, s16, 64
	s_addc_u32 s17, s17, 0
	v_mov_b32_e32 v0, 0
	v_mov_b32_e32 v1, 0
	v_mov_b32_e32 v2, 0
	v_mov_b32_e32 v3, 0
	v_mov_b32_e32 v4, 0
	v_mov_b32_e32 v5, 0
	v_mov_b32_e32 v6, 0
	v_mov_b32_e32 v7, 0
	v_mov_b32_e32 v8, 0
	v_mov_b32_e32 v9, 0
	v_mov_b32_e32 v10, 0
	v_mov_b32_e32 v11, 0
	v_mov_b32_e32 v12, 0
	v_mov_b32_e32 v13, 0
	v_mov_b32_e32 v14, 0
	v_mov_b32_e32 v15, 0
	v_mov_b32_e32 v16, 0
	v_mov_b32_e32 v17, 0
	v_mov_b32_e32 v18, 0
	v_mov_b32_e32 v19, 0
	v_mov_b32_e32 v20, 0
	v_mov_b32_e32 v21, 0
	v_mov_b32_e32 v22, 0
	v_mov_b32_e32 v23, 0
	v_mov_b32_e32 v24, 0
	v_mov_b32_e32 v25, 0
	v_mov_b32_e32 v26, 0
; __device__ __forceinline__ void gemm_mainloop8(const bf16_t* __restrict__ A, int lda,
;                                                const bf16_t* __restrict__ B, int ldb, int K,
;                                                bf16_t* sbase, f32x4 (&acc)[4][8], const int tid) {
;     ...
;   for (int kt = 0; kt < nk; kt++) {
;     __syncthreads();
;     {
;       bf16_t* d_ = sbase + wofs;
;       *(u32x4*)(d_) = ra[0];
;       *(u32x4*)(d_ + 64 * GROW) = ra[1];
; #pragma unroll
;       for (int i = 0; i < 4; i++) *(u32x4*)(d_ + (128 + 64 * i) * GROW) = rb[i];
;     }
;     __syncthreads();
;     {
;       int kofs = min((kt + 1) * 32, K - 32);
;       ra[0] = *(const u32x4*)(pa + kofs); ra[1] = *(const u32x4*)(pa + a64 + kofs);
; #pragma unroll
;       for (int i = 0; i < 4; i++) rb[i] = *(const u32x4*)(pb + (size_t)i * b64 + kofs);
;     }
;     bf16x8 af[4], bfr[8];
; #pragma unroll
;     for (int mi = 0; mi < 4; mi++) af[mi] = *(const bf16x8*)(sbase + raofs + mi * 16 * GROW);
; #pragma unroll
;     for (int ni = 0; ni < 8; ni++) bfr[ni] = *(const bf16x8*)(sbase + rbofs + ni * 16 * GROW);
; #pragma unroll
;     for (int mi = 0; mi < 4; mi++)
; #pragma unroll
;       for (int ni = 0; ni < 8; ni++)
;         acc[mi][ni] = __builtin_amdgcn_mfma_f32_16x16x32_bf16(af[mi], bfr[ni], acc[mi][ni], 0, 0, 0);
	v_mov_b32_e32 v27, 0
	v_mov_b32_e32 v28, 0
	v_mov_b32_e32 v29, 0
	v_mov_b32_e32 v30, 0
	v_mov_b32_e32 v31, 0
	v_mov_b32_e32 v32, 0
	v_mov_b32_e32 v33, 0
	v_mov_b32_e32 v34, 0
	v_mov_b32_e32 v35, 0
	v_mov_b32_e32 v36, 0
	v_mov_b32_e32 v37, 0
	v_mov_b32_e32 v38, 0
	v_mov_b32_e32 v39, 0
	v_mov_b32_e32 v40, 0
	v_mov_b32_e32 v41, 0
	v_mov_b32_e32 v42, 0
	v_mov_b32_e32 v43, 0
	v_mov_b32_e32 v44, 0
	v_mov_b32_e32 v45, 0
	v_mov_b32_e32 v46, 0
	v_mov_b32_e32 v47, 0
	v_mov_b32_e32 v48, 0
	v_mov_b32_e32 v49, 0
	v_mov_b32_e32 v50, 0
	v_mov_b32_e32 v51, 0
	v_mov_b32_e32 v52, 0
	v_mov_b32_e32 v53, 0
	v_mov_b32_e32 v54, 0
	v_mov_b32_e32 v55, 0
	v_mov_b32_e32 v56, 0
	v_mov_b32_e32 v57, 0
	v_mov_b32_e32 v58, 0
	v_mov_b32_e32 v59, 0
	v_mov_b32_e32 v60, 0
	v_mov_b32_e32 v61, 0
	v_mov_b32_e32 v62, 0
	v_mov_b32_e32 v63, 0
	v_mov_b32_e32 v64, 0
	v_mov_b32_e32 v65, 0
	v_mov_b32_e32 v66, 0
	v_mov_b32_e32 v67, 0
	v_mov_b32_e32 v68, 0
	v_mov_b32_e32 v69, 0
	v_mov_b32_e32 v70, 0
	v_mov_b32_e32 v71, 0
	v_mov_b32_e32 v72, 0
	v_mov_b32_e32 v73, 0
	v_mov_b32_e32 v74, 0
	v_mov_b32_e32 v75, 0
	v_mov_b32_e32 v76, 0
	v_mov_b32_e32 v77, 0
	v_mov_b32_e32 v78, 0
	v_mov_b32_e32 v79, 0
	v_mov_b32_e32 v80, 0
	v_mov_b32_e32 v81, 0
	v_mov_b32_e32 v82, 0
	v_mov_b32_e32 v83, 0
	v_mov_b32_e32 v84, 0
	v_mov_b32_e32 v85, 0
	v_mov_b32_e32 v86, 0
	v_mov_b32_e32 v87, 0
	v_mov_b32_e32 v88, 0
	v_mov_b32_e32 v89, 0
	v_mov_b32_e32 v90, 0
	v_mov_b32_e32 v91, 0
	v_mov_b32_e32 v92, 0
	v_mov_b32_e32 v93, 0
	v_mov_b32_e32 v94, 0
	v_mov_b32_e32 v95, 0
	v_mov_b32_e32 v96, 0
	v_mov_b32_e32 v97, 0
	v_mov_b32_e32 v98, 0
	v_mov_b32_e32 v99, 0
	v_mov_b32_e32 v100, 0
	v_mov_b32_e32 v101, 0
	v_mov_b32_e32 v102, 0
	v_mov_b32_e32 v103, 0
	v_mov_b32_e32 v104, 0
	v_mov_b32_e32 v105, 0
	v_mov_b32_e32 v106, 0
	v_mov_b32_e32 v107, 0
	v_mov_b32_e32 v108, 0
	v_mov_b32_e32 v109, 0
	v_mov_b32_e32 v110, 0
	v_mov_b32_e32 v111, 0
	v_mov_b32_e32 v112, 0
	v_mov_b32_e32 v113, 0
	v_mov_b32_e32 v114, 0
	v_mov_b32_e32 v115, 0
	v_mov_b32_e32 v116, 0
	v_mov_b32_e32 v117, 0
	v_mov_b32_e32 v118, 0
	v_mov_b32_e32 v119, 0
	v_mov_b32_e32 v120, 0
	v_mov_b32_e32 v121, 0
	v_mov_b32_e32 v122, 0
	v_mov_b32_e32 v123, 0
	v_mov_b32_e32 v124, 0
	v_mov_b32_e32 v125, 0
	v_mov_b32_e32 v126, 0
	v_mov_b32_e32 v127, 0
	s_waitcnt vmcnt(12)
.Lmlp1_tile:
	s_barrier
	ds_read_b128 v[128:131], v246 offset:0
	ds_read_b128 v[148:151], v247 offset:0
	ds_read_b128 v[152:155], v247 offset:256
	ds_read_b128 v[132:135], v246 offset:1024
	ds_read_b128 v[156:159], v247 offset:512
	ds_read_b128 v[160:163], v247 offset:768
	ds_read_b128 v[136:139], v246 offset:2048
	ds_read_b128 v[168:171], v247 offset:4096
	ds_read_b128 v[172:175], v247 offset:4352
	ds_read_b128 v[140:143], v246 offset:3072
	ds_read_b128 v[176:179], v247 offset:4608
	ds_read_b128 v[180:183], v247 offset:4864
	s_mov_b32 s42, 0
.Lmlp1_kloop:
	s_waitcnt vmcnt(6) lgkmcnt(0)
	s_barrier
	s_add_u32 m0, s10, 0x0
	s_nop 0
	global_load_lds_dwordx4 v240, s[12:13]
	s_add_u32 m0, s10, 0x400
	s_nop 0
	global_load_lds_dwordx4 v241, s[12:13]
	s_add_u32 m0, s32, 0x2000
	s_nop 0
	global_load_lds_dwordx4 v242, s[16:17]
	s_add_u32 m0, s32, 0x2400
	s_nop 0
	global_load_lds_dwordx4 v243, s[16:17]
	s_add_u32 m0, s32, 0x2800
	s_nop 0
	global_load_lds_dwordx4 v244, s[16:17]
	s_add_u32 m0, s32, 0x2c00
	s_nop 0
	global_load_lds_dwordx4 v245, s[16:17]
	s_add_u32 s12, s12, 64
	s_addc_u32 s13, s13, 0
	s_add_u32 s16, s16, 64
	s_addc_u32 s17, s17, 0
	v_mfma_f32_16x16x32_bf16 v[0:3], v[148:151], v[128:131], v[0:3]
	ds_read_b128 v[184:187], v246 offset:24576
	v_mfma_f32_16x16x32_bf16 v[4:7], v[152:155], v[128:131], v[4:7]
	ds_read_b128 v[200:203], v247 offset:24576
	v_mfma_f32_16x16x32_bf16 v[8:11], v[156:159], v[128:131], v[8:11]
	ds_read_b128 v[204:207], v247 offset:24832
	v_mfma_f32_16x16x32_bf16 v[12:15], v[160:163], v[128:131], v[12:15]
	ds_read_b128 v[188:191], v246 offset:25600
	v_mfma_f32_16x16x32_bf16 v[16:19], v[168:171], v[128:131], v[16:19]
	ds_read_b128 v[208:211], v247 offset:25088
	v_mfma_f32_16x16x32_bf16 v[20:23], v[172:175], v[128:131], v[20:23]
	ds_read_b128 v[212:215], v247 offset:25344
	v_mfma_f32_16x16x32_bf16 v[24:27], v[176:179], v[128:131], v[24:27]
	ds_read_b128 v[192:195], v246 offset:26624
	v_mfma_f32_16x16x32_bf16 v[28:31], v[180:183], v[128:131], v[28:31]
	ds_read_b128 v[216:219], v247 offset:28672
	v_mfma_f32_16x16x32_bf16 v[32:35], v[148:151], v[132:135], v[32:35]
	ds_read_b128 v[220:223], v247 offset:28928
	v_mfma_f32_16x16x32_bf16 v[36:39], v[152:155], v[132:135], v[36:39]
	ds_read_b128 v[196:199], v246 offset:27648
	v_mfma_f32_16x16x32_bf16 v[40:43], v[156:159], v[132:135], v[40:43]
	ds_read_b128 v[228:231], v247 offset:29184
	v_mfma_f32_16x16x32_bf16 v[44:47], v[160:163], v[132:135], v[44:47]
	ds_read_b128 v[232:235], v247 offset:29440
	v_mfma_f32_16x16x32_bf16 v[48:51], v[168:171], v[132:135], v[48:51]
	v_mfma_f32_16x16x32_bf16 v[52:55], v[172:175], v[132:135], v[52:55]
	v_mfma_f32_16x16x32_bf16 v[56:59], v[176:179], v[132:135], v[56:59]
	v_mfma_f32_16x16x32_bf16 v[60:63], v[180:183], v[132:135], v[60:63]
	v_mfma_f32_16x16x32_bf16 v[64:67], v[148:151], v[136:139], v[64:67]
	v_mfma_f32_16x16x32_bf16 v[68:71], v[152:155], v[136:139], v[68:71]
	v_mfma_f32_16x16x32_bf16 v[72:75], v[156:159], v[136:139], v[72:75]
	v_mfma_f32_16x16x32_bf16 v[76:79], v[160:163], v[136:139], v[76:79]
	v_mfma_f32_16x16x32_bf16 v[80:83], v[168:171], v[136:139], v[80:83]
	v_mfma_f32_16x16x32_bf16 v[84:87], v[172:175], v[136:139], v[84:87]
	v_mfma_f32_16x16x32_bf16 v[88:91], v[176:179], v[136:139], v[88:91]
	v_mfma_f32_16x16x32_bf16 v[92:95], v[180:183], v[136:139], v[92:95]
	v_mfma_f32_16x16x32_bf16 v[96:99], v[148:151], v[140:143], v[96:99]
	v_mfma_f32_16x16x32_bf16 v[100:103], v[152:155], v[140:143], v[100:103]
	v_mfma_f32_16x16x32_bf16 v[104:107], v[156:159], v[140:143], v[104:107]
	v_mfma_f32_16x16x32_bf16 v[108:111], v[160:163], v[140:143], v[108:111]
	v_mfma_f32_16x16x32_bf16 v[112:115], v[168:171], v[140:143], v[112:115]
	v_mfma_f32_16x16x32_bf16 v[116:119], v[172:175], v[140:143], v[116:119]
	v_mfma_f32_16x16x32_bf16 v[120:123], v[176:179], v[140:143], v[120:123]
	v_mfma_f32_16x16x32_bf16 v[124:127], v[180:183], v[140:143], v[124:127]
	s_waitcnt vmcnt(6) lgkmcnt(0)
	s_barrier
; __device__ __forceinline__ void gemm_mainloop8(const bf16_t* __restrict__ A, int lda,
;                                                const bf16_t* __restrict__ B, int ldb, int K,
;                                                bf16_t* sbase, f32x4 (&acc)[4][8], const int tid) {
;     ...
;   for (int kt = 0; kt < nk; kt++) {
;     __syncthreads();
;     {
;       bf16_t* d_ = sbase + wofs;
;       *(u32x4*)(d_) = ra[0];
;       *(u32x4*)(d_ + 64 * GROW) = ra[1];
; #pragma unroll
;       for (int i = 0; i < 4; i++) *(u32x4*)(d_ + (128 + 64 * i) * GROW) = rb[i];
;     }
;     __syncthreads();
;     {
;       int kofs = min((kt + 1) * 32, K - 32);
;       ra[0] = *(const u32x4*)(pa + kofs); ra[1] = *(const u32x4*)(pa + a64 + kofs);
; #pragma unroll
;       for (int i = 0; i < 4; i++) rb[i] = *(const u32x4*)(pb + (size_t)i * b64 + kofs);
;     }
;     bf16x8 af[4], bfr[8];
; #pragma unroll
;     for (int mi = 0; mi < 4; mi++) af[mi] = *(const bf16x8*)(sbase + raofs + mi * 16 * GROW);
; #pragma unroll
;     for (int ni = 0; ni < 8; ni++) bfr[ni] = *(const bf16x8*)(sbase + rbofs + ni * 16 * GROW);
; #pragma unroll
;     for (int mi = 0; mi < 4; mi++)
; #pragma unroll
;       for (int ni = 0; ni < 8; ni++)
;         acc[mi][ni] = __builtin_amdgcn_mfma_f32_16x16x32_bf16(af[mi], bfr[ni], acc[mi][ni], 0, 0, 0);
	s_add_u32 m0, s10, 0x6000
	s_nop 0
	global_load_lds_dwordx4 v240, s[12:13]
	s_add_u32 m0, s10, 0x6400
	s_nop 0
	global_load_lds_dwordx4 v241, s[12:13]
	s_add_u32 m0, s32, 0x8000
	s_nop 0
	global_load_lds_dwordx4 v242, s[16:17]
	s_add_u32 m0, s32, 0x8400
	s_nop 0
	global_load_lds_dwordx4 v243, s[16:17]
	s_add_u32 m0, s32, 0x8800
	s_nop 0
	global_load_lds_dwordx4 v244, s[16:17]
	s_add_u32 m0, s32, 0x8c00
	s_nop 0
	global_load_lds_dwordx4 v245, s[16:17]
	s_add_u32 s12, s12, 64
	s_addc_u32 s13, s13, 0
	s_add_u32 s16, s16, 64
	s_addc_u32 s17, s17, 0
	v_mfma_f32_16x16x32_bf16 v[0:3], v[200:203], v[184:187], v[0:3]
	ds_read_b128 v[128:131], v246 offset:49152
	v_mfma_f32_16x16x32_bf16 v[4:7], v[204:207], v[184:187], v[4:7]
	ds_read_b128 v[148:151], v247 offset:49152
	v_mfma_f32_16x16x32_bf16 v[8:11], v[208:211], v[184:187], v[8:11]
	ds_read_b128 v[152:155], v247 offset:49408
	v_mfma_f32_16x16x32_bf16 v[12:15], v[212:215], v[184:187], v[12:15]
	ds_read_b128 v[132:135], v246 offset:50176
	v_mfma_f32_16x16x32_bf16 v[16:19], v[216:219], v[184:187], v[16:19]
	ds_read_b128 v[156:159], v247 offset:49664
	v_mfma_f32_16x16x32_bf16 v[20:23], v[220:223], v[184:187], v[20:23]
	ds_read_b128 v[160:163], v247 offset:49920
	v_mfma_f32_16x16x32_bf16 v[24:27], v[228:231], v[184:187], v[24:27]
	ds_read_b128 v[136:139], v246 offset:51200
	v_mfma_f32_16x16x32_bf16 v[28:31], v[232:235], v[184:187], v[28:31]
	ds_read_b128 v[168:171], v247 offset:53248
	v_mfma_f32_16x16x32_bf16 v[32:35], v[200:203], v[188:191], v[32:35]
	ds_read_b128 v[172:175], v247 offset:53504
	v_mfma_f32_16x16x32_bf16 v[36:39], v[204:207], v[188:191], v[36:39]
	ds_read_b128 v[140:143], v246 offset:52224
	v_mfma_f32_16x16x32_bf16 v[40:43], v[208:211], v[188:191], v[40:43]
	ds_read_b128 v[176:179], v247 offset:53760
	v_mfma_f32_16x16x32_bf16 v[44:47], v[212:215], v[188:191], v[44:47]
	ds_read_b128 v[180:183], v247 offset:54016
	v_mfma_f32_16x16x32_bf16 v[48:51], v[216:219], v[188:191], v[48:51]
	v_mfma_f32_16x16x32_bf16 v[52:55], v[220:223], v[188:191], v[52:55]
	v_mfma_f32_16x16x32_bf16 v[56:59], v[228:231], v[188:191], v[56:59]
	v_mfma_f32_16x16x32_bf16 v[60:63], v[232:235], v[188:191], v[60:63]
	v_mfma_f32_16x16x32_bf16 v[64:67], v[200:203], v[192:195], v[64:67]
	v_mfma_f32_16x16x32_bf16 v[68:71], v[204:207], v[192:195], v[68:71]
	v_mfma_f32_16x16x32_bf16 v[72:75], v[208:211], v[192:195], v[72:75]
	v_mfma_f32_16x16x32_bf16 v[76:79], v[212:215], v[192:195], v[76:79]
	v_mfma_f32_16x16x32_bf16 v[80:83], v[216:219], v[192:195], v[80:83]
	v_mfma_f32_16x16x32_bf16 v[84:87], v[220:223], v[192:195], v[84:87]
	v_mfma_f32_16x16x32_bf16 v[88:91], v[228:231], v[192:195], v[88:91]
	v_mfma_f32_16x16x32_bf16 v[92:95], v[232:235], v[192:195], v[92:95]
	v_mfma_f32_16x16x32_bf16 v[96:99], v[200:203], v[196:199], v[96:99]
	v_mfma_f32_16x16x32_bf16 v[100:103], v[204:207], v[196:199], v[100:103]
	v_mfma_f32_16x16x32_bf16 v[104:107], v[208:211], v[196:199], v[104:107]
	v_mfma_f32_16x16x32_bf16 v[108:111], v[212:215], v[196:199], v[108:111]
	v_mfma_f32_16x16x32_bf16 v[112:115], v[216:219], v[196:199], v[112:115]
	v_mfma_f32_16x16x32_bf16 v[116:119], v[220:223], v[196:199], v[116:119]
	v_mfma_f32_16x16x32_bf16 v[120:123], v[228:231], v[196:199], v[120:123]
	v_mfma_f32_16x16x32_bf16 v[124:127], v[232:235], v[196:199], v[124:127]
	s_waitcnt vmcnt(6) lgkmcnt(0)
	s_barrier
	s_add_u32 m0, s10, 0xc000
	s_nop 0
	global_load_lds_dwordx4 v240, s[12:13]
	s_add_u32 m0, s10, 0xc400
	s_nop 0
	global_load_lds_dwordx4 v241, s[12:13]
	s_add_u32 m0, s32, 0xe000
	s_nop 0
	global_load_lds_dwordx4 v242, s[16:17]
	s_add_u32 m0, s32, 0xe400
	s_nop 0
	global_load_lds_dwordx4 v243, s[16:17]
	s_add_u32 m0, s32, 0xe800
	s_nop 0
	global_load_lds_dwordx4 v244, s[16:17]
	s_add_u32 m0, s32, 0xec00
	s_nop 0
	global_load_lds_dwordx4 v245, s[16:17]
	s_add_u32 s12, s12, 64
	s_addc_u32 s13, s13, 0
	s_add_u32 s16, s16, 64
	s_addc_u32 s17, s17, 0
	v_mfma_f32_16x16x32_bf16 v[0:3], v[148:151], v[128:131], v[0:3]
	ds_read_b128 v[184:187], v246 offset:0
	v_mfma_f32_16x16x32_bf16 v[4:7], v[152:155], v[128:131], v[4:7]
	ds_read_b128 v[200:203], v247 offset:0
	v_mfma_f32_16x16x32_bf16 v[8:11], v[156:159], v[128:131], v[8:11]
	ds_read_b128 v[204:207], v247 offset:256
	v_mfma_f32_16x16x32_bf16 v[12:15], v[160:163], v[128:131], v[12:15]
	ds_read_b128 v[188:191], v246 offset:1024
	v_mfma_f32_16x16x32_bf16 v[16:19], v[168:171], v[128:131], v[16:19]
	ds_read_b128 v[208:211], v247 offset:512
	v_mfma_f32_16x16x32_bf16 v[20:23], v[172:175], v[128:131], v[20:23]
	ds_read_b128 v[212:215], v247 offset:768
	v_mfma_f32_16x16x32_bf16 v[24:27], v[176:179], v[128:131], v[24:27]
	ds_read_b128 v[192:195], v246 offset:2048
	v_mfma_f32_16x16x32_bf16 v[28:31], v[180:183], v[128:131], v[28:31]
	ds_read_b128 v[216:219], v247 offset:4096
	v_mfma_f32_16x16x32_bf16 v[32:35], v[148:151], v[132:135], v[32:35]
	ds_read_b128 v[220:223], v247 offset:4352
	v_mfma_f32_16x16x32_bf16 v[36:39], v[152:155], v[132:135], v[36:39]
	ds_read_b128 v[196:199], v246 offset:3072
	v_mfma_f32_16x16x32_bf16 v[40:43], v[156:159], v[132:135], v[40:43]
	ds_read_b128 v[228:231], v247 offset:4608
	v_mfma_f32_16x16x32_bf16 v[44:47], v[160:163], v[132:135], v[44:47]
	ds_read_b128 v[232:235], v247 offset:4864
	v_mfma_f32_16x16x32_bf16 v[48:51], v[168:171], v[132:135], v[48:51]
	v_mfma_f32_16x16x32_bf16 v[52:55], v[172:175], v[132:135], v[52:55]
	v_mfma_f32_16x16x32_bf16 v[56:59], v[176:179], v[132:135], v[56:59]
	v_mfma_f32_16x16x32_bf16 v[60:63], v[180:183], v[132:135], v[60:63]
	v_mfma_f32_16x16x32_bf16 v[64:67], v[148:151], v[136:139], v[64:67]
	v_mfma_f32_16x16x32_bf16 v[68:71], v[152:155], v[136:139], v[68:71]
	v_mfma_f32_16x16x32_bf16 v[72:75], v[156:159], v[136:139], v[72:75]
	v_mfma_f32_16x16x32_bf16 v[76:79], v[160:163], v[136:139], v[76:79]
	v_mfma_f32_16x16x32_bf16 v[80:83], v[168:171], v[136:139], v[80:83]
	v_mfma_f32_16x16x32_bf16 v[84:87], v[172:175], v[136:139], v[84:87]
	v_mfma_f32_16x16x32_bf16 v[88:91], v[176:179], v[136:139], v[88:91]
	v_mfma_f32_16x16x32_bf16 v[92:95], v[180:183], v[136:139], v[92:95]
	v_mfma_f32_16x16x32_bf16 v[96:99], v[148:151], v[140:143], v[96:99]
	v_mfma_f32_16x16x32_bf16 v[100:103], v[152:155], v[140:143], v[100:103]
	v_mfma_f32_16x16x32_bf16 v[104:107], v[156:159], v[140:143], v[104:107]
	v_mfma_f32_16x16x32_bf16 v[108:111], v[160:163], v[140:143], v[108:111]
	v_mfma_f32_16x16x32_bf16 v[112:115], v[168:171], v[140:143], v[112:115]
	v_mfma_f32_16x16x32_bf16 v[116:119], v[172:175], v[140:143], v[116:119]
	v_mfma_f32_16x16x32_bf16 v[120:123], v[176:179], v[140:143], v[120:123]
	v_mfma_f32_16x16x32_bf16 v[124:127], v[180:183], v[140:143], v[124:127]
	s_waitcnt vmcnt(6) lgkmcnt(0)
	s_barrier
; __device__ __forceinline__ void gemm_mainloop8(const bf16_t* __restrict__ A, int lda,
;                                                const bf16_t* __restrict__ B, int ldb, int K,
;                                                bf16_t* sbase, f32x4 (&acc)[4][8], const int tid) {
;     ...
;   for (int kt = 0; kt < nk; kt++) {
;     __syncthreads();
;     {
;       bf16_t* d_ = sbase + wofs;
;       *(u32x4*)(d_) = ra[0];
;       *(u32x4*)(d_ + 64 * GROW) = ra[1];
; #pragma unroll
;       for (int i = 0; i < 4; i++) *(u32x4*)(d_ + (128 + 64 * i) * GROW) = rb[i];
;     }
;     __syncthreads();
;     {
;       int kofs = min((kt + 1) * 32, K - 32);
;       ra[0] = *(const u32x4*)(pa + kofs); ra[1] = *(const u32x4*)(pa + a64 + kofs);
; #pragma unroll
;       for (int i = 0; i < 4; i++) rb[i] = *(const u32x4*)(pb + (size_t)i * b64 + kofs);
;     }
;     bf16x8 af[4], bfr[8];
; #pragma unroll
;     for (int mi = 0; mi < 4; mi++) af[mi] = *(const bf16x8*)(sbase + raofs + mi * 16 * GROW);
; #pragma unroll
;     for (int ni = 0; ni < 8; ni++) bfr[ni] = *(const bf16x8*)(sbase + rbofs + ni * 16 * GROW);
; #pragma unroll
;     for (int mi = 0; mi < 4; mi++)
; #pragma unroll
;       for (int ni = 0; ni < 8; ni++)
;         acc[mi][ni] = __builtin_amdgcn_mfma_f32_16x16x32_bf16(af[mi], bfr[ni], acc[mi][ni], 0, 0, 0);
	s_add_u32 m0, s10, 0x0
	s_nop 0
	global_load_lds_dwordx4 v240, s[12:13]
	s_add_u32 m0, s10, 0x400
	s_nop 0
	global_load_lds_dwordx4 v241, s[12:13]
	s_add_u32 m0, s32, 0x2000
	s_nop 0
	global_load_lds_dwordx4 v242, s[16:17]
	s_add_u32 m0, s32, 0x2400
	s_nop 0
	global_load_lds_dwordx4 v243, s[16:17]
	s_add_u32 m0, s32, 0x2800
	s_nop 0
	global_load_lds_dwordx4 v244, s[16:17]
	s_add_u32 m0, s32, 0x2c00
	s_nop 0
	global_load_lds_dwordx4 v245, s[16:17]
	s_add_u32 s12, s12, 64
	s_addc_u32 s13, s13, 0
	s_add_u32 s16, s16, 64
	s_addc_u32 s17, s17, 0
	v_mfma_f32_16x16x32_bf16 v[0:3], v[200:203], v[184:187], v[0:3]
	ds_read_b128 v[128:131], v246 offset:24576
	v_mfma_f32_16x16x32_bf16 v[4:7], v[204:207], v[184:187], v[4:7]
	ds_read_b128 v[148:151], v247 offset:24576
	v_mfma_f32_16x16x32_bf16 v[8:11], v[208:211], v[184:187], v[8:11]
	ds_read_b128 v[152:155], v247 offset:24832
	v_mfma_f32_16x16x32_bf16 v[12:15], v[212:215], v[184:187], v[12:15]
	ds_read_b128 v[132:135], v246 offset:25600
	v_mfma_f32_16x16x32_bf16 v[16:19], v[216:219], v[184:187], v[16:19]
	ds_read_b128 v[156:159], v247 offset:25088
	v_mfma_f32_16x16x32_bf16 v[20:23], v[220:223], v[184:187], v[20:23]
	ds_read_b128 v[160:163], v247 offset:25344
	v_mfma_f32_16x16x32_bf16 v[24:27], v[228:231], v[184:187], v[24:27]
	ds_read_b128 v[136:139], v246 offset:26624
	v_mfma_f32_16x16x32_bf16 v[28:31], v[232:235], v[184:187], v[28:31]
	ds_read_b128 v[168:171], v247 offset:28672
	v_mfma_f32_16x16x32_bf16 v[32:35], v[200:203], v[188:191], v[32:35]
	ds_read_b128 v[172:175], v247 offset:28928
	v_mfma_f32_16x16x32_bf16 v[36:39], v[204:207], v[188:191], v[36:39]
	ds_read_b128 v[140:143], v246 offset:27648
	v_mfma_f32_16x16x32_bf16 v[40:43], v[208:211], v[188:191], v[40:43]
	ds_read_b128 v[176:179], v247 offset:29184
	v_mfma_f32_16x16x32_bf16 v[44:47], v[212:215], v[188:191], v[44:47]
	ds_read_b128 v[180:183], v247 offset:29440
	v_mfma_f32_16x16x32_bf16 v[48:51], v[216:219], v[188:191], v[48:51]
	v_mfma_f32_16x16x32_bf16 v[52:55], v[220:223], v[188:191], v[52:55]
	v_mfma_f32_16x16x32_bf16 v[56:59], v[228:231], v[188:191], v[56:59]
	v_mfma_f32_16x16x32_bf16 v[60:63], v[232:235], v[188:191], v[60:63]
	v_mfma_f32_16x16x32_bf16 v[64:67], v[200:203], v[192:195], v[64:67]
	v_mfma_f32_16x16x32_bf16 v[68:71], v[204:207], v[192:195], v[68:71]
	v_mfma_f32_16x16x32_bf16 v[72:75], v[208:211], v[192:195], v[72:75]
	v_mfma_f32_16x16x32_bf16 v[76:79], v[212:215], v[192:195], v[76:79]
	v_mfma_f32_16x16x32_bf16 v[80:83], v[216:219], v[192:195], v[80:83]
	v_mfma_f32_16x16x32_bf16 v[84:87], v[220:223], v[192:195], v[84:87]
	v_mfma_f32_16x16x32_bf16 v[88:91], v[228:231], v[192:195], v[88:91]
	v_mfma_f32_16x16x32_bf16 v[92:95], v[232:235], v[192:195], v[92:95]
	v_mfma_f32_16x16x32_bf16 v[96:99], v[200:203], v[196:199], v[96:99]
	v_mfma_f32_16x16x32_bf16 v[100:103], v[204:207], v[196:199], v[100:103]
	v_mfma_f32_16x16x32_bf16 v[104:107], v[208:211], v[196:199], v[104:107]
	v_mfma_f32_16x16x32_bf16 v[108:111], v[212:215], v[196:199], v[108:111]
	v_mfma_f32_16x16x32_bf16 v[112:115], v[216:219], v[196:199], v[112:115]
	v_mfma_f32_16x16x32_bf16 v[116:119], v[220:223], v[196:199], v[116:119]
	v_mfma_f32_16x16x32_bf16 v[120:123], v[228:231], v[196:199], v[120:123]
	v_mfma_f32_16x16x32_bf16 v[124:127], v[232:235], v[196:199], v[124:127]
	s_waitcnt vmcnt(6) lgkmcnt(0)
	s_barrier
	s_add_u32 m0, s10, 0x6000
	s_nop 0
	global_load_lds_dwordx4 v240, s[12:13]
	s_add_u32 m0, s10, 0x6400
	s_nop 0
	global_load_lds_dwordx4 v241, s[12:13]
	s_add_u32 m0, s32, 0x8000
	s_nop 0
	global_load_lds_dwordx4 v242, s[16:17]
	s_add_u32 m0, s32, 0x8400
	s_nop 0
	global_load_lds_dwordx4 v243, s[16:17]
	s_add_u32 m0, s32, 0x8800
	s_nop 0
	global_load_lds_dwordx4 v244, s[16:17]
	s_add_u32 m0, s32, 0x8c00
	s_nop 0
	global_load_lds_dwordx4 v245, s[16:17]
	s_add_u32 s12, s12, 64
	s_addc_u32 s13, s13, 0
	s_add_u32 s16, s16, 64
	s_addc_u32 s17, s17, 0
	v_mfma_f32_16x16x32_bf16 v[0:3], v[148:151], v[128:131], v[0:3]
	ds_read_b128 v[184:187], v246 offset:49152
	v_mfma_f32_16x16x32_bf16 v[4:7], v[152:155], v[128:131], v[4:7]
	ds_read_b128 v[200:203], v247 offset:49152
	v_mfma_f32_16x16x32_bf16 v[8:11], v[156:159], v[128:131], v[8:11]
	ds_read_b128 v[204:207], v247 offset:49408
	v_mfma_f32_16x16x32_bf16 v[12:15], v[160:163], v[128:131], v[12:15]
	ds_read_b128 v[188:191], v246 offset:50176
	v_mfma_f32_16x16x32_bf16 v[16:19], v[168:171], v[128:131], v[16:19]
	ds_read_b128 v[208:211], v247 offset:49664
	v_mfma_f32_16x16x32_bf16 v[20:23], v[172:175], v[128:131], v[20:23]
	ds_read_b128 v[212:215], v247 offset:49920
	v_mfma_f32_16x16x32_bf16 v[24:27], v[176:179], v[128:131], v[24:27]
	ds_read_b128 v[192:195], v246 offset:51200
	v_mfma_f32_16x16x32_bf16 v[28:31], v[180:183], v[128:131], v[28:31]
	ds_read_b128 v[216:219], v247 offset:53248
	v_mfma_f32_16x16x32_bf16 v[32:35], v[148:151], v[132:135], v[32:35]
	ds_read_b128 v[220:223], v247 offset:53504
	v_mfma_f32_16x16x32_bf16 v[36:39], v[152:155], v[132:135], v[36:39]
	ds_read_b128 v[196:199], v246 offset:52224
	v_mfma_f32_16x16x32_bf16 v[40:43], v[156:159], v[132:135], v[40:43]
	ds_read_b128 v[228:231], v247 offset:53760
	v_mfma_f32_16x16x32_bf16 v[44:47], v[160:163], v[132:135], v[44:47]
	ds_read_b128 v[232:235], v247 offset:54016
	v_mfma_f32_16x16x32_bf16 v[48:51], v[168:171], v[132:135], v[48:51]
	v_mfma_f32_16x16x32_bf16 v[52:55], v[172:175], v[132:135], v[52:55]
	v_mfma_f32_16x16x32_bf16 v[56:59], v[176:179], v[132:135], v[56:59]
	v_mfma_f32_16x16x32_bf16 v[60:63], v[180:183], v[132:135], v[60:63]
	v_mfma_f32_16x16x32_bf16 v[64:67], v[148:151], v[136:139], v[64:67]
	v_mfma_f32_16x16x32_bf16 v[68:71], v[152:155], v[136:139], v[68:71]
	v_mfma_f32_16x16x32_bf16 v[72:75], v[156:159], v[136:139], v[72:75]
	v_mfma_f32_16x16x32_bf16 v[76:79], v[160:163], v[136:139], v[76:79]
	v_mfma_f32_16x16x32_bf16 v[80:83], v[168:171], v[136:139], v[80:83]
	v_mfma_f32_16x16x32_bf16 v[84:87], v[172:175], v[136:139], v[84:87]
	v_mfma_f32_16x16x32_bf16 v[88:91], v[176:179], v[136:139], v[88:91]
	v_mfma_f32_16x16x32_bf16 v[92:95], v[180:183], v[136:139], v[92:95]
	v_mfma_f32_16x16x32_bf16 v[96:99], v[148:151], v[140:143], v[96:99]
	v_mfma_f32_16x16x32_bf16 v[100:103], v[152:155], v[140:143], v[100:103]
	v_mfma_f32_16x16x32_bf16 v[104:107], v[156:159], v[140:143], v[104:107]
	v_mfma_f32_16x16x32_bf16 v[108:111], v[160:163], v[140:143], v[108:111]
	v_mfma_f32_16x16x32_bf16 v[112:115], v[168:171], v[140:143], v[112:115]
	v_mfma_f32_16x16x32_bf16 v[116:119], v[172:175], v[140:143], v[116:119]
	v_mfma_f32_16x16x32_bf16 v[120:123], v[176:179], v[140:143], v[120:123]
	v_mfma_f32_16x16x32_bf16 v[124:127], v[180:183], v[140:143], v[124:127]
	s_waitcnt vmcnt(6) lgkmcnt(0)
	s_barrier
; __device__ __forceinline__ void gemm_mainloop8(const bf16_t* __restrict__ A, int lda,
;                                                const bf16_t* __restrict__ B, int ldb, int K,
;                                                bf16_t* sbase, f32x4 (&acc)[4][8], const int tid) {
;     ...
;   for (int kt = 0; kt < nk; kt++) {
;     __syncthreads();
;     {
;       bf16_t* d_ = sbase + wofs;
;       *(u32x4*)(d_) = ra[0];
;       *(u32x4*)(d_ + 64 * GROW) = ra[1];
; #pragma unroll
;       for (int i = 0; i < 4; i++) *(u32x4*)(d_ + (128 + 64 * i) * GROW) = rb[i];
;     }
;     __syncthreads();
;     {
;       int kofs = min((kt + 1) * 32, K - 32);
;       ra[0] = *(const u32x4*)(pa + kofs); ra[1] = *(const u32x4*)(pa + a64 + kofs);
; #pragma unroll
;       for (int i = 0; i < 4; i++) rb[i] = *(const u32x4*)(pb + (size_t)i * b64 + kofs);
;     }
;     bf16x8 af[4], bfr[8];
; #pragma unroll
;     for (int mi = 0; mi < 4; mi++) af[mi] = *(const bf16x8*)(sbase + raofs + mi * 16 * GROW);
; #pragma unroll
;     for (int ni = 0; ni < 8; ni++) bfr[ni] = *(const bf16x8*)(sbase + rbofs + ni * 16 * GROW);
; #pragma unroll
;     for (int mi = 0; mi < 4; mi++)
; #pragma unroll
;       for (int ni = 0; ni < 8; ni++)
;         acc[mi][ni] = __builtin_amdgcn_mfma_f32_16x16x32_bf16(af[mi], bfr[ni], acc[mi][ni], 0, 0, 0);
	s_add_u32 m0, s10, 0xc000
	s_nop 0
	global_load_lds_dwordx4 v240, s[12:13]
	s_add_u32 m0, s10, 0xc400
	s_nop 0
	global_load_lds_dwordx4 v241, s[12:13]
	s_add_u32 m0, s32, 0xe000
	s_nop 0
	global_load_lds_dwordx4 v242, s[16:17]
	s_add_u32 m0, s32, 0xe400
	s_nop 0
	global_load_lds_dwordx4 v243, s[16:17]
	s_add_u32 m0, s32, 0xe800
	s_nop 0
	global_load_lds_dwordx4 v244, s[16:17]
	s_add_u32 m0, s32, 0xec00
	s_nop 0
	global_load_lds_dwordx4 v245, s[16:17]
	s_add_u32 s12, s12, 64
	s_addc_u32 s13, s13, 0
	s_add_u32 s16, s16, 64
	s_addc_u32 s17, s17, 0
	v_mfma_f32_16x16x32_bf16 v[0:3], v[200:203], v[184:187], v[0:3]
	ds_read_b128 v[128:131], v246 offset:0
	v_mfma_f32_16x16x32_bf16 v[4:7], v[204:207], v[184:187], v[4:7]
	ds_read_b128 v[148:151], v247 offset:0
	v_mfma_f32_16x16x32_bf16 v[8:11], v[208:211], v[184:187], v[8:11]
	ds_read_b128 v[152:155], v247 offset:256
	v_mfma_f32_16x16x32_bf16 v[12:15], v[212:215], v[184:187], v[12:15]
	ds_read_b128 v[132:135], v246 offset:1024
	v_mfma_f32_16x16x32_bf16 v[16:19], v[216:219], v[184:187], v[16:19]
	ds_read_b128 v[156:159], v247 offset:512
	v_mfma_f32_16x16x32_bf16 v[20:23], v[220:223], v[184:187], v[20:23]
	ds_read_b128 v[160:163], v247 offset:768
	v_mfma_f32_16x16x32_bf16 v[24:27], v[228:231], v[184:187], v[24:27]
	ds_read_b128 v[136:139], v246 offset:2048
	v_mfma_f32_16x16x32_bf16 v[28:31], v[232:235], v[184:187], v[28:31]
	ds_read_b128 v[168:171], v247 offset:4096
	v_mfma_f32_16x16x32_bf16 v[32:35], v[200:203], v[188:191], v[32:35]
	ds_read_b128 v[172:175], v247 offset:4352
	v_mfma_f32_16x16x32_bf16 v[36:39], v[204:207], v[188:191], v[36:39]
	ds_read_b128 v[140:143], v246 offset:3072
	v_mfma_f32_16x16x32_bf16 v[40:43], v[208:211], v[188:191], v[40:43]
	ds_read_b128 v[176:179], v247 offset:4608
	v_mfma_f32_16x16x32_bf16 v[44:47], v[212:215], v[188:191], v[44:47]
	ds_read_b128 v[180:183], v247 offset:4864
	v_mfma_f32_16x16x32_bf16 v[48:51], v[216:219], v[188:191], v[48:51]
	v_mfma_f32_16x16x32_bf16 v[52:55], v[220:223], v[188:191], v[52:55]
	v_mfma_f32_16x16x32_bf16 v[56:59], v[228:231], v[188:191], v[56:59]
	v_mfma_f32_16x16x32_bf16 v[60:63], v[232:235], v[188:191], v[60:63]
	v_mfma_f32_16x16x32_bf16 v[64:67], v[200:203], v[192:195], v[64:67]
	v_mfma_f32_16x16x32_bf16 v[68:71], v[204:207], v[192:195], v[68:71]
	v_mfma_f32_16x16x32_bf16 v[72:75], v[208:211], v[192:195], v[72:75]
	v_mfma_f32_16x16x32_bf16 v[76:79], v[212:215], v[192:195], v[76:79]
	v_mfma_f32_16x16x32_bf16 v[80:83], v[216:219], v[192:195], v[80:83]
	v_mfma_f32_16x16x32_bf16 v[84:87], v[220:223], v[192:195], v[84:87]
	v_mfma_f32_16x16x32_bf16 v[88:91], v[228:231], v[192:195], v[88:91]
	v_mfma_f32_16x16x32_bf16 v[92:95], v[232:235], v[192:195], v[92:95]
	v_mfma_f32_16x16x32_bf16 v[96:99], v[200:203], v[196:199], v[96:99]
	v_mfma_f32_16x16x32_bf16 v[100:103], v[204:207], v[196:199], v[100:103]
	v_mfma_f32_16x16x32_bf16 v[104:107], v[208:211], v[196:199], v[104:107]
	v_mfma_f32_16x16x32_bf16 v[108:111], v[212:215], v[196:199], v[108:111]
	v_mfma_f32_16x16x32_bf16 v[112:115], v[216:219], v[196:199], v[112:115]
	v_mfma_f32_16x16x32_bf16 v[116:119], v[220:223], v[196:199], v[116:119]
	v_mfma_f32_16x16x32_bf16 v[120:123], v[228:231], v[196:199], v[120:123]
	v_mfma_f32_16x16x32_bf16 v[124:127], v[232:235], v[196:199], v[124:127]
	s_add_u32 s42, s42, 1
	s_cmp_lt_u32 s42, 5
	s_cbranch_scc1 .Lmlp1_kloop
	s_waitcnt vmcnt(6) lgkmcnt(0)
	s_barrier
	s_add_u32 m0, s10, 0x0
	s_nop 0
	global_load_lds_dwordx4 v240, s[12:13]
	s_add_u32 m0, s10, 0x400
	s_nop 0
	global_load_lds_dwordx4 v241, s[12:13]
	s_add_u32 m0, s32, 0x2000
	s_nop 0
	global_load_lds_dwordx4 v242, s[16:17]
	s_add_u32 m0, s32, 0x2400
	s_nop 0
	global_load_lds_dwordx4 v243, s[16:17]
	s_add_u32 m0, s32, 0x2800
	s_nop 0
	global_load_lds_dwordx4 v244, s[16:17]
	s_add_u32 m0, s32, 0x2c00
	s_nop 0
	global_load_lds_dwordx4 v245, s[16:17]
	s_add_u32 s12, s12, 64
	s_addc_u32 s13, s13, 0
	s_add_u32 s16, s16, 64
	s_addc_u32 s17, s17, 0
	v_mfma_f32_16x16x32_bf16 v[0:3], v[148:151], v[128:131], v[0:3]
	ds_read_b128 v[184:187], v246 offset:24576
	v_mfma_f32_16x16x32_bf16 v[4:7], v[152:155], v[128:131], v[4:7]
	ds_read_b128 v[200:203], v247 offset:24576
	v_mfma_f32_16x16x32_bf16 v[8:11], v[156:159], v[128:131], v[8:11]
	ds_read_b128 v[204:207], v247 offset:24832
	v_mfma_f32_16x16x32_bf16 v[12:15], v[160:163], v[128:131], v[12:15]
	ds_read_b128 v[188:191], v246 offset:25600
	v_mfma_f32_16x16x32_bf16 v[16:19], v[168:171], v[128:131], v[16:19]
	ds_read_b128 v[208:211], v247 offset:25088
	v_mfma_f32_16x16x32_bf16 v[20:23], v[172:175], v[128:131], v[20:23]
	ds_read_b128 v[212:215], v247 offset:25344
	v_mfma_f32_16x16x32_bf16 v[24:27], v[176:179], v[128:131], v[24:27]
	ds_read_b128 v[192:195], v246 offset:26624
	v_mfma_f32_16x16x32_bf16 v[28:31], v[180:183], v[128:131], v[28:31]
	ds_read_b128 v[216:219], v247 offset:28672
	v_mfma_f32_16x16x32_bf16 v[32:35], v[148:151], v[132:135], v[32:35]
	ds_read_b128 v[220:223], v247 offset:28928
	v_mfma_f32_16x16x32_bf16 v[36:39], v[152:155], v[132:135], v[36:39]
	ds_read_b128 v[196:199], v246 offset:27648
	v_mfma_f32_16x16x32_bf16 v[40:43], v[156:159], v[132:135], v[40:43]
	ds_read_b128 v[228:231], v247 offset:29184
	v_mfma_f32_16x16x32_bf16 v[44:47], v[160:163], v[132:135], v[44:47]
	ds_read_b128 v[232:235], v247 offset:29440
	v_mfma_f32_16x16x32_bf16 v[48:51], v[168:171], v[132:135], v[48:51]
	v_mfma_f32_16x16x32_bf16 v[52:55], v[172:175], v[132:135], v[52:55]
	v_mfma_f32_16x16x32_bf16 v[56:59], v[176:179], v[132:135], v[56:59]
	v_mfma_f32_16x16x32_bf16 v[60:63], v[180:183], v[132:135], v[60:63]
	v_mfma_f32_16x16x32_bf16 v[64:67], v[148:151], v[136:139], v[64:67]
	v_mfma_f32_16x16x32_bf16 v[68:71], v[152:155], v[136:139], v[68:71]
	v_mfma_f32_16x16x32_bf16 v[72:75], v[156:159], v[136:139], v[72:75]
	v_mfma_f32_16x16x32_bf16 v[76:79], v[160:163], v[136:139], v[76:79]
	v_mfma_f32_16x16x32_bf16 v[80:83], v[168:171], v[136:139], v[80:83]
	v_mfma_f32_16x16x32_bf16 v[84:87], v[172:175], v[136:139], v[84:87]
	v_mfma_f32_16x16x32_bf16 v[88:91], v[176:179], v[136:139], v[88:91]
	v_mfma_f32_16x16x32_bf16 v[92:95], v[180:183], v[136:139], v[92:95]
	v_mfma_f32_16x16x32_bf16 v[96:99], v[148:151], v[140:143], v[96:99]
	v_mfma_f32_16x16x32_bf16 v[100:103], v[152:155], v[140:143], v[100:103]
	v_mfma_f32_16x16x32_bf16 v[104:107], v[156:159], v[140:143], v[104:107]
	v_mfma_f32_16x16x32_bf16 v[108:111], v[160:163], v[140:143], v[108:111]
	v_mfma_f32_16x16x32_bf16 v[112:115], v[168:171], v[140:143], v[112:115]
	v_mfma_f32_16x16x32_bf16 v[116:119], v[172:175], v[140:143], v[116:119]
	v_mfma_f32_16x16x32_bf16 v[120:123], v[176:179], v[140:143], v[120:123]
	v_mfma_f32_16x16x32_bf16 v[124:127], v[180:183], v[140:143], v[124:127]
	s_waitcnt vmcnt(6) lgkmcnt(0)
	s_barrier
; __device__ __forceinline__ int otid() { int t = threadIdx.x; asm volatile("" : "+v"(t)); return t; }
; __device__ __forceinline__ bool swz_tile(int r, int TM, int TN, int SR, int SC, int& tm, int& tn) {
;   int b = blockIdx.x;
;   int x = b & 7, j = b >> 3;
;   int nsc = (TN + SC - 1) / SC, nsr = (TM + SR - 1) / SR;
;   int s = r * 8 + x;
;   if (s >= nsr * nsc || j >= SR * SC) return false;
;   int sr = s / nsc, sc = s - sr * nsc;
;   tm = sr * SR + j / SC;
;   tn = sc * SC + j % SC;
;   return tm < TM && tn < TN;
; }
; __device__ void phase_mlp1_big(CParams& p, int l, int tm, int tn, char* smem) {
;   const int tid = otid();
;   int row0 = tm * 128, col0 = tn * 256;
;   f32x4 acc[4][8];
;   zero_acc<8>(acc);
;   gemm_mainloop8(p.hbuf + (size_t)row0 * DM, DM, p.W1T + ((size_t)l * DFF + col0) * DM, DM, DM, (bf16_t*)smem, acc, tid);
	s_add_u32 m0, s10, 0x6000
	s_nop 0
	global_load_lds_dwordx4 v240, s[12:13]
	s_add_u32 m0, s10, 0x6400
	s_nop 0
	global_load_lds_dwordx4 v241, s[12:13]
	s_add_u32 m0, s32, 0x8000
	s_nop 0
	global_load_lds_dwordx4 v242, s[16:17]
	s_add_u32 m0, s32, 0x8400
	s_nop 0
	global_load_lds_dwordx4 v243, s[16:17]
	s_add_u32 m0, s32, 0x8800
	s_nop 0
	global_load_lds_dwordx4 v244, s[16:17]
	s_add_u32 m0, s32, 0x8c00
	s_nop 0
	global_load_lds_dwordx4 v245, s[16:17]
	s_add_u32 s12, s12, 64
	s_addc_u32 s13, s13, 0
	s_add_u32 s16, s16, 64
	s_addc_u32 s17, s17, 0
	v_mfma_f32_16x16x32_bf16 v[0:3], v[200:203], v[184:187], v[0:3]
	ds_read_b128 v[128:131], v246 offset:49152
	v_mfma_f32_16x16x32_bf16 v[4:7], v[204:207], v[184:187], v[4:7]
	ds_read_b128 v[148:151], v247 offset:49152
	v_mfma_f32_16x16x32_bf16 v[8:11], v[208:211], v[184:187], v[8:11]
	ds_read_b128 v[152:155], v247 offset:49408
	v_mfma_f32_16x16x32_bf16 v[12:15], v[212:215], v[184:187], v[12:15]
	ds_read_b128 v[132:135], v246 offset:50176
	v_mfma_f32_16x16x32_bf16 v[16:19], v[216:219], v[184:187], v[16:19]
	ds_read_b128 v[156:159], v247 offset:49664
	v_mfma_f32_16x16x32_bf16 v[20:23], v[220:223], v[184:187], v[20:23]
	ds_read_b128 v[160:163], v247 offset:49920
	v_mfma_f32_16x16x32_bf16 v[24:27], v[228:231], v[184:187], v[24:27]
	ds_read_b128 v[136:139], v246 offset:51200
	v_mfma_f32_16x16x32_bf16 v[28:31], v[232:235], v[184:187], v[28:31]
	ds_read_b128 v[168:171], v247 offset:53248
	v_mfma_f32_16x16x32_bf16 v[32:35], v[200:203], v[188:191], v[32:35]
	ds_read_b128 v[172:175], v247 offset:53504
	v_mfma_f32_16x16x32_bf16 v[36:39], v[204:207], v[188:191], v[36:39]
	ds_read_b128 v[140:143], v246 offset:52224
	v_mfma_f32_16x16x32_bf16 v[40:43], v[208:211], v[188:191], v[40:43]
	ds_read_b128 v[176:179], v247 offset:53760
	v_mfma_f32_16x16x32_bf16 v[44:47], v[212:215], v[188:191], v[44:47]
	ds_read_b128 v[180:183], v247 offset:54016
	v_mfma_f32_16x16x32_bf16 v[48:51], v[216:219], v[188:191], v[48:51]
	v_mfma_f32_16x16x32_bf16 v[52:55], v[220:223], v[188:191], v[52:55]
	v_mfma_f32_16x16x32_bf16 v[56:59], v[228:231], v[188:191], v[56:59]
	v_mfma_f32_16x16x32_bf16 v[60:63], v[232:235], v[188:191], v[60:63]
	v_mfma_f32_16x16x32_bf16 v[64:67], v[200:203], v[192:195], v[64:67]
	v_mfma_f32_16x16x32_bf16 v[68:71], v[204:207], v[192:195], v[68:71]
	v_mfma_f32_16x16x32_bf16 v[72:75], v[208:211], v[192:195], v[72:75]
	v_mfma_f32_16x16x32_bf16 v[76:79], v[212:215], v[192:195], v[76:79]
	v_mfma_f32_16x16x32_bf16 v[80:83], v[216:219], v[192:195], v[80:83]
	v_mfma_f32_16x16x32_bf16 v[84:87], v[220:223], v[192:195], v[84:87]
	v_mfma_f32_16x16x32_bf16 v[88:91], v[228:231], v[192:195], v[88:91]
	v_mfma_f32_16x16x32_bf16 v[92:95], v[232:235], v[192:195], v[92:95]
	v_mfma_f32_16x16x32_bf16 v[96:99], v[200:203], v[196:199], v[96:99]
	v_mfma_f32_16x16x32_bf16 v[100:103], v[204:207], v[196:199], v[100:103]
	v_mfma_f32_16x16x32_bf16 v[104:107], v[208:211], v[196:199], v[104:107]
	v_mfma_f32_16x16x32_bf16 v[108:111], v[212:215], v[196:199], v[108:111]
	v_mfma_f32_16x16x32_bf16 v[112:115], v[216:219], v[196:199], v[112:115]
	v_mfma_f32_16x16x32_bf16 v[116:119], v[220:223], v[196:199], v[116:119]
	v_mfma_f32_16x16x32_bf16 v[120:123], v[228:231], v[196:199], v[120:123]
	v_mfma_f32_16x16x32_bf16 v[124:127], v[232:235], v[196:199], v[124:127]
	s_waitcnt vmcnt(0) lgkmcnt(0)
	s_barrier
	s_nop 15
	s_nop 15
	s_mul_i32 s43, s28, 0x2000
	s_lshl_b32 s44, s29, 1
	s_add_u32 s43, s43, s44
	s_add_u32 s54, s24, s43
	s_addc_u32 s55, s25, 0
	s_add_u32 s51, s51, 1
	s_cmp_lt_u32 s51, 4
	s_cbranch_scc0 .Lmlp1_nonext
	s_lshl_b32 s43, s51, 3
	s_and_b32 s44, s4, 7
	s_add_u32 s43, s43, s44
	s_lshr_b32 s44, s43, 1
	s_lshl_b32 s44, s44, 3
	s_lshr_b32 s45, s4, 6
	s_add_u32 s44, s44, s45
	s_lshl_b32 s28, s44, 7
	s_and_b32 s43, s43, 1
	s_lshl_b32 s43, s43, 3
	s_lshr_b32 s45, s4, 3
	s_and_b32 s45, s45, 7
	s_add_u32 s43, s43, s45
	s_lshl_b32 s29, s43, 8
	s_mul_i32 s43, s28, 0x800
	s_add_u32 s12, s0, s43
	s_addc_u32 s13, s1, 0
	s_mul_i32 s43, s2, 0x800000
	s_mul_i32 s44, s29, 0x800
	s_add_u32 s43, s43, s44
	s_add_u32 s16, s6, s43
	s_addc_u32 s17, s7, 0
	s_add_u32 m0, s10, 0x0
	s_nop 0
	global_load_lds_dwordx4 v240, s[12:13]
	s_add_u32 m0, s10, 0x400
	s_nop 0
	global_load_lds_dwordx4 v241, s[12:13]
	s_add_u32 m0, s32, 0x2000
	s_nop 0
	global_load_lds_dwordx4 v242, s[16:17]
	s_add_u32 m0, s32, 0x2400
	s_nop 0
	global_load_lds_dwordx4 v243, s[16:17]
	s_add_u32 m0, s32, 0x2800
	s_nop 0
	global_load_lds_dwordx4 v244, s[16:17]
	s_add_u32 m0, s32, 0x2c00
	s_nop 0
	global_load_lds_dwordx4 v245, s[16:17]
	s_add_u32 s12, s12, 64
	s_addc_u32 s13, s13, 0
	s_add_u32 s16, s16, 64
	s_addc_u32 s17, s17, 0
	s_add_u32 m0, s10, 0x6000
	s_nop 0
	global_load_lds_dwordx4 v240, s[12:13]
	s_add_u32 m0, s10, 0x6400
	s_nop 0
	global_load_lds_dwordx4 v241, s[12:13]
	s_add_u32 m0, s32, 0x8000
	s_nop 0
	global_load_lds_dwordx4 v242, s[16:17]
	s_add_u32 m0, s32, 0x8400
	s_nop 0
	global_load_lds_dwordx4 v243, s[16:17]
	s_add_u32 m0, s32, 0x8800
	s_nop 0
	global_load_lds_dwordx4 v244, s[16:17]
	s_add_u32 m0, s32, 0x8c00
	s_nop 0
	global_load_lds_dwordx4 v245, s[16:17]
	s_add_u32 s12, s12, 64
	s_addc_u32 s13, s13, 0
	s_add_u32 s16, s16, 64
	s_addc_u32 s17, s17, 0
	s_add_u32 m0, s10, 0xc000
	s_nop 0
	global_load_lds_dwordx4 v240, s[12:13]
	s_add_u32 m0, s10, 0xc400
	s_nop 0
	global_load_lds_dwordx4 v241, s[12:13]
	s_add_u32 m0, s32, 0xe000
	s_nop 0
	global_load_lds_dwordx4 v242, s[16:17]
	s_add_u32 m0, s32, 0xe400
	s_nop 0
	global_load_lds_dwordx4 v243, s[16:17]
	s_add_u32 m0, s32, 0xe800
	s_nop 0
	global_load_lds_dwordx4 v244, s[16:17]
	s_add_u32 m0, s32, 0xec00
	s_nop 0
	global_load_lds_dwordx4 v245, s[16:17]
	s_add_u32 s12, s12, 64
	s_addc_u32 s13, s13, 0
	s_add_u32 s16, s16, 64
	s_addc_u32 s17, s17, 0
; __device__ void phase_mlp1_big(CParams& p, int l, int tm, int tn, char* smem) {
;     ...
; #pragma unroll
;   for (int mi = 0; mi < 4; mi++)
; #pragma unroll
;     for (int ni = 0; ni < 8; ni++)
; #pragma unroll
;       for (int j = 0; j < 4; j++) {
;         int rl = wr * 64 + mi * 16 + (lane >> 4) * 4 + j;
;         int cl = wc * 128 + ni * 16 + (lane & 15);
;         float a = fmaxf(acc[mi][ni][j], 0.f);
;         p.hidden[(size_t)(row0 + rl) * DFF + col0 + cl] = f2bf(a * a);
;       }
.Lmlp1_nonext:
	v_max_f32_e32 v0, 0, v0
	v_max_f32_e32 v1, 0, v1
	v_max_f32_e32 v2, 0, v2
	v_max_f32_e32 v3, 0, v3
	v_max_f32_e32 v4, 0, v4
	v_max_f32_e32 v5, 0, v5
	v_max_f32_e32 v6, 0, v6
	v_max_f32_e32 v7, 0, v7
	v_max_f32_e32 v8, 0, v8
	v_max_f32_e32 v9, 0, v9
	v_max_f32_e32 v10, 0, v10
	v_max_f32_e32 v11, 0, v11
	v_max_f32_e32 v12, 0, v12
	v_max_f32_e32 v13, 0, v13
	v_max_f32_e32 v14, 0, v14
	v_max_f32_e32 v15, 0, v15
	v_max_f32_e32 v16, 0, v16
	v_max_f32_e32 v17, 0, v17
	v_max_f32_e32 v18, 0, v18
	v_max_f32_e32 v19, 0, v19
	v_max_f32_e32 v20, 0, v20
	v_max_f32_e32 v21, 0, v21
	v_max_f32_e32 v22, 0, v22
	v_max_f32_e32 v23, 0, v23
	v_max_f32_e32 v24, 0, v24
	v_max_f32_e32 v25, 0, v25
	v_max_f32_e32 v26, 0, v26
	v_max_f32_e32 v27, 0, v27
	v_max_f32_e32 v28, 0, v28
	v_max_f32_e32 v29, 0, v29
	v_max_f32_e32 v30, 0, v30
	v_max_f32_e32 v31, 0, v31
	v_mul_f32_e32 v0, v0, v0
	v_mul_f32_e32 v1, v1, v1
	v_mul_f32_e32 v2, v2, v2
	v_mul_f32_e32 v3, v3, v3
	v_mul_f32_e32 v4, v4, v4
	v_mul_f32_e32 v5, v5, v5
	v_mul_f32_e32 v6, v6, v6
	v_mul_f32_e32 v7, v7, v7
	v_mul_f32_e32 v8, v8, v8
	v_mul_f32_e32 v9, v9, v9
	v_mul_f32_e32 v10, v10, v10
	v_mul_f32_e32 v11, v11, v11
	v_mul_f32_e32 v12, v12, v12
	v_mul_f32_e32 v13, v13, v13
	v_mul_f32_e32 v14, v14, v14
	v_mul_f32_e32 v15, v15, v15
	v_mul_f32_e32 v16, v16, v16
	v_mul_f32_e32 v17, v17, v17
	v_mul_f32_e32 v18, v18, v18
	v_mul_f32_e32 v19, v19, v19
	v_mul_f32_e32 v20, v20, v20
	v_mul_f32_e32 v21, v21, v21
	v_mul_f32_e32 v22, v22, v22
	v_mul_f32_e32 v23, v23, v23
	v_mul_f32_e32 v24, v24, v24
	v_mul_f32_e32 v25, v25, v25
	v_mul_f32_e32 v26, v26, v26
	v_mul_f32_e32 v27, v27, v27
	v_mul_f32_e32 v28, v28, v28
	v_mul_f32_e32 v29, v29, v29
	v_mul_f32_e32 v30, v30, v30
	v_mul_f32_e32 v31, v31, v31
	v_cvt_pk_bf16_f32 v148, v0, v1
	v_cvt_pk_bf16_f32 v149, v2, v3
	v_cvt_pk_bf16_f32 v150, v4, v5
	v_cvt_pk_bf16_f32 v151, v6, v7
	global_store_dwordx4 v248, v[148:151], s[54:55] offset:0
	v_cvt_pk_bf16_f32 v152, v8, v9
	v_cvt_pk_bf16_f32 v153, v10, v11
	v_cvt_pk_bf16_f32 v154, v12, v13
	v_cvt_pk_bf16_f32 v155, v14, v15
	global_store_dwordx4 v248, v[152:155], s[54:55] offset:16
	v_cvt_pk_bf16_f32 v156, v16, v17
	v_cvt_pk_bf16_f32 v157, v18, v19
	v_cvt_pk_bf16_f32 v158, v20, v21
	v_cvt_pk_bf16_f32 v159, v22, v23
	global_store_dwordx4 v248, v[156:159], s[54:55] offset:128
	v_cvt_pk_bf16_f32 v160, v24, v25
	v_cvt_pk_bf16_f32 v161, v26, v27
	v_cvt_pk_bf16_f32 v162, v28, v29
	v_cvt_pk_bf16_f32 v163, v30, v31
	global_store_dwordx4 v248, v[160:163], s[54:55] offset:144
	s_add_u32 s54, s54, 0x20000
	s_addc_u32 s55, s55, 0
	v_max_f32_e32 v32, 0, v32
	v_max_f32_e32 v33, 0, v33
	v_max_f32_e32 v34, 0, v34
	v_max_f32_e32 v35, 0, v35
	v_max_f32_e32 v36, 0, v36
	v_max_f32_e32 v37, 0, v37
	v_max_f32_e32 v38, 0, v38
	v_max_f32_e32 v39, 0, v39
	v_max_f32_e32 v40, 0, v40
	v_max_f32_e32 v41, 0, v41
	v_max_f32_e32 v42, 0, v42
	v_max_f32_e32 v43, 0, v43
	v_max_f32_e32 v44, 0, v44
	v_max_f32_e32 v45, 0, v45
	v_max_f32_e32 v46, 0, v46
	v_max_f32_e32 v47, 0, v47
	v_max_f32_e32 v48, 0, v48
	v_max_f32_e32 v49, 0, v49
	v_max_f32_e32 v50, 0, v50
	v_max_f32_e32 v51, 0, v51
	v_max_f32_e32 v52, 0, v52
	v_max_f32_e32 v53, 0, v53
	v_max_f32_e32 v54, 0, v54
	v_max_f32_e32 v55, 0, v55
	v_max_f32_e32 v56, 0, v56
	v_max_f32_e32 v57, 0, v57
	v_max_f32_e32 v58, 0, v58
	v_max_f32_e32 v59, 0, v59
	v_max_f32_e32 v60, 0, v60
	v_max_f32_e32 v61, 0, v61
	v_max_f32_e32 v62, 0, v62
	v_max_f32_e32 v63, 0, v63
	v_mul_f32_e32 v32, v32, v32
	v_mul_f32_e32 v33, v33, v33
	v_mul_f32_e32 v34, v34, v34
	v_mul_f32_e32 v35, v35, v35
	v_mul_f32_e32 v36, v36, v36
	v_mul_f32_e32 v37, v37, v37
	v_mul_f32_e32 v38, v38, v38
	v_mul_f32_e32 v39, v39, v39
	v_mul_f32_e32 v40, v40, v40
	v_mul_f32_e32 v41, v41, v41
	v_mul_f32_e32 v42, v42, v42
	v_mul_f32_e32 v43, v43, v43
	v_mul_f32_e32 v44, v44, v44
	v_mul_f32_e32 v45, v45, v45
	v_mul_f32_e32 v46, v46, v46
	v_mul_f32_e32 v47, v47, v47
	v_mul_f32_e32 v48, v48, v48
	v_mul_f32_e32 v49, v49, v49
	v_mul_f32_e32 v50, v50, v50
	v_mul_f32_e32 v51, v51, v51
	v_mul_f32_e32 v52, v52, v52
	v_mul_f32_e32 v53, v53, v53
	v_mul_f32_e32 v54, v54, v54
	v_mul_f32_e32 v55, v55, v55
	v_mul_f32_e32 v56, v56, v56
	v_mul_f32_e32 v57, v57, v57
	v_mul_f32_e32 v58, v58, v58
	v_mul_f32_e32 v59, v59, v59
	v_mul_f32_e32 v60, v60, v60
	v_mul_f32_e32 v61, v61, v61
	v_mul_f32_e32 v62, v62, v62
	v_mul_f32_e32 v63, v63, v63
	v_cvt_pk_bf16_f32 v168, v32, v33
	v_cvt_pk_bf16_f32 v169, v34, v35
	v_cvt_pk_bf16_f32 v170, v36, v37
	v_cvt_pk_bf16_f32 v171, v38, v39
	global_store_dwordx4 v248, v[168:171], s[54:55] offset:0
	v_cvt_pk_bf16_f32 v172, v40, v41
	v_cvt_pk_bf16_f32 v173, v42, v43
	v_cvt_pk_bf16_f32 v174, v44, v45
	v_cvt_pk_bf16_f32 v175, v46, v47
	global_store_dwordx4 v248, v[172:175], s[54:55] offset:16
	v_cvt_pk_bf16_f32 v176, v48, v49
	v_cvt_pk_bf16_f32 v177, v50, v51
	v_cvt_pk_bf16_f32 v178, v52, v53
	v_cvt_pk_bf16_f32 v179, v54, v55
	global_store_dwordx4 v248, v[176:179], s[54:55] offset:128
	v_cvt_pk_bf16_f32 v180, v56, v57
	v_cvt_pk_bf16_f32 v181, v58, v59
	v_cvt_pk_bf16_f32 v182, v60, v61
	v_cvt_pk_bf16_f32 v183, v62, v63
	global_store_dwordx4 v248, v[180:183], s[54:55] offset:144
	s_add_u32 s54, s54, 0x20000
	s_addc_u32 s55, s55, 0
	v_max_f32_e32 v64, 0, v64
	v_max_f32_e32 v65, 0, v65
	v_max_f32_e32 v66, 0, v66
	v_max_f32_e32 v67, 0, v67
	v_max_f32_e32 v68, 0, v68
	v_max_f32_e32 v69, 0, v69
	v_max_f32_e32 v70, 0, v70
	v_max_f32_e32 v71, 0, v71
	v_max_f32_e32 v72, 0, v72
	v_max_f32_e32 v73, 0, v73
	v_max_f32_e32 v74, 0, v74
	v_max_f32_e32 v75, 0, v75
	v_max_f32_e32 v76, 0, v76
	v_max_f32_e32 v77, 0, v77
	v_max_f32_e32 v78, 0, v78
	v_max_f32_e32 v79, 0, v79
; __device__ void phase_mlp1_big(CParams& p, int l, int tm, int tn, char* smem) {
;     ...
; #pragma unroll
;   for (int mi = 0; mi < 4; mi++)
; #pragma unroll
;     for (int ni = 0; ni < 8; ni++)
; #pragma unroll
;       for (int j = 0; j < 4; j++) {
;         int rl = wr * 64 + mi * 16 + (lane >> 4) * 4 + j;
;         int cl = wc * 128 + ni * 16 + (lane & 15);
;         float a = fmaxf(acc[mi][ni][j], 0.f);
;         p.hidden[(size_t)(row0 + rl) * DFF + col0 + cl] = f2bf(a * a);
;       }
	v_max_f32_e32 v80, 0, v80
	v_max_f32_e32 v81, 0, v81
	v_max_f32_e32 v82, 0, v82
	v_max_f32_e32 v83, 0, v83
	v_max_f32_e32 v84, 0, v84
	v_max_f32_e32 v85, 0, v85
	v_max_f32_e32 v86, 0, v86
	v_max_f32_e32 v87, 0, v87
	v_max_f32_e32 v88, 0, v88
	v_max_f32_e32 v89, 0, v89
	v_max_f32_e32 v90, 0, v90
	v_max_f32_e32 v91, 0, v91
	v_max_f32_e32 v92, 0, v92
	v_max_f32_e32 v93, 0, v93
	v_max_f32_e32 v94, 0, v94
	v_max_f32_e32 v95, 0, v95
	v_mul_f32_e32 v64, v64, v64
	v_mul_f32_e32 v65, v65, v65
	v_mul_f32_e32 v66, v66, v66
	v_mul_f32_e32 v67, v67, v67
	v_mul_f32_e32 v68, v68, v68
	v_mul_f32_e32 v69, v69, v69
	v_mul_f32_e32 v70, v70, v70
	v_mul_f32_e32 v71, v71, v71
	v_mul_f32_e32 v72, v72, v72
	v_mul_f32_e32 v73, v73, v73
	v_mul_f32_e32 v74, v74, v74
	v_mul_f32_e32 v75, v75, v75
	v_mul_f32_e32 v76, v76, v76
	v_mul_f32_e32 v77, v77, v77
	v_mul_f32_e32 v78, v78, v78
	v_mul_f32_e32 v79, v79, v79
	v_mul_f32_e32 v80, v80, v80
	v_mul_f32_e32 v81, v81, v81
	v_mul_f32_e32 v82, v82, v82
	v_mul_f32_e32 v83, v83, v83
	v_mul_f32_e32 v84, v84, v84
	v_mul_f32_e32 v85, v85, v85
	v_mul_f32_e32 v86, v86, v86
	v_mul_f32_e32 v87, v87, v87
	v_mul_f32_e32 v88, v88, v88
	v_mul_f32_e32 v89, v89, v89
	v_mul_f32_e32 v90, v90, v90
	v_mul_f32_e32 v91, v91, v91
	v_mul_f32_e32 v92, v92, v92
	v_mul_f32_e32 v93, v93, v93
	v_mul_f32_e32 v94, v94, v94
	v_mul_f32_e32 v95, v95, v95
	v_cvt_pk_bf16_f32 v200, v64, v65
	v_cvt_pk_bf16_f32 v201, v66, v67
	v_cvt_pk_bf16_f32 v202, v68, v69
	v_cvt_pk_bf16_f32 v203, v70, v71
	global_store_dwordx4 v248, v[200:203], s[54:55] offset:0
	v_cvt_pk_bf16_f32 v204, v72, v73
	v_cvt_pk_bf16_f32 v205, v74, v75
	v_cvt_pk_bf16_f32 v206, v76, v77
	v_cvt_pk_bf16_f32 v207, v78, v79
	global_store_dwordx4 v248, v[204:207], s[54:55] offset:16
	v_cvt_pk_bf16_f32 v208, v80, v81
	v_cvt_pk_bf16_f32 v209, v82, v83
	v_cvt_pk_bf16_f32 v210, v84, v85
	v_cvt_pk_bf16_f32 v211, v86, v87
	global_store_dwordx4 v248, v[208:211], s[54:55] offset:128
	v_cvt_pk_bf16_f32 v212, v88, v89
	v_cvt_pk_bf16_f32 v213, v90, v91
	v_cvt_pk_bf16_f32 v214, v92, v93
	v_cvt_pk_bf16_f32 v215, v94, v95
	global_store_dwordx4 v248, v[212:215], s[54:55] offset:144
	s_add_u32 s54, s54, 0x20000
	s_addc_u32 s55, s55, 0
	v_max_f32_e32 v96, 0, v96
	v_max_f32_e32 v97, 0, v97
	v_max_f32_e32 v98, 0, v98
	v_max_f32_e32 v99, 0, v99
	v_max_f32_e32 v100, 0, v100
	v_max_f32_e32 v101, 0, v101
	v_max_f32_e32 v102, 0, v102
	v_max_f32_e32 v103, 0, v103
	v_max_f32_e32 v104, 0, v104
	v_max_f32_e32 v105, 0, v105
	v_max_f32_e32 v106, 0, v106
	v_max_f32_e32 v107, 0, v107
	v_max_f32_e32 v108, 0, v108
	v_max_f32_e32 v109, 0, v109
	v_max_f32_e32 v110, 0, v110
	v_max_f32_e32 v111, 0, v111
	v_max_f32_e32 v112, 0, v112
	v_max_f32_e32 v113, 0, v113
	v_max_f32_e32 v114, 0, v114
	v_max_f32_e32 v115, 0, v115
	v_max_f32_e32 v116, 0, v116
	v_max_f32_e32 v117, 0, v117
	v_max_f32_e32 v118, 0, v118
	v_max_f32_e32 v119, 0, v119
	v_max_f32_e32 v120, 0, v120
	v_max_f32_e32 v121, 0, v121
	v_max_f32_e32 v122, 0, v122
	v_max_f32_e32 v123, 0, v123
	v_max_f32_e32 v124, 0, v124
	v_max_f32_e32 v125, 0, v125
	v_max_f32_e32 v126, 0, v126
	v_max_f32_e32 v127, 0, v127
	v_mul_f32_e32 v96, v96, v96
	v_mul_f32_e32 v97, v97, v97
	v_mul_f32_e32 v98, v98, v98
	v_mul_f32_e32 v99, v99, v99
	v_mul_f32_e32 v100, v100, v100
	v_mul_f32_e32 v101, v101, v101
	v_mul_f32_e32 v102, v102, v102
	v_mul_f32_e32 v103, v103, v103
	v_mul_f32_e32 v104, v104, v104
	v_mul_f32_e32 v105, v105, v105
	v_mul_f32_e32 v106, v106, v106
	v_mul_f32_e32 v107, v107, v107
	v_mul_f32_e32 v108, v108, v108
	v_mul_f32_e32 v109, v109, v109
	v_mul_f32_e32 v110, v110, v110
	v_mul_f32_e32 v111, v111, v111
	v_mul_f32_e32 v112, v112, v112
	v_mul_f32_e32 v113, v113, v113
	v_mul_f32_e32 v114, v114, v114
	v_mul_f32_e32 v115, v115, v115
	v_mul_f32_e32 v116, v116, v116
	v_mul_f32_e32 v117, v117, v117
	v_mul_f32_e32 v118, v118, v118
	v_mul_f32_e32 v119, v119, v119
	v_mul_f32_e32 v120, v120, v120
	v_mul_f32_e32 v121, v121, v121
	v_mul_f32_e32 v122, v122, v122
	v_mul_f32_e32 v123, v123, v123
	v_mul_f32_e32 v124, v124, v124
	v_mul_f32_e32 v125, v125, v125
	v_mul_f32_e32 v126, v126, v126
	v_mul_f32_e32 v127, v127, v127
	v_cvt_pk_bf16_f32 v216, v96, v97
	v_cvt_pk_bf16_f32 v217, v98, v99
	v_cvt_pk_bf16_f32 v218, v100, v101
	v_cvt_pk_bf16_f32 v219, v102, v103
	global_store_dwordx4 v248, v[216:219], s[54:55] offset:0
	v_cvt_pk_bf16_f32 v220, v104, v105
	v_cvt_pk_bf16_f32 v221, v106, v107
	v_cvt_pk_bf16_f32 v222, v108, v109
	v_cvt_pk_bf16_f32 v223, v110, v111
	global_store_dwordx4 v248, v[220:223], s[54:55] offset:16
	v_cvt_pk_bf16_f32 v228, v112, v113
	v_cvt_pk_bf16_f32 v229, v114, v115
	v_cvt_pk_bf16_f32 v230, v116, v117
	v_cvt_pk_bf16_f32 v231, v118, v119
	global_store_dwordx4 v248, v[228:231], s[54:55] offset:128
	v_cvt_pk_bf16_f32 v232, v120, v121
	v_cvt_pk_bf16_f32 v233, v122, v123
	v_cvt_pk_bf16_f32 v234, v124, v125
	v_cvt_pk_bf16_f32 v235, v126, v127
	global_store_dwordx4 v248, v[232:235], s[54:55] offset:144
	s_waitcnt vmcnt(0) lgkmcnt(0)
; template <int NI>
; __device__ __forceinline__ void zero_acc(f32x4 (&acc)[4][NI]) {
; #pragma unroll
;   for (int a = 0; a < 4; a++)
; #pragma unroll
;     for (int b = 0; b < NI; b++) acc[a][b] = f32x4{0.f, 0.f, 0.f, 0.f};
	v_mov_b32_e32 v0, 0
	v_mov_b32_e32 v1, 0
	v_mov_b32_e32 v2, 0
	v_mov_b32_e32 v3, 0
	v_mov_b32_e32 v4, 0
	v_mov_b32_e32 v5, 0
	v_mov_b32_e32 v6, 0
	v_mov_b32_e32 v7, 0
	v_mov_b32_e32 v8, 0
	v_mov_b32_e32 v9, 0
	v_mov_b32_e32 v10, 0
	v_mov_b32_e32 v11, 0
	v_mov_b32_e32 v12, 0
	v_mov_b32_e32 v13, 0
	v_mov_b32_e32 v14, 0
	v_mov_b32_e32 v15, 0
	v_mov_b32_e32 v16, 0
	v_mov_b32_e32 v17, 0
	v_mov_b32_e32 v18, 0
	v_mov_b32_e32 v19, 0
	v_mov_b32_e32 v20, 0
	v_mov_b32_e32 v21, 0
	v_mov_b32_e32 v22, 0
	v_mov_b32_e32 v23, 0
	v_mov_b32_e32 v24, 0
	v_mov_b32_e32 v25, 0
	v_mov_b32_e32 v26, 0
	v_mov_b32_e32 v27, 0
	v_mov_b32_e32 v28, 0
	v_mov_b32_e32 v29, 0
	v_mov_b32_e32 v30, 0
	v_mov_b32_e32 v31, 0
	v_mov_b32_e32 v32, 0
	v_mov_b32_e32 v33, 0
	v_mov_b32_e32 v34, 0
	v_mov_b32_e32 v35, 0
	v_mov_b32_e32 v36, 0
	v_mov_b32_e32 v37, 0
	v_mov_b32_e32 v38, 0
	v_mov_b32_e32 v39, 0
	v_mov_b32_e32 v40, 0
	v_mov_b32_e32 v41, 0
	v_mov_b32_e32 v42, 0
	v_mov_b32_e32 v43, 0
	v_mov_b32_e32 v44, 0
	v_mov_b32_e32 v45, 0
	v_mov_b32_e32 v46, 0
	v_mov_b32_e32 v47, 0
	v_mov_b32_e32 v48, 0
	v_mov_b32_e32 v49, 0
	v_mov_b32_e32 v50, 0
	v_mov_b32_e32 v51, 0
	v_mov_b32_e32 v52, 0
	v_mov_b32_e32 v53, 0
	v_mov_b32_e32 v54, 0
	v_mov_b32_e32 v55, 0
	v_mov_b32_e32 v56, 0
	v_mov_b32_e32 v57, 0
	v_mov_b32_e32 v58, 0
	v_mov_b32_e32 v59, 0
	v_mov_b32_e32 v60, 0
	v_mov_b32_e32 v61, 0
	v_mov_b32_e32 v62, 0
	v_mov_b32_e32 v63, 0
	v_mov_b32_e32 v64, 0
	v_mov_b32_e32 v65, 0
	v_mov_b32_e32 v66, 0
	v_mov_b32_e32 v67, 0
	v_mov_b32_e32 v68, 0
	v_mov_b32_e32 v69, 0
	v_mov_b32_e32 v70, 0
	v_mov_b32_e32 v71, 0
	v_mov_b32_e32 v72, 0
	v_mov_b32_e32 v73, 0
	v_mov_b32_e32 v74, 0
	v_mov_b32_e32 v75, 0
	v_mov_b32_e32 v76, 0
	v_mov_b32_e32 v77, 0
	v_mov_b32_e32 v78, 0
	v_mov_b32_e32 v79, 0
	v_mov_b32_e32 v80, 0
	v_mov_b32_e32 v81, 0
	v_mov_b32_e32 v82, 0
	v_mov_b32_e32 v83, 0
	v_mov_b32_e32 v84, 0
	v_mov_b32_e32 v85, 0
	v_mov_b32_e32 v86, 0
	v_mov_b32_e32 v87, 0
	v_mov_b32_e32 v88, 0
	v_mov_b32_e32 v89, 0
	v_mov_b32_e32 v90, 0
	v_mov_b32_e32 v91, 0
	v_mov_b32_e32 v92, 0
	v_mov_b32_e32 v93, 0
	v_mov_b32_e32 v94, 0
	v_mov_b32_e32 v95, 0
	v_mov_b32_e32 v96, 0
	v_mov_b32_e32 v97, 0
	v_mov_b32_e32 v98, 0
	v_mov_b32_e32 v99, 0
	v_mov_b32_e32 v100, 0
	v_mov_b32_e32 v101, 0
	v_mov_b32_e32 v102, 0
	v_mov_b32_e32 v103, 0
	v_mov_b32_e32 v104, 0
	v_mov_b32_e32 v105, 0
	v_mov_b32_e32 v106, 0
	v_mov_b32_e32 v107, 0
	v_mov_b32_e32 v108, 0
	v_mov_b32_e32 v109, 0
	v_mov_b32_e32 v110, 0
	v_mov_b32_e32 v111, 0
	v_mov_b32_e32 v112, 0
	v_mov_b32_e32 v113, 0
	v_mov_b32_e32 v114, 0
	v_mov_b32_e32 v115, 0
	v_mov_b32_e32 v116, 0
	v_mov_b32_e32 v117, 0
	v_mov_b32_e32 v118, 0
	v_mov_b32_e32 v119, 0
	v_mov_b32_e32 v120, 0
	v_mov_b32_e32 v121, 0
	v_mov_b32_e32 v122, 0
	v_mov_b32_e32 v123, 0
	v_mov_b32_e32 v124, 0
	v_mov_b32_e32 v125, 0
	v_mov_b32_e32 v126, 0
	v_mov_b32_e32 v127, 0
	s_cmp_lt_u32 s51, 4
	s_cbranch_scc1 .Lmlp1_tile
	s_barrier
	ds_write_b128 v145, v[236:239] offset:40960
	s_waitcnt lgkmcnt(0)
	s_barrier

; __device__ __forceinline__ int otid() { int t = threadIdx.x; asm volatile("" : "+v"(t)); return t; }
; template <int NI> ...
;     ...
;   const int lane = tid & 63, wid = tid >> 6, wr = wid >> 1, wc = wid & 1;
;   const int lrow = tid >> 2, lch = (tid & 3) * 8;
;   const int l15 = lane & 15, lq = lane >> 4;
;   const bf16_t* pa = A + (size_t)lrow * lda + lch;
;   const bf16_t* pb = B + (size_t)lrow * ldb + lch;
;   const size_t a64 = (size_t)64 * lda, b64 = (size_t)64 * ldb;
;   u32x4 a0[2], a1[2], b0[NB], b1[NB];
;   const int nk = K >> 5;
;   const int klast = K - 32;
;   const int wofs = lrow * GROW + lch;
;   const int raofs = (wr * 64 + l15) * GROW + lq * 8;
;   const int rbofs = 128 * GROW + (wc * (16 * NI) + l15) * GROW + lq * 8;
; __device__ void phase_proj_res(CParams& p, int l, int tm, int tn, char* smem, const bf16_t* A, int K,
;                                const bf16_t* Bt, int gate_off, float gscale) {
;   const int tid = otid();
;   bf16_t* sA = (bf16_t*)smem;
;   bf16_t* sB = sA + 128 * LDSS;
;   int row0 = tm * 128, col0 = tn * 128;
;   f32x4 acc[4][4];
;   zero_acc<4>(acc);
;   gemm_mainloop<4>(A + (size_t)row0 * K, K, Bt + (size_t)col0 * K, K, K, sA, sB, acc, tid);
;   const float* md = p.mod + ((size_t)l * 3 + modvec_of_tok(row0)) * 6144 + gate_off;
.LBB0_1127:
	s_or_b64 exec, exec, s[20:21]
	s_mov_b64 s[20:21], s[34:35]
	s_waitcnt lgkmcnt(0)
	s_barrier
	s_load_dwordx2 s[6:7], s[20:21], 0x128
	s_load_dwordx2 s[22:23], s[20:21], 0x1e0
	s_load_dwordx2 s[24:25], s[20:21], 0x160
	s_load_dwordx2 s[44:45], s[20:21], 0x148
	s_load_dwordx2 s[48:49], s[20:21], 0xf8
	s_waitcnt lgkmcnt(0)
	s_add_u32 s2, s6, s18
	s_addc_u32 s4, s7, s19
	v_readlane_b32 s6, v224, 15
	v_readlane_b32 s7, v224, 16
	s_add_u32 s18, s2, s6
	s_addc_u32 s19, s4, s7
	s_mov_b32 s2, 0
	s_mov_b64 exec, -1
	ds_read_b128 v[236:239], v145 offset:40960
	s_load_dwordx2 s[6:7], s[20:21], 0x1e0
	s_load_dwordx2 s[12:13], s[20:21], 0x128
	s_load_dwordx2 s[22:23], s[20:21], 0xf8
	s_load_dwordx2 s[26:27], s[20:21], 0x160
	v_readlane_b32 s0, v224, 26
	v_readlane_b32 s2, v225, 4
	v_readfirstlane_b32 s4, v147
	v_and_b32_e32 v250, 63, v147
	s_nop 3
	s_lshr_b32 s4, s4, 6
	s_lshl_b32 s8, s4, 11
	s_lshl_b32 s10, s4, 12
	v_lshrrev_b32_e32 v251, 2, v250
	v_and_b32_e32 v252, 3, v250
	v_lshrrev_b32_e32 v253, 4, v250
	v_sub_u32_e32 v253, 0, v253
	v_and_b32_e32 v253, 3, v253
	v_xor_b32_e32 v253, v252, v253
	v_lshlrev_b32_e32 v253, 4, v253
	s_lshl_b32 s40, s4, 5
	v_add_u32_e32 v252, s40, v251
	s_mov_b32 s41, 0x2000
	v_mul_lo_u32 v240, v252, s41
	v_add_u32_e32 v240, v240, v253
	v_add_u32_e32 v241, 0x20000, v240
	s_lshl_b32 s40, s4, 6
	v_add_u32_e32 v252, s40, v251
	s_mov_b32 s41, 0x2000
	v_mul_lo_u32 v242, v252, s41
	v_add_u32_e32 v242, v242, v253
	v_add_u32_e32 v243, 0x20000, v242
	v_add_u32_e32 v244, 0x40000, v242
	v_add_u32_e32 v245, 0x60000, v242
	v_and_b32_e32 v251, 15, v250
	v_lshrrev_b32_e32 v252, 2, v251
	v_sub_u32_e32 v252, 0, v252
	v_and_b32_e32 v252, 3, v252
	v_lshrrev_b32_e32 v253, 4, v250
	v_xor_b32_e32 v252, v253, v252
	v_lshlrev_b32_e32 v252, 4, v252
	s_lshr_b32 s40, s4, 1
	s_and_b32 s41, s4, 1
	s_lshl_b32 s52, s40, 6
	s_lshl_b32 s53, s41, 7
	v_add_u32_e32 v246, s52, v251
	v_lshl_add_u32 v246, v246, 6, v252
	v_add_u32_e32 v247, s53, v251
	v_lshl_add_u32 v247, v247, 6, v252
	v_add_u32_e32 v247, 0x2000, v247
	v_lshl_add_u32 v249, v253, 2, s53
	v_lshlrev_b32_e32 v249, 2, v249
	v_add_u32_e32 v248, s52, v251
	v_lshl_add_u32 v248, v248, 12, v249
	s_waitcnt lgkmcnt(0)
	s_mov_b32 s58, 0
	s_and_b32 s40, s2, 7
	s_lshl_b32 s40, s40, 4
	s_lshr_b32 s41, s2, 5
	s_add_u32 s40, s40, s41
	s_lshl_b32 s32, s40, 7
	s_lshr_b32 s41, s2, 3
	s_and_b32 s41, s41, 3
	s_lshl_b32 s28, s41, 8
	s_mul_i32 s40, s32, 0x2000
	s_add_u32 s16, s6, s40
	s_addc_u32 s17, s7, 0
	s_mul_i32 s40, s0, 0x800000
	s_mul_i32 s41, s28, 0x2000
	s_add_u32 s40, s40, s41
	s_add_u32 s18, s12, s40
	s_addc_u32 s19, s13, 0
	s_barrier
; template <int NI> ...
;     ...
;   G_LOAD(a0, b0, 0);
;   G_LOAD(a1, b1, 32);
;   __syncthreads();
;   G_WRITE(a0, b0, 0);
;   __syncthreads();
; template <int NI>
; __device__ __forceinline__ void zero_acc(f32x4 (&acc)[4][NI]) {
; #pragma unroll
;   for (int a = 0; a < 4; a++)
; #pragma unroll
;     for (int b = 0; b < NI; b++) acc[a][b] = f32x4{0.f, 0.f, 0.f, 0.f};
	s_add_u32 m0, s8, 0x0
	s_nop 0
	global_load_lds_dwordx4 v240, s[16:17]
	s_add_u32 m0, s8, 0x400
	s_nop 0
	global_load_lds_dwordx4 v241, s[16:17]
	s_add_u32 m0, s10, 0x2000
	s_nop 0
	global_load_lds_dwordx4 v242, s[18:19]
	s_add_u32 m0, s10, 0x2400
	s_nop 0
	global_load_lds_dwordx4 v243, s[18:19]
	s_add_u32 m0, s10, 0x2800
	s_nop 0
	global_load_lds_dwordx4 v244, s[18:19]
	s_add_u32 m0, s10, 0x2c00
	s_nop 0
	global_load_lds_dwordx4 v245, s[18:19]
	s_add_u32 s16, s16, 64
	s_addc_u32 s17, s17, 0
	s_add_u32 s18, s18, 64
	s_addc_u32 s19, s19, 0
	s_add_u32 m0, s8, 0x6000
	s_nop 0
	global_load_lds_dwordx4 v240, s[16:17]
	s_add_u32 m0, s8, 0x6400
	s_nop 0
	global_load_lds_dwordx4 v241, s[16:17]
	s_add_u32 m0, s10, 0x8000
	s_nop 0
	global_load_lds_dwordx4 v242, s[18:19]
	s_add_u32 m0, s10, 0x8400
	s_nop 0
	global_load_lds_dwordx4 v243, s[18:19]
	s_add_u32 m0, s10, 0x8800
	s_nop 0
	global_load_lds_dwordx4 v244, s[18:19]
	s_add_u32 m0, s10, 0x8c00
	s_nop 0
	global_load_lds_dwordx4 v245, s[18:19]
	s_add_u32 s16, s16, 64
	s_addc_u32 s17, s17, 0
	s_add_u32 s18, s18, 64
	s_addc_u32 s19, s19, 0
	s_add_u32 m0, s8, 0xc000
	s_nop 0
	global_load_lds_dwordx4 v240, s[16:17]
	s_add_u32 m0, s8, 0xc400
	s_nop 0
	global_load_lds_dwordx4 v241, s[16:17]
	s_add_u32 m0, s10, 0xe000
	s_nop 0
	global_load_lds_dwordx4 v242, s[18:19]
	s_add_u32 m0, s10, 0xe400
	s_nop 0
	global_load_lds_dwordx4 v243, s[18:19]
	s_add_u32 m0, s10, 0xe800
	s_nop 0
	global_load_lds_dwordx4 v244, s[18:19]
	s_add_u32 m0, s10, 0xec00
	s_nop 0
	global_load_lds_dwordx4 v245, s[18:19]
	s_add_u32 s16, s16, 64
	s_addc_u32 s17, s17, 0
	s_add_u32 s18, s18, 64
	s_addc_u32 s19, s19, 0
	v_mov_b32_e32 v0, 0
	v_mov_b32_e32 v1, 0
	v_mov_b32_e32 v2, 0
	v_mov_b32_e32 v3, 0
	v_mov_b32_e32 v4, 0
	v_mov_b32_e32 v5, 0
	v_mov_b32_e32 v6, 0
	v_mov_b32_e32 v7, 0
	v_mov_b32_e32 v8, 0
	v_mov_b32_e32 v9, 0
	v_mov_b32_e32 v10, 0
	v_mov_b32_e32 v11, 0
	v_mov_b32_e32 v12, 0
	v_mov_b32_e32 v13, 0
	v_mov_b32_e32 v14, 0
	v_mov_b32_e32 v15, 0
	v_mov_b32_e32 v16, 0
	v_mov_b32_e32 v17, 0
	v_mov_b32_e32 v18, 0
	v_mov_b32_e32 v19, 0
	v_mov_b32_e32 v20, 0
	v_mov_b32_e32 v21, 0
	v_mov_b32_e32 v22, 0
	v_mov_b32_e32 v23, 0
	v_mov_b32_e32 v24, 0
	v_mov_b32_e32 v25, 0
	v_mov_b32_e32 v26, 0
	v_mov_b32_e32 v27, 0
	v_mov_b32_e32 v28, 0
	v_mov_b32_e32 v29, 0
	v_mov_b32_e32 v30, 0
	v_mov_b32_e32 v31, 0
	v_mov_b32_e32 v32, 0
	v_mov_b32_e32 v33, 0
	v_mov_b32_e32 v34, 0
	v_mov_b32_e32 v35, 0
	v_mov_b32_e32 v36, 0
	v_mov_b32_e32 v37, 0
	v_mov_b32_e32 v38, 0
	v_mov_b32_e32 v39, 0
	v_mov_b32_e32 v40, 0
	v_mov_b32_e32 v41, 0
	v_mov_b32_e32 v42, 0
	v_mov_b32_e32 v43, 0
	v_mov_b32_e32 v44, 0
	v_mov_b32_e32 v45, 0
	v_mov_b32_e32 v46, 0
	v_mov_b32_e32 v47, 0
	v_mov_b32_e32 v48, 0
	v_mov_b32_e32 v49, 0
	v_mov_b32_e32 v50, 0
	v_mov_b32_e32 v51, 0
	v_mov_b32_e32 v52, 0
	v_mov_b32_e32 v53, 0
	v_mov_b32_e32 v54, 0
	v_mov_b32_e32 v55, 0
	v_mov_b32_e32 v56, 0
	v_mov_b32_e32 v57, 0
	v_mov_b32_e32 v58, 0
	v_mov_b32_e32 v59, 0
	v_mov_b32_e32 v60, 0
	v_mov_b32_e32 v61, 0
	v_mov_b32_e32 v62, 0
	v_mov_b32_e32 v63, 0
	v_mov_b32_e32 v64, 0
	v_mov_b32_e32 v65, 0
	v_mov_b32_e32 v66, 0
	v_mov_b32_e32 v67, 0
	v_mov_b32_e32 v68, 0
	v_mov_b32_e32 v69, 0
	v_mov_b32_e32 v70, 0
	v_mov_b32_e32 v71, 0
	v_mov_b32_e32 v72, 0
	v_mov_b32_e32 v73, 0
	v_mov_b32_e32 v74, 0
	v_mov_b32_e32 v75, 0
	v_mov_b32_e32 v76, 0
	v_mov_b32_e32 v77, 0
	v_mov_b32_e32 v78, 0
	v_mov_b32_e32 v79, 0
	v_mov_b32_e32 v80, 0
	v_mov_b32_e32 v81, 0
	v_mov_b32_e32 v82, 0
	v_mov_b32_e32 v83, 0
	v_mov_b32_e32 v84, 0
	v_mov_b32_e32 v85, 0
	v_mov_b32_e32 v86, 0
	v_mov_b32_e32 v87, 0
	v_mov_b32_e32 v88, 0
	v_mov_b32_e32 v89, 0
	v_mov_b32_e32 v90, 0
	v_mov_b32_e32 v91, 0
	v_mov_b32_e32 v92, 0
	v_mov_b32_e32 v93, 0
	v_mov_b32_e32 v94, 0
	v_mov_b32_e32 v95, 0
	v_mov_b32_e32 v96, 0
	v_mov_b32_e32 v97, 0
	v_mov_b32_e32 v98, 0
	v_mov_b32_e32 v99, 0
	v_mov_b32_e32 v100, 0
	v_mov_b32_e32 v101, 0
	v_mov_b32_e32 v102, 0
	v_mov_b32_e32 v103, 0
	v_mov_b32_e32 v104, 0
	v_mov_b32_e32 v105, 0
	v_mov_b32_e32 v106, 0
	v_mov_b32_e32 v107, 0
	v_mov_b32_e32 v108, 0
	v_mov_b32_e32 v109, 0
	v_mov_b32_e32 v110, 0
	v_mov_b32_e32 v111, 0
	v_mov_b32_e32 v112, 0
	v_mov_b32_e32 v113, 0
	v_mov_b32_e32 v114, 0
	v_mov_b32_e32 v115, 0
	v_mov_b32_e32 v116, 0
	v_mov_b32_e32 v117, 0
	v_mov_b32_e32 v118, 0
	v_mov_b32_e32 v119, 0
	v_mov_b32_e32 v120, 0
	v_mov_b32_e32 v121, 0
	v_mov_b32_e32 v122, 0
	v_mov_b32_e32 v123, 0
	v_mov_b32_e32 v124, 0
	v_mov_b32_e32 v125, 0
	v_mov_b32_e32 v126, 0
	v_mov_b32_e32 v127, 0
	s_waitcnt vmcnt(12)
.Lmlp2_tile:
	s_barrier
	ds_read_b128 v[128:131], v246 offset:0
	ds_read_b128 v[148:151], v247 offset:0
	ds_read_b128 v[152:155], v247 offset:1024
	ds_read_b128 v[132:135], v246 offset:1024
	ds_read_b128 v[156:159], v247 offset:2048
	ds_read_b128 v[160:163], v247 offset:3072
	ds_read_b128 v[136:139], v246 offset:2048
	ds_read_b128 v[168:171], v247 offset:4096
	ds_read_b128 v[172:175], v247 offset:5120
	ds_read_b128 v[140:143], v246 offset:3072
	ds_read_b128 v[176:179], v247 offset:6144
	ds_read_b128 v[180:183], v247 offset:7168
	s_mov_b32 s29, 0
